# v25 + nt hint on last-use loads in the GLA scan (UPD) and GLA readout (q, state, gate) phases
# speedup vs baseline: 1.0099x; 1.0006x over previous
; __device__ __forceinline__ unsigned pk2(float lo, float hi) { return f2bf(lo) | (f2bf(hi) << 16); }
; __device__ __forceinline__ void gla_scan(const float* UPD, const float* DEC, bf16* ST, int gtid, int gthreads) {
;     ...
;         for (int c0 = 0; c0 < 64; c0 += 16) {
;             f32x4 dv[16], uv[16];
; #pragma unroll
;             for (int i = 0; i < 16; ++i) { const size_t unit = (size_t)((c0 + i) * 4 + h); dv[i] = *(const f32x4*)(DEC + unit * 64 + 4 * kq); uv[i] = *(const f32x4*)(UPD + unit * 8192 + v * 64 + 4 * kq); }
;             asm volatile("" : "+v"(dv[0]), "+v"(dv[1]), "+v"(dv[2]), "+v"(dv[3]), "+v"(dv[4]), "+v"(dv[5]), "+v"(dv[6]), "+v"(dv[7]) :: "memory");
;             asm volatile("" : "+v"(dv[8]), "+v"(dv[9]), "+v"(dv[10]), "+v"(dv[11]), "+v"(dv[12]), "+v"(dv[13]), "+v"(dv[14]), "+v"(dv[15]) :: "memory");
;             asm volatile("" : "+v"(uv[0]), "+v"(uv[1]), "+v"(uv[2]), "+v"(uv[3]), "+v"(uv[4]), "+v"(uv[5]), "+v"(uv[6]), "+v"(uv[7]) :: "memory");
;             asm volatile("" : "+v"(uv[8]), "+v"(uv[9]), "+v"(uv[10]), "+v"(uv[11]), "+v"(uv[12]), "+v"(uv[13]), "+v"(uv[14]), "+v"(uv[15]) :: "memory");
; #pragma unroll
;             for (int i = 0; i < 16; ++i) {
;                 const size_t unit = (size_t)((c0 + i) * 4 + h);
;                 s = dv[i] * s + uv[i];
;                 u32x2 w; w.x = pk2(s[0], s[1]); w.y = pk2(s[2], s[3]);
;                 *(u32x2*)(ST + unit * 8192 + v * 64 + 4 * kq) = w;
.LBB0_473:
	v_lshl_add_u64 v[26:27], s[34:35], 0, v[18:19]
	v_add_co_u32_e32 v0, vcc, 0x401000, v26
	v_lshl_add_u64 v[24:25], s[34:35], 0, v[16:17]
	s_nop 0
	v_addc_co_u32_e32 v1, vcc, 0, v27, vcc
	v_add_co_u32_e32 v2, vcc, 0x400000, v26
	global_load_dwordx4 v[48:51], v[0:1], off offset:3072
	global_load_dwordx4 v[52:55], v[0:1], off offset:2048
	global_load_dwordx4 v[56:59], v[0:1], off offset:1024
	global_load_dwordx4 v[60:63], v[0:1], off
	v_addc_co_u32_e32 v3, vcc, 0, v27, vcc
	v_add_co_u32_e32 v80, vcc, 0x403000, v26
	global_load_dwordx4 v[64:67], v[2:3], off offset:3072
	global_load_dwordx4 v[68:71], v[2:3], off offset:2048
	global_load_dwordx4 v[72:75], v[2:3], off offset:1024
	global_load_dwordx4 v[76:79], v[2:3], off
	v_addc_co_u32_e32 v81, vcc, 0, v27, vcc
	v_add_co_u32_e32 v26, vcc, 0x402000, v26
	global_load_dwordx4 v[0:3], v[80:81], off offset:3072
	global_load_dwordx4 v[4:7], v[80:81], off offset:2048
	global_load_dwordx4 v[8:11], v[80:81], off offset:1024
	s_nop 0
	global_load_dwordx4 v[80:83], v[80:81], off
	v_addc_co_u32_e32 v27, vcc, 0, v27, vcc
	v_add_co_u32_e32 v100, vcc, 0x190e0000, v24
	global_load_dwordx4 v[84:87], v[26:27], off offset:3072
	global_load_dwordx4 v[88:91], v[26:27], off offset:2048
	global_load_dwordx4 v[92:95], v[26:27], off offset:1024
	global_load_dwordx4 v[96:99], v[26:27], off
	v_addc_co_u32_e32 v101, vcc, 0, v25, vcc
	v_add_co_u32_e32 v26, vcc, 0x190c0000, v24
	v_lshl_add_u64 v[28:29], s[34:35], 0, v[14:15]
	s_nop 0
	v_addc_co_u32_e32 v27, vcc, 0, v25, vcc
	v_add_co_u32_e32 v108, vcc, 0x190a0000, v24
	global_load_dwordx4 v[100:103], v[100:101], off nt
	s_nop 0
	global_load_dwordx4 v[104:107], v[26:27], off nt
	v_addc_co_u32_e32 v109, vcc, 0, v25, vcc
	v_add_co_u32_e32 v26, vcc, 0x19080000, v24
	v_add_co_u32_e64 v160, s[0:1], s21, v28
	s_nop 0
	v_addc_co_u32_e32 v27, vcc, 0, v25, vcc
	v_add_co_u32_e32 v116, vcc, 0x19060000, v24
	global_load_dwordx4 v[108:111], v[108:109], off nt
	s_nop 0
	global_load_dwordx4 v[112:115], v[26:27], off nt
	v_addc_co_u32_e32 v117, vcc, 0, v25, vcc
	v_add_co_u32_e32 v26, vcc, 0x19040000, v24
	v_addc_co_u32_e64 v161, s[0:1], 0, v29, s[0:1]
	s_nop 0
	v_addc_co_u32_e32 v27, vcc, 0, v25, vcc
	v_add_co_u32_e32 v124, vcc, 0x19020000, v24
	global_load_dwordx4 v[116:119], v[116:117], off nt
	s_nop 0
	global_load_dwordx4 v[120:123], v[26:27], off nt
	v_addc_co_u32_e32 v125, vcc, 0, v25, vcc
	v_add_co_u32_e32 v26, vcc, 0x19000000, v24
	v_add_co_u32_e64 v162, s[0:1], s28, v28
	s_nop 0
	v_addc_co_u32_e32 v27, vcc, 0, v25, vcc
	v_add_co_u32_e32 v132, vcc, 0x191e0000, v24
	global_load_dwordx4 v[124:127], v[124:125], off nt
	s_nop 0
	global_load_dwordx4 v[128:131], v[26:27], off nt
	v_addc_co_u32_e32 v133, vcc, 0, v25, vcc
	v_add_co_u32_e32 v26, vcc, 0x191c0000, v24
	v_addc_co_u32_e64 v163, s[0:1], 0, v29, s[0:1]
	s_nop 0
	v_addc_co_u32_e32 v27, vcc, 0, v25, vcc
	v_add_co_u32_e32 v140, vcc, 0x191a0000, v24
	global_load_dwordx4 v[132:135], v[132:133], off nt
	s_nop 0
	global_load_dwordx4 v[136:139], v[26:27], off nt
	v_addc_co_u32_e32 v141, vcc, 0, v25, vcc
	v_add_co_u32_e32 v26, vcc, 0x19180000, v24
	v_add_co_u32_e64 v164, s[0:1], s29, v28
	s_nop 0
	v_addc_co_u32_e32 v27, vcc, 0, v25, vcc
	v_add_co_u32_e32 v148, vcc, 0x19160000, v24
	global_load_dwordx4 v[140:143], v[140:141], off nt
	s_nop 0
	global_load_dwordx4 v[144:147], v[26:27], off nt
	v_addc_co_u32_e32 v149, vcc, 0, v25, vcc
	v_add_co_u32_e32 v26, vcc, 0x19140000, v24
	v_addc_co_u32_e64 v165, s[0:1], 0, v29, s[0:1]
	s_nop 0
	v_addc_co_u32_e32 v27, vcc, 0, v25, vcc
	v_add_co_u32_e32 v156, vcc, 0x19120000, v24
	global_load_dwordx4 v[148:151], v[148:149], off nt
	s_nop 0
	global_load_dwordx4 v[152:155], v[26:27], off nt
	v_addc_co_u32_e32 v157, vcc, 0, v25, vcc
	v_add_co_u32_e32 v158, vcc, 0x19100000, v24
	v_add_co_u32_e64 v166, s[0:1], s30, v28
	s_nop 0
	v_addc_co_u32_e32 v159, vcc, 0, v25, vcc
	global_load_dwordx4 v[24:27], v[156:157], off nt
	s_nop 0
	global_load_dwordx4 v[156:159], v[158:159], off nt
	v_addc_co_u32_e64 v167, s[0:1], 0, v29, s[0:1]
	v_add_co_u32_e64 v168, s[0:1], s31, v28
	s_waitcnt vmcnt(24)
	s_waitcnt vmcnt(16)
	s_waitcnt vmcnt(8)
	v_addc_co_u32_e64 v169, s[0:1], 0, v29, s[0:1]
	v_add_co_u32_e64 v170, s[0:1], s37, v28
	v_pk_fma_f32 v[22:23], v[22:23], v[78:79], v[130:131]
	s_nop 0
	v_addc_co_u32_e64 v171, s[0:1], 0, v29, s[0:1]
	v_pk_fma_f32 v[20:21], v[20:21], v[76:77], v[128:129]
	v_add_co_u32_e64 v172, s[0:1], s39, v28
	v_bfe_u32 v12, v20, 16, 1
	v_bfe_u32 v76, v21, 16, 1
	v_bfe_u32 v77, v22, 16, 1
	v_bfe_u32 v78, v23, 16, 1
	v_pk_fma_f32 v[74:75], v[74:75], v[22:23], v[126:127]
	v_pk_fma_f32 v[72:73], v[72:73], v[20:21], v[124:125]
	v_addc_co_u32_e64 v173, s[0:1], 0, v29, s[0:1]
	v_add3_u32 v12, v20, v12, s11
	v_add3_u32 v76, v21, v76, s11
	v_add3_u32 v77, v22, v77, s11
	v_add3_u32 v78, v23, v78, s11
	v_bfe_u32 v79, v72, 16, 1
	v_bfe_u32 v124, v73, 16, 1
	v_bfe_u32 v125, v74, 16, 1
	v_bfe_u32 v126, v75, 16, 1
	v_pk_fma_f32 v[20:21], v[70:71], v[74:75], v[122:123]
	v_pk_fma_f32 v[22:23], v[68:69], v[72:73], v[120:121]
	v_add_co_u32_e64 v44, s[0:1], s56, v28
	v_lshrrev_b32_e32 v12, 16, v12
	v_lshrrev_b32_e32 v69, 16, v77
	v_add3_u32 v70, v72, v79, s11
	v_add3_u32 v71, v73, v124, s11
	v_add3_u32 v72, v74, v125, s11
	v_add3_u32 v73, v75, v126, s11
	v_bfe_u32 v74, v22, 16, 1
	v_bfe_u32 v75, v23, 16, 1
	v_bfe_u32 v77, v20, 16, 1
	v_bfe_u32 v79, v21, 16, 1
	v_pk_fma_f32 v[66:67], v[66:67], v[20:21], v[118:119]
	v_pk_fma_f32 v[64:65], v[64:65], v[22:23], v[116:117]
	v_addc_co_u32_e64 v45, s[0:1], 0, v29, s[0:1]
	v_and_or_b32 v68, v76, s20, v12
	v_and_or_b32 v69, v78, s20, v69
	v_lshrrev_b32_e32 v12, 16, v70
	v_lshrrev_b32_e32 v70, 16, v72
	v_add3_u32 v72, v22, v74, s11
	v_add3_u32 v74, v23, v75, s11
	v_add3_u32 v75, v20, v77, s11
	v_add3_u32 v76, v21, v79, s11
	v_bfe_u32 v77, v64, 16, 1
	v_bfe_u32 v78, v65, 16, 1
	v_bfe_u32 v79, v66, 16, 1
	v_bfe_u32 v116, v67, 16, 1
	v_pk_fma_f32 v[20:21], v[62:63], v[66:67], v[114:115]
	v_pk_fma_f32 v[22:23], v[60:61], v[64:65], v[112:113]
	v_add_co_u32_e64 v42, s[0:1], s57, v28
	s_waitcnt vmcnt(0)
; __device__ __forceinline__ unsigned pk2(float lo, float hi) { return f2bf(lo) | (f2bf(hi) << 16); }
; __device__ __forceinline__ void gla_scan(const float* UPD, const float* DEC, bf16* ST, int gtid, int gthreads) {
;     ...
; #pragma unroll
;             for (int i = 0; i < 16; ++i) {
;                 const size_t unit = (size_t)((c0 + i) * 4 + h);
;                 s = dv[i] * s + uv[i];
;                 u32x2 w; w.x = pk2(s[0], s[1]); w.y = pk2(s[2], s[3]);
;                 *(u32x2*)(ST + unit * 8192 + v * 64 + 4 * kq) = w;
;             }
	global_store_dwordx2 v[160:161], v[68:69], off
	v_and_or_b32 v60, v71, s20, v12
	v_and_or_b32 v61, v73, s20, v70
	v_lshrrev_b32_e32 v12, 16, v72
	v_lshrrev_b32_e32 v62, 16, v75
	v_add3_u32 v63, v64, v77, s11
	v_add3_u32 v64, v65, v78, s11
	v_add3_u32 v65, v66, v79, s11
	v_add3_u32 v66, v67, v116, s11
	v_bfe_u32 v67, v22, 16, 1
	v_bfe_u32 v68, v23, 16, 1
	v_bfe_u32 v69, v20, 16, 1
	v_bfe_u32 v70, v21, 16, 1
	v_pk_fma_f32 v[58:59], v[58:59], v[20:21], v[110:111]
	v_pk_fma_f32 v[56:57], v[56:57], v[22:23], v[108:109]
	v_addc_co_u32_e64 v43, s[0:1], 0, v29, s[0:1]
	global_store_dwordx2 v[162:163], v[60:61], off
	v_and_or_b32 v60, v74, s20, v12
	v_and_or_b32 v61, v76, s20, v62
	v_lshrrev_b32_e32 v12, 16, v63
	v_lshrrev_b32_e32 v62, 16, v65
	v_add3_u32 v63, v22, v67, s11
	v_add3_u32 v65, v23, v68, s11
	v_add3_u32 v67, v20, v69, s11
	v_add3_u32 v68, v21, v70, s11
	v_bfe_u32 v69, v56, 16, 1
	v_bfe_u32 v70, v57, 16, 1
	v_bfe_u32 v71, v58, 16, 1
	v_bfe_u32 v72, v59, 16, 1
	v_pk_fma_f32 v[20:21], v[54:55], v[58:59], v[106:107]
	v_pk_fma_f32 v[22:23], v[52:53], v[56:57], v[104:105]
	v_add_co_u32_e64 v40, s[0:1], s70, v28
	global_store_dwordx2 v[164:165], v[60:61], off
	v_and_or_b32 v52, v64, s20, v12
	v_and_or_b32 v53, v66, s20, v62
	v_lshrrev_b32_e32 v12, 16, v63
	v_lshrrev_b32_e32 v54, 16, v67
	v_add3_u32 v55, v56, v69, s11
	v_add3_u32 v56, v57, v70, s11
	v_add3_u32 v57, v58, v71, s11
	v_add3_u32 v58, v59, v72, s11
	v_bfe_u32 v59, v22, 16, 1
	v_bfe_u32 v60, v23, 16, 1
	v_bfe_u32 v61, v20, 16, 1
	v_bfe_u32 v62, v21, 16, 1
	v_pk_fma_f32 v[50:51], v[50:51], v[20:21], v[102:103]
	v_pk_fma_f32 v[48:49], v[48:49], v[22:23], v[100:101]
	v_addc_co_u32_e64 v41, s[0:1], 0, v29, s[0:1]
	global_store_dwordx2 v[166:167], v[52:53], off
	v_and_or_b32 v52, v65, s20, v12
	v_and_or_b32 v53, v68, s20, v54
	v_lshrrev_b32_e32 v12, 16, v55
	v_lshrrev_b32_e32 v54, 16, v57
	v_add3_u32 v55, v22, v59, s11
	v_add3_u32 v57, v23, v60, s11
	v_add3_u32 v59, v20, v61, s11
	v_add3_u32 v60, v21, v62, s11
	v_bfe_u32 v61, v48, 16, 1
	v_bfe_u32 v62, v49, 16, 1
	v_bfe_u32 v63, v50, 16, 1
	v_pk_fma_f32 v[20:21], v[98:99], v[50:51], v[158:159]
	v_pk_fma_f32 v[22:23], v[96:97], v[48:49], v[156:157]
	v_add_co_u32_e64 v38, s[0:1], s71, v28
	v_bfe_u32 v64, v51, 16, 1
	global_store_dwordx2 v[168:169], v[52:53], off
	v_and_or_b32 v52, v56, s20, v12
	v_and_or_b32 v53, v58, s20, v54
	v_lshrrev_b32_e32 v12, 16, v55
	v_lshrrev_b32_e32 v54, 16, v59
	v_add3_u32 v55, v48, v61, s11
	v_add3_u32 v56, v49, v62, s11
	v_add3_u32 v50, v50, v63, s11
	v_bfe_u32 v58, v22, 16, 1
	v_bfe_u32 v59, v23, 16, 1
	v_bfe_u32 v61, v20, 16, 1
	v_bfe_u32 v62, v21, 16, 1
	v_pk_fma_f32 v[26:27], v[94:95], v[20:21], v[26:27]
	v_pk_fma_f32 v[24:25], v[92:93], v[22:23], v[24:25]
	v_addc_co_u32_e64 v39, s[0:1], 0, v29, s[0:1]
	v_add3_u32 v51, v51, v64, s11
	global_store_dwordx2 v[170:171], v[52:53], off
	v_and_or_b32 v48, v57, s20, v12
	v_and_or_b32 v49, v60, s20, v54
	v_lshrrev_b32_e32 v12, 16, v55
	v_lshrrev_b32_e32 v50, 16, v50
	v_add3_u32 v52, v22, v58, s11
	v_add3_u32 v53, v23, v59, s11
	v_add3_u32 v54, v20, v61, s11
	v_add3_u32 v55, v21, v62, s11
	v_bfe_u32 v57, v24, 16, 1
	v_bfe_u32 v58, v25, 16, 1
	v_bfe_u32 v59, v26, 16, 1
	v_bfe_u32 v60, v27, 16, 1
	v_pk_fma_f32 v[20:21], v[90:91], v[26:27], v[154:155]
	v_pk_fma_f32 v[22:23], v[88:89], v[24:25], v[152:153]
	v_add_co_u32_e64 v36, s[0:1], s72, v28
	global_store_dwordx2 v[172:173], v[48:49], off
	v_and_or_b32 v48, v56, s20, v12
	v_and_or_b32 v49, v51, s20, v50
	v_lshrrev_b32_e32 v12, 16, v52
	v_lshrrev_b32_e32 v50, 16, v54
	v_add3_u32 v51, v24, v57, s11
	v_add3_u32 v52, v25, v58, s11
	v_add3_u32 v54, v26, v59, s11
	v_add3_u32 v56, v27, v60, s11
	v_bfe_u32 v57, v22, 16, 1
	v_bfe_u32 v58, v23, 16, 1
	v_bfe_u32 v59, v20, 16, 1
	v_bfe_u32 v60, v21, 16, 1
	v_pk_fma_f32 v[24:25], v[86:87], v[20:21], v[150:151]
; __device__ __forceinline__ unsigned pk2(float lo, float hi) { return f2bf(lo) | (f2bf(hi) << 16); }
; __device__ __forceinline__ void gla_scan(const float* UPD, const float* DEC, bf16* ST, int gtid, int gthreads) {
;     for (int p = gtid; p < 4 * 128 * 16; p += gthreads) {
;         const int h = p >> 11, rem = p & 2047, v = rem >> 4, kq = rem & 15;
;         f32x4 s = (f32x4){0.f, 0.f, 0.f, 0.f};
; #pragma unroll 1
;         for (int c0 = 0; c0 < 64; c0 += 16) {
;             f32x4 dv[16], uv[16];
; #pragma unroll
;             for (int i = 0; i < 16; ++i) { const size_t unit = (size_t)((c0 + i) * 4 + h); dv[i] = *(const f32x4*)(DEC + unit * 64 + 4 * kq); uv[i] = *(const f32x4*)(UPD + unit * 8192 + v * 64 + 4 * kq); }
;             asm volatile("" : "+v"(dv[0]), "+v"(dv[1]), "+v"(dv[2]), "+v"(dv[3]), "+v"(dv[4]), "+v"(dv[5]), "+v"(dv[6]), "+v"(dv[7]) :: "memory");
;             asm volatile("" : "+v"(dv[8]), "+v"(dv[9]), "+v"(dv[10]), "+v"(dv[11]), "+v"(dv[12]), "+v"(dv[13]), "+v"(dv[14]), "+v"(dv[15]) :: "memory");
;             asm volatile("" : "+v"(uv[0]), "+v"(uv[1]), "+v"(uv[2]), "+v"(uv[3]), "+v"(uv[4]), "+v"(uv[5]), "+v"(uv[6]), "+v"(uv[7]) :: "memory");
;             asm volatile("" : "+v"(uv[8]), "+v"(uv[9]), "+v"(uv[10]), "+v"(uv[11]), "+v"(uv[12]), "+v"(uv[13]), "+v"(uv[14]), "+v"(uv[15]) :: "memory");
; #pragma unroll
;             for (int i = 0; i < 16; ++i) {
;                 const size_t unit = (size_t)((c0 + i) * 4 + h);
;                 s = dv[i] * s + uv[i];
;                 u32x2 w; w.x = pk2(s[0], s[1]); w.y = pk2(s[2], s[3]);
;                 *(u32x2*)(ST + unit * 8192 + v * 64 + 4 * kq) = w;
;             }
	v_pk_fma_f32 v[26:27], v[84:85], v[22:23], v[148:149]
	v_addc_co_u32_e64 v37, s[0:1], 0, v29, s[0:1]
	global_store_dwordx2 v[44:45], v[48:49], off
	v_and_or_b32 v44, v53, s20, v12
	v_and_or_b32 v45, v55, s20, v50
	v_lshrrev_b32_e32 v12, 16, v51
	v_lshrrev_b32_e32 v48, 16, v54
	v_add3_u32 v49, v22, v57, s11
	v_add3_u32 v50, v23, v58, s11
	v_add3_u32 v51, v20, v59, s11
	v_add3_u32 v53, v21, v60, s11
	v_bfe_u32 v54, v26, 16, 1
	v_bfe_u32 v57, v24, 16, 1
	v_pk_fma_f32 v[20:21], v[82:83], v[24:25], v[146:147]
	v_pk_fma_f32 v[22:23], v[80:81], v[26:27], v[144:145]
	v_add_co_u32_e64 v34, s[0:1], s73, v28
	v_bfe_u32 v55, v27, 16, 1
	v_bfe_u32 v58, v25, 16, 1
	global_store_dwordx2 v[42:43], v[44:45], off
	v_and_or_b32 v42, v52, s20, v12
	v_and_or_b32 v43, v56, s20, v48
	v_lshrrev_b32_e32 v12, 16, v49
	v_lshrrev_b32_e32 v44, 16, v51
	v_add3_u32 v26, v26, v54, s11
	v_add3_u32 v45, v24, v57, s11
	v_bfe_u32 v49, v22, 16, 1
	v_bfe_u32 v51, v23, 16, 1
	v_bfe_u32 v52, v20, 16, 1
	v_bfe_u32 v54, v21, 16, 1
	v_pk_fma_f32 v[10:11], v[10:11], v[20:21], v[142:143]
	v_pk_fma_f32 v[8:9], v[8:9], v[22:23], v[140:141]
	v_addc_co_u32_e64 v35, s[0:1], 0, v29, s[0:1]
	v_add3_u32 v27, v27, v55, s11
	v_add3_u32 v48, v25, v58, s11
	global_store_dwordx2 v[40:41], v[42:43], off
	v_and_or_b32 v24, v50, s20, v12
	v_and_or_b32 v25, v53, s20, v44
	v_lshrrev_b32_e32 v12, 16, v26
	v_lshrrev_b32_e32 v26, 16, v45
	v_add3_u32 v22, v22, v49, s11
	v_add3_u32 v40, v23, v51, s11
	v_add3_u32 v20, v20, v52, s11
	v_add3_u32 v41, v21, v54, s11
	v_bfe_u32 v21, v8, 16, 1
	v_bfe_u32 v23, v9, 16, 1
	v_bfe_u32 v42, v10, 16, 1
	v_pk_fma_f32 v[6:7], v[6:7], v[10:11], v[138:139]
	v_pk_fma_f32 v[4:5], v[4:5], v[8:9], v[136:137]
	v_add_co_u32_e64 v32, s[0:1], s74, v28
	v_bfe_u32 v43, v11, 16, 1
	global_store_dwordx2 v[38:39], v[24:25], off
	v_and_or_b32 v24, v27, s20, v12
	v_and_or_b32 v25, v48, s20, v26
	v_lshrrev_b32_e32 v12, 16, v22
	v_lshrrev_b32_e32 v26, 16, v20
	v_add3_u32 v8, v8, v21, s11
	v_add3_u32 v9, v9, v23, s11
	v_add3_u32 v10, v10, v42, s11
	v_bfe_u32 v27, v4, 16, 1
	v_bfe_u32 v39, v6, 16, 1
	v_pk_fma_f32 v[22:23], v[2:3], v[6:7], v[134:135]
	v_pk_fma_f32 v[20:21], v[0:1], v[4:5], v[132:133]
	v_addc_co_u32_e64 v33, s[0:1], 0, v29, s[0:1]
	v_add3_u32 v11, v11, v43, s11
	v_bfe_u32 v38, v5, 16, 1
	v_bfe_u32 v42, v7, 16, 1
	v_and_or_b32 v0, v40, s20, v12
	v_and_or_b32 v1, v41, s20, v26
	v_lshrrev_b32_e32 v2, 16, v8
	v_lshrrev_b32_e32 v3, 16, v10
	v_add3_u32 v4, v4, v27, s11
	v_add3_u32 v6, v6, v39, s11
	v_bfe_u32 v8, v20, 16, 1
	v_bfe_u32 v12, v22, 16, 1
	v_add_co_u32_e64 v30, s[0:1], s75, v28
	global_store_dwordx2 v[36:37], v[24:25], off
	v_add3_u32 v5, v5, v38, s11
	v_add3_u32 v7, v7, v42, s11
	v_bfe_u32 v10, v21, 16, 1
	v_bfe_u32 v24, v23, 16, 1
	global_store_dwordx2 v[34:35], v[0:1], off
	v_and_or_b32 v0, v9, s20, v2
	v_and_or_b32 v1, v11, s20, v3
	v_lshrrev_b32_e32 v2, 16, v4
	v_lshrrev_b32_e32 v3, 16, v6
	v_add3_u32 v4, v20, v8, s11
	v_add3_u32 v8, v22, v12, s11
	s_add_i32 s77, s77, 16
	v_addc_co_u32_e64 v31, s[0:1], 0, v29, s[0:1]
	v_add_co_u32_e32 v28, vcc, 0x1d0f0000, v28
	v_add3_u32 v6, v21, v10, s11
	v_add3_u32 v9, v23, v24, s11
	global_store_dwordx2 v[32:33], v[0:1], off
	v_and_or_b32 v0, v5, s20, v2
	v_and_or_b32 v1, v7, s20, v3
	v_lshrrev_b32_e32 v2, 16, v4
	v_lshrrev_b32_e32 v3, 16, v8
	v_lshl_add_u64 v[14:15], v[14:15], 0, s[64:65]
	v_lshl_add_u64 v[16:17], v[16:17], 0, s[66:67]
	v_lshl_add_u64 v[18:19], v[18:19], 0, s[68:69]
	s_cmp_gt_u32 s77, 47
	v_addc_co_u32_e32 v29, vcc, 0, v29, vcc
	global_store_dwordx2 v[30:31], v[0:1], off
	v_and_or_b32 v0, v6, s20, v2
	v_and_or_b32 v1, v9, s20, v3
	global_store_dwordx2 v[28:29], v[0:1], off
	s_cbranch_scc0 .LBB0_473
	v_add_u32_e32 v46, s2, v46
	v_cmp_lt_i32_e32 vcc, s76, v46
	s_or_b64 s[62:63], vcc, s[62:63]
	v_add_u32_e32 v47, s3, v47
	s_andn2_b64 exec, exec, s[62:63]
	s_cbranch_execnz .LBB0_472

; __device__ __forceinline__ void gla_out_unit(const bf16* PROJ, const bf16* ST, const float* norm_o, bf16* Y, int unit, int lane) {
;     ...
; #pragma unroll 1
;     for (int ki = 0; ki < 2; ++ki) {
;         bf16x8 bq[4], as[8];
; #pragma unroll
;         for (int ni = 0; ni < 4; ++ni) bq[ni] = *(const bf16x8*)(PROJ + (size_t)(tok0 + 16 * ni + fr) * NPROJ + 1024 + h * 64 + 32 * ki + 8 * fq);
; #pragma unroll
;         for (int mi = 0; mi < 8; ++mi) as[mi] = *(const bf16x8*)(st + (16 * mi + fr) * 64 + 32 * ki + 8 * fq);
;         asm volatile("" : "+v"(as[0]), "+v"(as[1]), "+v"(as[2]), "+v"(as[3]), "+v"(as[4]), "+v"(as[5]), "+v"(as[6]), "+v"(as[7]), "+v"(bq[0]), "+v"(bq[1]), "+v"(bq[2]), "+v"(bq[3]));
; #pragma unroll
;         for (int mi = 0; mi < 8; ++mi)
; #pragma unroll
;             for (int ni = 0; ni < 4; ++ni) acc[mi][ni] = __builtin_amdgcn_mfma_f32_16x16x32_bf16(as[mi], bq[ni], acc[mi][ni], 0, 0, 0);
;     }
;     f32x4 nov[8];
; #pragma unroll
;     for (int mi = 0; mi < 8; ++mi) nov[mi] = *(const f32x4*)(norm_o + h * 128 + 16 * mi + 4 * fq);
; #pragma unroll
;     for (int ni = 0; ni < 4; ++ni) {
;         u32x2 gg1[8];
; #pragma unroll
;         for (int mi = 0; mi < 8; ++mi) gg1[mi] = *(const u32x2*)(PROJ + (size_t)(tok0 + 16 * ni + fr) * NPROJ + 2048 + h * 128 + 16 * mi + 4 * fq);
;         asm volatile("" : "+v"(gg1[0]), "+v"(gg1[1]), "+v"(gg1[2]), "+v"(gg1[3]), "+v"(gg1[4]), "+v"(gg1[5]), "+v"(gg1[6]), "+v"(gg1[7]));
;         float ss = 0.f;
; #pragma unroll
;         for (int mi = 0; mi < 8; ++mi) { acc[mi][ni] = acc[mi][ni] * 0.125f; const f32x4 o = acc[mi][ni]; ss += (o[0] * o[0] + o[1] * o[1]) + (o[2] * o[2] + o[3] * o[3]); }
.LBB0_523:
	s_lshl_b64 s[2:3], s[72:73], 1
	v_lshl_add_u64 v[172:173], v[166:167], 0, s[2:3]
	v_add_co_u32_e32 v196, vcc, s21, v172
	v_lshl_add_u64 v[188:189], v[52:53], 0, s[2:3]
	s_nop 0
	v_addc_co_u32_e32 v197, vcc, 0, v173, vcc
	v_add_co_u32_e32 v212, vcc, s28, v172
	v_lshl_add_u64 v[184:185], v[54:55], 0, s[2:3]
	s_nop 0
	v_addc_co_u32_e32 v213, vcc, 0, v173, vcc
	v_add_co_u32_e32 v220, vcc, s29, v172
	v_lshl_add_u64 v[180:181], v[162:163], 0, s[2:3]
	v_lshl_add_u64 v[176:177], v[164:165], 0, s[2:3]
	v_addc_co_u32_e32 v221, vcc, 0, v173, vcc
	global_load_dwordx4 v[168:171], v[172:173], off offset:2048 nt
	s_nop 0
	global_load_dwordx4 v[172:175], v[172:173], off nt
	s_nop 0
	global_load_dwordx4 v[176:179], v[176:177], off offset:2048 nt
	s_nop 0
	global_load_dwordx4 v[180:183], v[180:181], off offset:2048 nt
	s_nop 0
	global_load_dwordx4 v[184:187], v[184:185], off offset:2048 nt
	s_nop 0
	global_load_dwordx4 v[188:191], v[188:189], off offset:2048 nt
	s_nop 0
	global_load_dwordx4 v[192:195], v[196:197], off offset:2048 nt
	s_nop 0
	global_load_dwordx4 v[196:199], v[196:197], off nt
	s_nop 0
	global_load_dwordx4 v[208:211], v[212:213], off offset:2048 nt
	s_nop 0
	global_load_dwordx4 v[212:215], v[212:213], off nt
	s_nop 0
	global_load_dwordx4 v[216:219], v[220:221], off offset:2048 nt
	s_nop 0
	global_load_dwordx4 v[220:223], v[220:221], off nt
	s_mov_b64 s[72:73], 32
	s_and_b64 vcc, exec, s[70:71]
	s_mov_b64 s[70:71], 0
	s_waitcnt vmcnt(0)
	s_nop 0
	v_mfma_f32_16x16x32_bf16 v[128:131], v[172:175], v[188:191], v[128:131]
	v_mfma_f32_16x16x32_bf16 v[124:127], v[172:175], v[184:187], v[124:127]
	v_mfma_f32_16x16x32_bf16 v[92:95], v[172:175], v[180:183], v[92:95]
	v_mfma_f32_16x16x32_bf16 v[28:31], v[172:175], v[176:179], v[28:31]
	v_mfma_f32_16x16x32_bf16 v[64:67], v[168:171], v[188:191], v[64:67]
	v_mfma_f32_16x16x32_bf16 v[120:123], v[168:171], v[184:187], v[120:123]
	v_mfma_f32_16x16x32_bf16 v[88:91], v[168:171], v[180:183], v[88:91]
	v_mfma_f32_16x16x32_bf16 v[24:27], v[168:171], v[176:179], v[24:27]
	v_mfma_f32_16x16x32_bf16 v[56:59], v[220:223], v[188:191], v[56:59]
	v_mfma_f32_16x16x32_bf16 v[112:115], v[220:223], v[184:187], v[112:115]
	v_mfma_f32_16x16x32_bf16 v[80:83], v[220:223], v[180:183], v[80:83]
	v_mfma_f32_16x16x32_bf16 v[12:15], v[220:223], v[176:179], v[12:15]
	v_mfma_f32_16x16x32_bf16 v[40:43], v[216:219], v[188:191], v[40:43]
	v_mfma_f32_16x16x32_bf16 v[104:107], v[216:219], v[184:187], v[104:107]
	v_mfma_f32_16x16x32_bf16 v[72:75], v[216:219], v[180:183], v[72:75]
	v_mfma_f32_16x16x32_bf16 v[8:11], v[216:219], v[176:179], v[8:11]
	v_mfma_f32_16x16x32_bf16 v[36:39], v[212:215], v[188:191], v[36:39]
	v_mfma_f32_16x16x32_bf16 v[100:103], v[212:215], v[184:187], v[100:103]
	v_mfma_f32_16x16x32_bf16 v[68:71], v[212:215], v[180:183], v[68:71]
	v_mfma_f32_16x16x32_bf16 v[4:7], v[212:215], v[176:179], v[4:7]
	v_mfma_f32_16x16x32_bf16 v[32:35], v[208:211], v[188:191], v[32:35]
	v_mfma_f32_16x16x32_bf16 v[96:99], v[208:211], v[184:187], v[96:99]
	v_mfma_f32_16x16x32_bf16 v[60:63], v[208:211], v[180:183], v[60:63]
	v_mfma_f32_16x16x32_bf16 v[0:3], v[208:211], v[176:179], v[0:3]
	v_mfma_f32_16x16x32_bf16 v[44:47], v[196:199], v[188:191], v[44:47]
	v_mfma_f32_16x16x32_bf16 v[108:111], v[196:199], v[184:187], v[108:111]
	v_mfma_f32_16x16x32_bf16 v[76:79], v[196:199], v[180:183], v[76:79]
	v_mfma_f32_16x16x32_bf16 v[16:19], v[196:199], v[176:179], v[16:19]
	v_mfma_f32_16x16x32_bf16 v[48:51], v[192:195], v[188:191], v[48:51]
	v_mfma_f32_16x16x32_bf16 v[116:119], v[192:195], v[184:187], v[116:119]
	v_mfma_f32_16x16x32_bf16 v[84:87], v[192:195], v[180:183], v[84:87]
	v_mfma_f32_16x16x32_bf16 v[20:23], v[192:195], v[176:179], v[20:23]
	s_cbranch_vccnz .LBB0_523
	v_lshl_add_u64 v[160:161], v[160:161], 0, s[6:7]
	v_lshl_add_u64 v[160:161], v[160:161], 0, v[132:133]
	v_lshl_add_u64 v[162:163], v[160:161], 0, s[64:65]
	v_add_co_u32_e32 v160, vcc, 0x1000, v160
	global_load_dwordx4 v[52:55], v[136:137], off nt
	s_nop 0
	v_addc_co_u32_e32 v161, vcc, 0, v161, vcc
	global_load_dwordx2 v[210:211], v[162:163], off offset:32 nt
	global_load_dwordx2 v[190:191], v[162:163], off offset:64 nt
	global_load_dwordx2 v[184:185], v[162:163], off offset:96 nt
	global_load_dwordx2 v[178:179], v[162:163], off offset:128 nt
	global_load_dwordx2 v[212:213], v[160:161], off nt
	global_load_dwordx2 v[172:173], v[162:163], off offset:160 nt
	global_load_dwordx2 v[164:165], v[162:163], off offset:192 nt
	s_nop 0
	global_load_dwordx2 v[160:161], v[162:163], off offset:224 nt
	v_pk_mul_f32 v[216:217], v[128:129], s[66:67] op_sel_hi:[1,0]
	v_pk_mul_f32 v[198:199], v[64:65], s[66:67] op_sel_hi:[1,0]
	v_pk_mul_f32 v[214:215], v[130:131], s[66:67] op_sel_hi:[1,0]
	v_pk_mul_f32 v[196:197], v[66:67], s[66:67] op_sel_hi:[1,0]
	v_mov_b32_e32 v66, v217
	v_mov_b32_e32 v67, v199
	v_mov_b32_e32 v64, v216
	v_mov_b32_e32 v65, v198
	v_pk_mul_f32 v[66:67], v[66:67], v[66:67]
	v_mov_b32_e32 v128, v215
	v_mov_b32_e32 v129, v197
	v_pk_fma_f32 v[64:65], v[64:65], v[64:65], v[66:67]
	v_mov_b32_e32 v66, v214
	v_mov_b32_e32 v67, v196
	v_pk_mul_f32 v[128:129], v[128:129], v[128:129]
	v_pk_mul_f32 v[192:193], v[58:59], s[66:67] op_sel_hi:[1,0]
	v_pk_mul_f32 v[194:195], v[56:57], s[66:67] op_sel_hi:[1,0]
	v_pk_fma_f32 v[66:67], v[66:67], v[66:67], v[128:129]
	v_pk_mul_f32 v[56:57], v[192:193], v[192:193]
	v_pk_mul_f32 v[58:59], v[194:195], v[194:195]
	v_pk_add_f32 v[64:65], v[64:65], v[66:67]
	v_pk_mov_b32 v[66:67], v[58:59], v[56:57] op_sel:[1,0]
	v_mov_b32_e32 v59, v57
	v_pk_mul_f32 v[182:183], v[36:37], s[66:67] op_sel_hi:[1,0]
	v_pk_add_f32 v[56:57], v[66:67], v[58:59]
; __device__ __forceinline__ unsigned pk2(float lo, float hi) { return f2bf(lo) | (f2bf(hi) << 16); }
; __device__ __forceinline__ float silu_f(float g) { return g * __builtin_amdgcn_rcpf(1.0f + __expf(-g)); }
; __device__ __forceinline__ void gla_out_unit(const bf16* PROJ, const bf16* ST, const float* norm_o, bf16* Y, int unit, int lane) {
;     ...
;     f32x4 nov[8];
; #pragma unroll
;     for (int mi = 0; mi < 8; ++mi) nov[mi] = *(const f32x4*)(norm_o + h * 128 + 16 * mi + 4 * fq);
; #pragma unroll
;     for (int ni = 0; ni < 4; ++ni) {
;         u32x2 gg1[8];
; #pragma unroll
;         for (int mi = 0; mi < 8; ++mi) gg1[mi] = *(const u32x2*)(PROJ + (size_t)(tok0 + 16 * ni + fr) * NPROJ + 2048 + h * 128 + 16 * mi + 4 * fq);
;         asm volatile("" : "+v"(gg1[0]), "+v"(gg1[1]), "+v"(gg1[2]), "+v"(gg1[3]), "+v"(gg1[4]), "+v"(gg1[5]), "+v"(gg1[6]), "+v"(gg1[7]));
;         float ss = 0.f;
; #pragma unroll
;         for (int mi = 0; mi < 8; ++mi) { acc[mi][ni] = acc[mi][ni] * 0.125f; const f32x4 o = acc[mi][ni]; ss += (o[0] * o[0] + o[1] * o[1]) + (o[2] * o[2] + o[3] * o[3]); }
;         ss += __shfl_xor(ss, 16); ss += __shfl_xor(ss, 32);
;         const float rs = __builtin_amdgcn_rsqf(ss * (1.f / 128.f) + EPS);
;         const size_t tok = (size_t)(tok0 + 16 * ni + fr);
; #pragma unroll
;         for (int mi = 0; mi < 8; ++mi) {
;             const int v = h * 128 + 16 * mi + 4 * fq;
;             const f32x4 no = nov[mi]; const u32x2 g2 = gg1[mi];
;             const f32x4 o = acc[mi][ni];
;             const float y0 = o[0] * rs * no[0] * silu_f(bf_lo(g2.x)), y1 = o[1] * rs * no[1] * silu_f(bf_hi(g2.x));
;             const float y2 = o[2] * rs * no[2] * silu_f(bf_lo(g2.y)), y3 = o[3] * rs * no[3] * silu_f(bf_hi(g2.y));
;             u32x2 w; w.x = pk2(y0, y1); w.y = pk2(y2, y3);
;             *(u32x2*)(Y + tok * D + 512 + v) = w;
	v_pk_mul_f32 v[180:181], v[38:39], s[66:67] op_sel_hi:[1,0]
	v_mul_f32_e32 v38, v182, v182
	v_pk_add_f32 v[36:37], v[64:65], v[64:65] op_sel:[0,1] op_sel_hi:[1,0]
	v_pk_mul_f32 v[130:131], v[50:51], s[66:67] op_sel_hi:[1,0]
	v_mov_b32_e32 v37, v38
	v_pk_add_f32 v[38:39], v[56:57], v[56:57] op_sel:[0,1] op_sel_hi:[1,0]
	v_pk_mul_f32 v[162:163], v[48:49], s[66:67] op_sel_hi:[1,0]
	global_load_dwordx4 v[64:67], v[136:137], off offset:64 nt
	global_load_dwordx4 v[56:59], v[136:137], off offset:128 nt
	global_load_dwordx4 v[48:51], v[136:137], off offset:192 nt
	v_pk_mul_f32 v[188:189], v[40:41], s[66:67] op_sel_hi:[1,0]
	v_mul_f32_e32 v40, v183, v183
	v_mov_b32_e32 v39, v40
	v_pk_mul_f32 v[186:187], v[42:43], s[66:67] op_sel_hi:[1,0]
	v_pk_add_f32 v[36:37], v[36:37], v[38:39]
	v_mul_f32_e32 v38, v189, v189
	v_mul_f32_e32 v41, v180, v180
	v_pk_fma_f32 v[38:39], v[188:189], v[188:189], v[38:39] op_sel_hi:[1,1,0]
	v_mul_f32_e32 v40, v187, v187
	v_mul_f32_e32 v42, v181, v181
	v_mov_b32_e32 v39, v41
	v_pk_fma_f32 v[40:41], v[186:187], v[186:187], v[40:41] op_sel_hi:[1,1,0]
	v_pk_mul_f32 v[174:175], v[34:35], s[66:67] op_sel_hi:[1,0]
	v_mov_b32_e32 v41, v42
	v_pk_mul_f32 v[176:177], v[32:33], s[66:67] op_sel_hi:[1,0]
	v_pk_add_f32 v[38:39], v[38:39], v[40:41]
	v_pk_mul_f32 v[32:33], v[174:175], v[174:175]
	v_pk_mul_f32 v[34:35], v[176:177], v[176:177]
	v_pk_add_f32 v[36:37], v[36:37], v[38:39]
	v_pk_mov_b32 v[38:39], v[34:35], v[32:33] op_sel:[1,0]
	v_mov_b32_e32 v35, v33
	v_pk_add_f32 v[32:33], v[38:39], v[34:35]
	v_mul_f32_e32 v38, v162, v162
	v_mul_f32_e32 v39, v163, v163
	v_pk_add_f32 v[34:35], v[36:37], v[36:37] op_sel:[0,1] op_sel_hi:[1,0]
	v_pk_add_f32 v[32:33], v[32:33], v[32:33] op_sel:[0,1] op_sel_hi:[1,0]
	v_pk_mul_f32 v[168:169], v[46:47], s[66:67] op_sel_hi:[1,0]
	v_pk_mul_f32 v[170:171], v[44:45], s[66:67] op_sel_hi:[1,0]
	v_mov_b32_e32 v35, v38
	v_mov_b32_e32 v33, v39
	v_pk_add_f32 v[32:33], v[34:35], v[32:33]
	v_mul_f32_e32 v34, v171, v171
	v_mul_f32_e32 v36, v169, v169
	v_mul_f32_e32 v40, v130, v130
	v_mul_f32_e32 v41, v131, v131
	v_pk_fma_f32 v[34:35], v[170:171], v[170:171], v[34:35] op_sel_hi:[1,1,0]
	v_pk_fma_f32 v[36:37], v[168:169], v[168:169], v[36:37] op_sel_hi:[1,1,0]
	v_mov_b32_e32 v35, v40
	v_mov_b32_e32 v37, v41
	v_pk_add_f32 v[34:35], v[34:35], v[36:37]
	v_lshlrev_b64 v[158:159], 11, v[158:159]
	v_pk_add_f32 v[32:33], v[32:33], v[34:35]
	v_and_b32_e32 v34, 64, v206
	v_add_f32_e32 v32, v32, v33
	v_xor_b32_e32 v33, 16, v206
	v_add_u32_e32 v34, 64, v34
	v_cmp_lt_i32_e32 vcc, v33, v34
	v_lshl_add_u64 v[158:159], v[138:139], 0, v[158:159]
	s_add_i32 s68, s68, s36
	v_cndmask_b32_e32 v33, v206, v33, vcc
	v_lshlrev_b32_e32 v208, 2, v33
	ds_bpermute_b32 v33, v208, v32
	s_cmpk_lt_i32 s68, 0x100
	s_waitcnt lgkmcnt(0)
	v_add_f32_e32 v128, v32, v33
	v_xor_b32_e32 v32, 32, v206
	v_cmp_lt_i32_e32 vcc, v32, v34
	s_nop 1
	v_cndmask_b32_e32 v32, v206, v32, vcc
	v_lshlrev_b32_e32 v209, 2, v32
	ds_bpermute_b32 v129, v209, v128
	global_load_dwordx4 v[44:47], v[136:137], off offset:256 nt
	global_load_dwordx4 v[40:43], v[136:137], off offset:320 nt
	global_load_dwordx4 v[36:39], v[136:137], off offset:384 nt
	global_load_dwordx4 v[32:35], v[136:137], off offset:448 nt
	s_waitcnt vmcnt(7)
	s_waitcnt lgkmcnt(0)
	v_add_f32_e32 v128, v128, v129
	v_fmamk_f32 v128, v128, 0x3c000000, v145
	v_lshlrev_b32_e32 v218, 16, v212
	v_rsq_f32_e32 v166, v128
	v_mul_f32_e32 v128, 0xbfb8aa3b, v218
	v_and_b32_e32 v212, 0xffff0000, v212
	v_exp_f32_e32 v128, v128
	v_mul_f32_e32 v129, 0xbfb8aa3b, v212
	v_lshlrev_b32_e32 v219, 16, v213
	v_exp_f32_e32 v129, v129
	v_mul_f32_e32 v167, 0xbfb8aa3b, v219
	v_exp_f32_e32 v167, v167
	v_add_f32_e32 v128, 1.0, v128
	v_rcp_f32_e32 v220, v128
	v_add_f32_e32 v128, 1.0, v129
	v_rcp_f32_e32 v222, v128
	v_mov_b32_e32 v128, v216
	v_mov_b32_e32 v129, v214
	v_and_b32_e32 v213, 0xffff0000, v213
	v_pk_mul_f32 v[224:225], v[128:129], v[166:167] op_sel_hi:[1,0]
	v_mov_b32_e32 v128, v52
	v_add_f32_e32 v52, 1.0, v167
	v_rcp_f32_e32 v221, v52
	v_mul_f32_e32 v52, 0xbfb8aa3b, v213
	v_exp_f32_e32 v52, v52
	v_mov_b32_e32 v214, v217
	v_mov_b32_e32 v129, v54
	v_pk_mul_f32 v[214:215], v[214:215], v[166:167] op_sel_hi:[1,0]
	v_add_f32_e32 v52, 1.0, v52
	v_rcp_f32_e32 v223, v52
	v_mov_b32_e32 v54, v53
	v_pk_mul_f32 v[52:53], v[54:55], v[214:215]
	v_pk_mul_f32 v[224:225], v[128:129], v[224:225]
	v_pk_mul_f32 v[212:213], v[222:223], v[212:213]
	v_pk_mul_f32 v[218:219], v[220:221], v[218:219]
	v_pk_mul_f32 v[52:53], v[212:213], v[52:53]
	v_pk_mul_f32 v[218:219], v[218:219], v[224:225]
	v_and_b32_sdwa v213, v53, v207 dst_sel:DWORD dst_unused:UNUSED_PAD src0_sel:WORD_1 src1_sel:DWORD
	v_and_b32_sdwa v214, v52, v207 dst_sel:DWORD dst_unused:UNUSED_PAD src0_sel:WORD_1 src1_sel:DWORD
	v_and_b32_sdwa v167, v219, v207 dst_sel:DWORD dst_unused:UNUSED_PAD src0_sel:WORD_1 src1_sel:DWORD
	v_and_b32_sdwa v212, v218, v207 dst_sel:DWORD dst_unused:UNUSED_PAD src0_sel:WORD_1 src1_sel:DWORD
	v_add3_u32 v53, v53, v213, s30
	v_add3_u32 v52, v52, v214, s30
	v_add3_u32 v212, v218, v212, s30
	v_add3_u32 v167, v219, v167, s30
	v_and_b32_e32 v53, 0xffff0000, v53
	v_and_b32_e32 v52, 0xffff0000, v52
	v_or_b32_sdwa v53, v53, v167 dst_sel:DWORD dst_unused:UNUSED_PAD src0_sel:DWORD src1_sel:WORD_1
	v_or_b32_sdwa v52, v52, v212 dst_sel:DWORD dst_unused:UNUSED_PAD src0_sel:DWORD src1_sel:WORD_1
	v_lshlrev_b32_e32 v212, 16, v210
	global_store_dwordx2 v[158:159], v[52:53], off offset:1024
	v_mul_f32_e32 v52, 0xbfb8aa3b, v212
	v_and_b32_e32 v210, 0xffff0000, v210
	v_exp_f32_e32 v52, v52
	v_mul_f32_e32 v53, 0xbfb8aa3b, v210
	v_lshlrev_b32_e32 v213, 16, v211
	v_exp_f32_e32 v53, v53
	v_mul_f32_e32 v167, 0xbfb8aa3b, v213
	v_exp_f32_e32 v167, v167
	v_add_f32_e32 v52, 1.0, v52
	v_rcp_f32_e32 v214, v52
	v_add_f32_e32 v52, 1.0, v53
	v_rcp_f32_e32 v216, v52
	v_mov_b32_e32 v52, v198
	v_mov_b32_e32 v53, v196
	v_and_b32_e32 v211, 0xffff0000, v211
	v_pk_mul_f32 v[218:219], v[52:53], v[166:167] op_sel_hi:[1,0]
	s_waitcnt vmcnt(7)
; __device__ __forceinline__ unsigned pk2(float lo, float hi) { return f2bf(lo) | (f2bf(hi) << 16); }
; __device__ __forceinline__ float silu_f(float g) { return g * __builtin_amdgcn_rcpf(1.0f + __expf(-g)); }
; __device__ __forceinline__ void gla_out_unit(const bf16* PROJ, const bf16* ST, const float* norm_o, bf16* Y, int unit, int lane) {
;     ...
; #pragma unroll
;         for (int mi = 0; mi < 8; ++mi) {
;             const int v = h * 128 + 16 * mi + 4 * fq;
;             const f32x4 no = nov[mi]; const u32x2 g2 = gg1[mi];
;             const f32x4 o = acc[mi][ni];
;             const float y0 = o[0] * rs * no[0] * silu_f(bf_lo(g2.x)), y1 = o[1] * rs * no[1] * silu_f(bf_hi(g2.x));
;             const float y2 = o[2] * rs * no[2] * silu_f(bf_lo(g2.y)), y3 = o[3] * rs * no[3] * silu_f(bf_hi(g2.y));
;             u32x2 w; w.x = pk2(y0, y1); w.y = pk2(y2, y3);
;             *(u32x2*)(Y + tok * D + 512 + v) = w;
;         }
	v_mov_b32_e32 v52, v64
	v_add_f32_e32 v64, 1.0, v167
	v_rcp_f32_e32 v215, v64
	v_mul_f32_e32 v64, 0xbfb8aa3b, v211
	v_exp_f32_e32 v64, v64
	v_mov_b32_e32 v196, v199
	v_mov_b32_e32 v53, v66
	v_pk_mul_f32 v[196:197], v[196:197], v[166:167] op_sel_hi:[1,0]
	v_add_f32_e32 v64, 1.0, v64
	v_rcp_f32_e32 v217, v64
	v_mov_b32_e32 v66, v65
	v_pk_mul_f32 v[64:65], v[66:67], v[196:197]
	v_pk_mul_f32 v[218:219], v[52:53], v[218:219]
	v_pk_mul_f32 v[196:197], v[216:217], v[210:211]
	v_pk_mul_f32 v[212:213], v[214:215], v[212:213]
	v_pk_mul_f32 v[64:65], v[196:197], v[64:65]
	v_pk_mul_f32 v[212:213], v[212:213], v[218:219]
	v_and_b32_sdwa v197, v65, v207 dst_sel:DWORD dst_unused:UNUSED_PAD src0_sel:WORD_1 src1_sel:DWORD
	v_and_b32_sdwa v198, v64, v207 dst_sel:DWORD dst_unused:UNUSED_PAD src0_sel:WORD_1 src1_sel:DWORD
	v_and_b32_sdwa v167, v213, v207 dst_sel:DWORD dst_unused:UNUSED_PAD src0_sel:WORD_1 src1_sel:DWORD
	v_and_b32_sdwa v196, v212, v207 dst_sel:DWORD dst_unused:UNUSED_PAD src0_sel:WORD_1 src1_sel:DWORD
	v_add3_u32 v65, v65, v197, s30
	v_add3_u32 v64, v64, v198, s30
	v_add3_u32 v196, v212, v196, s30
	v_add3_u32 v167, v213, v167, s30
	v_and_b32_e32 v65, 0xffff0000, v65
	v_and_b32_e32 v64, 0xffff0000, v64
	v_or_b32_sdwa v65, v65, v167 dst_sel:DWORD dst_unused:UNUSED_PAD src0_sel:DWORD src1_sel:WORD_1
	v_or_b32_sdwa v64, v64, v196 dst_sel:DWORD dst_unused:UNUSED_PAD src0_sel:DWORD src1_sel:WORD_1
	v_lshlrev_b32_e32 v196, 16, v190
	global_store_dwordx2 v[158:159], v[64:65], off offset:1056
	v_mul_f32_e32 v64, 0xbfb8aa3b, v196
	v_and_b32_e32 v190, 0xffff0000, v190
	v_exp_f32_e32 v64, v64
	v_mul_f32_e32 v65, 0xbfb8aa3b, v190
	v_lshlrev_b32_e32 v197, 16, v191
	v_exp_f32_e32 v65, v65
	v_mul_f32_e32 v167, 0xbfb8aa3b, v197
	v_exp_f32_e32 v167, v167
	v_add_f32_e32 v64, 1.0, v64
	v_rcp_f32_e32 v198, v64
	v_add_f32_e32 v64, 1.0, v65
	v_rcp_f32_e32 v210, v64
	v_mov_b32_e32 v64, v194
	v_mov_b32_e32 v65, v192
	v_and_b32_e32 v191, 0xffff0000, v191
	v_pk_mul_f32 v[212:213], v[64:65], v[166:167] op_sel_hi:[1,0]
	s_waitcnt vmcnt(7)
	v_mov_b32_e32 v64, v56
	v_add_f32_e32 v56, 1.0, v167
	v_rcp_f32_e32 v199, v56
	v_mul_f32_e32 v56, 0xbfb8aa3b, v191
	v_exp_f32_e32 v56, v56
	v_mov_b32_e32 v192, v195
	v_mov_b32_e32 v65, v58
	v_pk_mul_f32 v[192:193], v[192:193], v[166:167] op_sel_hi:[1,0]
	v_add_f32_e32 v56, 1.0, v56
	v_rcp_f32_e32 v211, v56
	v_mov_b32_e32 v58, v57
	v_pk_mul_f32 v[56:57], v[58:59], v[192:193]
	v_pk_mul_f32 v[212:213], v[64:65], v[212:213]
	v_pk_mul_f32 v[190:191], v[210:211], v[190:191]
	v_pk_mul_f32 v[196:197], v[198:199], v[196:197]
	v_pk_mul_f32 v[56:57], v[190:191], v[56:57]
	v_pk_mul_f32 v[196:197], v[196:197], v[212:213]
	v_and_b32_sdwa v191, v57, v207 dst_sel:DWORD dst_unused:UNUSED_PAD src0_sel:WORD_1 src1_sel:DWORD
	v_and_b32_sdwa v192, v56, v207 dst_sel:DWORD dst_unused:UNUSED_PAD src0_sel:WORD_1 src1_sel:DWORD
	v_and_b32_sdwa v167, v197, v207 dst_sel:DWORD dst_unused:UNUSED_PAD src0_sel:WORD_1 src1_sel:DWORD
	v_and_b32_sdwa v190, v196, v207 dst_sel:DWORD dst_unused:UNUSED_PAD src0_sel:WORD_1 src1_sel:DWORD
	v_add3_u32 v57, v57, v191, s30
	v_add3_u32 v56, v56, v192, s30
	v_add3_u32 v190, v196, v190, s30
	v_add3_u32 v167, v197, v167, s30
	v_and_b32_e32 v57, 0xffff0000, v57
	v_and_b32_e32 v56, 0xffff0000, v56
	v_or_b32_sdwa v57, v57, v167 dst_sel:DWORD dst_unused:UNUSED_PAD src0_sel:DWORD src1_sel:WORD_1
	v_or_b32_sdwa v56, v56, v190 dst_sel:DWORD dst_unused:UNUSED_PAD src0_sel:DWORD src1_sel:WORD_1
	v_lshlrev_b32_e32 v190, 16, v184
	global_store_dwordx2 v[158:159], v[56:57], off offset:1088
	v_mul_f32_e32 v56, 0xbfb8aa3b, v190
	v_and_b32_e32 v184, 0xffff0000, v184
	v_exp_f32_e32 v56, v56
	v_mul_f32_e32 v57, 0xbfb8aa3b, v184
	v_lshlrev_b32_e32 v191, 16, v185
	v_exp_f32_e32 v57, v57
	v_mul_f32_e32 v167, 0xbfb8aa3b, v191
	v_exp_f32_e32 v167, v167
	v_add_f32_e32 v56, 1.0, v56
	v_rcp_f32_e32 v192, v56
	v_add_f32_e32 v56, 1.0, v57
	v_rcp_f32_e32 v194, v56
	v_mov_b32_e32 v56, v188
	v_mov_b32_e32 v57, v186
	v_and_b32_e32 v185, 0xffff0000, v185
	v_pk_mul_f32 v[196:197], v[56:57], v[166:167] op_sel_hi:[1,0]
	s_waitcnt vmcnt(7)
	v_mov_b32_e32 v56, v48
	v_add_f32_e32 v48, 1.0, v167
	v_rcp_f32_e32 v193, v48
	v_mul_f32_e32 v48, 0xbfb8aa3b, v185
	v_exp_f32_e32 v48, v48
	v_mov_b32_e32 v186, v189
	v_mov_b32_e32 v57, v50
	v_pk_mul_f32 v[186:187], v[186:187], v[166:167] op_sel_hi:[1,0]
	v_add_f32_e32 v48, 1.0, v48
	v_rcp_f32_e32 v195, v48
	v_mov_b32_e32 v50, v49
	v_pk_mul_f32 v[48:49], v[50:51], v[186:187]
	v_pk_mul_f32 v[196:197], v[56:57], v[196:197]
	v_pk_mul_f32 v[184:185], v[194:195], v[184:185]
	v_pk_mul_f32 v[190:191], v[192:193], v[190:191]
	v_pk_mul_f32 v[48:49], v[184:185], v[48:49]
	v_pk_mul_f32 v[190:191], v[190:191], v[196:197]
	v_and_b32_sdwa v185, v49, v207 dst_sel:DWORD dst_unused:UNUSED_PAD src0_sel:WORD_1 src1_sel:DWORD
	v_and_b32_sdwa v186, v48, v207 dst_sel:DWORD dst_unused:UNUSED_PAD src0_sel:WORD_1 src1_sel:DWORD
	v_and_b32_sdwa v167, v191, v207 dst_sel:DWORD dst_unused:UNUSED_PAD src0_sel:WORD_1 src1_sel:DWORD
	v_and_b32_sdwa v184, v190, v207 dst_sel:DWORD dst_unused:UNUSED_PAD src0_sel:WORD_1 src1_sel:DWORD
	v_add3_u32 v49, v49, v185, s30
	v_add3_u32 v48, v48, v186, s30
	v_add3_u32 v184, v190, v184, s30
	v_add3_u32 v167, v191, v167, s30
	v_and_b32_e32 v49, 0xffff0000, v49
	v_and_b32_e32 v48, 0xffff0000, v48
	v_or_b32_sdwa v49, v49, v167 dst_sel:DWORD dst_unused:UNUSED_PAD src0_sel:DWORD src1_sel:WORD_1
	v_or_b32_sdwa v48, v48, v184 dst_sel:DWORD dst_unused:UNUSED_PAD src0_sel:DWORD src1_sel:WORD_1
	v_lshlrev_b32_e32 v184, 16, v178
	global_store_dwordx2 v[158:159], v[48:49], off offset:1120
	v_mul_f32_e32 v48, 0xbfb8aa3b, v184
	v_and_b32_e32 v178, 0xffff0000, v178
	v_exp_f32_e32 v48, v48
	v_mul_f32_e32 v49, 0xbfb8aa3b, v178
	v_lshlrev_b32_e32 v185, 16, v179
	v_exp_f32_e32 v49, v49
	v_mul_f32_e32 v167, 0xbfb8aa3b, v185
	v_exp_f32_e32 v167, v167
	v_add_f32_e32 v48, 1.0, v48
	v_rcp_f32_e32 v186, v48
	v_add_f32_e32 v48, 1.0, v49
	v_rcp_f32_e32 v188, v48
	v_mov_b32_e32 v48, v182
	v_mov_b32_e32 v49, v180
	v_and_b32_e32 v179, 0xffff0000, v179
	v_pk_mul_f32 v[190:191], v[48:49], v[166:167] op_sel_hi:[1,0]
	s_waitcnt vmcnt(7)
; __device__ __forceinline__ unsigned pk2(float lo, float hi) { return f2bf(lo) | (f2bf(hi) << 16); }
; __device__ __forceinline__ float silu_f(float g) { return g * __builtin_amdgcn_rcpf(1.0f + __expf(-g)); }
; __device__ __forceinline__ void gla_out_unit(const bf16* PROJ, const bf16* ST, const float* norm_o, bf16* Y, int unit, int lane) {
;     ...
; #pragma unroll
;         for (int mi = 0; mi < 8; ++mi) {
;             const int v = h * 128 + 16 * mi + 4 * fq;
;             const f32x4 no = nov[mi]; const u32x2 g2 = gg1[mi];
;             const f32x4 o = acc[mi][ni];
;             const float y0 = o[0] * rs * no[0] * silu_f(bf_lo(g2.x)), y1 = o[1] * rs * no[1] * silu_f(bf_hi(g2.x));
;             const float y2 = o[2] * rs * no[2] * silu_f(bf_lo(g2.y)), y3 = o[3] * rs * no[3] * silu_f(bf_hi(g2.y));
;             u32x2 w; w.x = pk2(y0, y1); w.y = pk2(y2, y3);
;             *(u32x2*)(Y + tok * D + 512 + v) = w;
;         }
	v_mov_b32_e32 v48, v44
	v_add_f32_e32 v44, 1.0, v167
	v_rcp_f32_e32 v187, v44
	v_mul_f32_e32 v44, 0xbfb8aa3b, v179
	v_exp_f32_e32 v44, v44
	v_mov_b32_e32 v180, v183
	v_mov_b32_e32 v49, v46
	v_pk_mul_f32 v[180:181], v[180:181], v[166:167] op_sel_hi:[1,0]
	v_add_f32_e32 v44, 1.0, v44
	v_rcp_f32_e32 v189, v44
	v_mov_b32_e32 v46, v45
	v_pk_mul_f32 v[44:45], v[46:47], v[180:181]
	v_pk_mul_f32 v[190:191], v[48:49], v[190:191]
	v_pk_mul_f32 v[178:179], v[188:189], v[178:179]
	v_pk_mul_f32 v[184:185], v[186:187], v[184:185]
	v_pk_mul_f32 v[44:45], v[178:179], v[44:45]
	v_pk_mul_f32 v[184:185], v[184:185], v[190:191]
	v_and_b32_sdwa v179, v45, v207 dst_sel:DWORD dst_unused:UNUSED_PAD src0_sel:WORD_1 src1_sel:DWORD
	v_and_b32_sdwa v180, v44, v207 dst_sel:DWORD dst_unused:UNUSED_PAD src0_sel:WORD_1 src1_sel:DWORD
	v_and_b32_sdwa v167, v185, v207 dst_sel:DWORD dst_unused:UNUSED_PAD src0_sel:WORD_1 src1_sel:DWORD
	v_and_b32_sdwa v178, v184, v207 dst_sel:DWORD dst_unused:UNUSED_PAD src0_sel:WORD_1 src1_sel:DWORD
	v_add3_u32 v45, v45, v179, s30
	v_add3_u32 v44, v44, v180, s30
	v_add3_u32 v178, v184, v178, s30
	v_add3_u32 v167, v185, v167, s30
	v_and_b32_e32 v45, 0xffff0000, v45
	v_and_b32_e32 v44, 0xffff0000, v44
	v_or_b32_sdwa v45, v45, v167 dst_sel:DWORD dst_unused:UNUSED_PAD src0_sel:DWORD src1_sel:WORD_1
	v_or_b32_sdwa v44, v44, v178 dst_sel:DWORD dst_unused:UNUSED_PAD src0_sel:DWORD src1_sel:WORD_1
	v_lshlrev_b32_e32 v178, 16, v172
	global_store_dwordx2 v[158:159], v[44:45], off offset:1152
	v_mul_f32_e32 v44, 0xbfb8aa3b, v178
	v_and_b32_e32 v172, 0xffff0000, v172
	v_exp_f32_e32 v44, v44
	v_mul_f32_e32 v45, 0xbfb8aa3b, v172
	v_lshlrev_b32_e32 v179, 16, v173
	v_exp_f32_e32 v45, v45
	v_mul_f32_e32 v167, 0xbfb8aa3b, v179
	v_exp_f32_e32 v167, v167
	v_add_f32_e32 v44, 1.0, v44
	v_rcp_f32_e32 v180, v44
	v_add_f32_e32 v44, 1.0, v45
	v_rcp_f32_e32 v182, v44
	v_mov_b32_e32 v44, v176
	v_mov_b32_e32 v45, v174
	v_and_b32_e32 v173, 0xffff0000, v173
	v_pk_mul_f32 v[184:185], v[44:45], v[166:167] op_sel_hi:[1,0]
	s_waitcnt vmcnt(7)
	v_mov_b32_e32 v44, v40
	v_add_f32_e32 v40, 1.0, v167
	v_rcp_f32_e32 v181, v40
	v_mul_f32_e32 v40, 0xbfb8aa3b, v173
	v_exp_f32_e32 v40, v40
	v_mov_b32_e32 v174, v177
	v_mov_b32_e32 v45, v42
	v_pk_mul_f32 v[174:175], v[174:175], v[166:167] op_sel_hi:[1,0]
	v_add_f32_e32 v40, 1.0, v40
	v_rcp_f32_e32 v183, v40
	v_mov_b32_e32 v42, v41
	v_pk_mul_f32 v[40:41], v[42:43], v[174:175]
	v_pk_mul_f32 v[184:185], v[44:45], v[184:185]
	v_pk_mul_f32 v[172:173], v[182:183], v[172:173]
	v_pk_mul_f32 v[178:179], v[180:181], v[178:179]
	v_pk_mul_f32 v[40:41], v[172:173], v[40:41]
	v_pk_mul_f32 v[178:179], v[178:179], v[184:185]
	v_and_b32_sdwa v173, v41, v207 dst_sel:DWORD dst_unused:UNUSED_PAD src0_sel:WORD_1 src1_sel:DWORD
	v_and_b32_sdwa v174, v40, v207 dst_sel:DWORD dst_unused:UNUSED_PAD src0_sel:WORD_1 src1_sel:DWORD
	v_and_b32_sdwa v167, v179, v207 dst_sel:DWORD dst_unused:UNUSED_PAD src0_sel:WORD_1 src1_sel:DWORD
	v_and_b32_sdwa v172, v178, v207 dst_sel:DWORD dst_unused:UNUSED_PAD src0_sel:WORD_1 src1_sel:DWORD
	v_add3_u32 v41, v41, v173, s30
	v_add3_u32 v40, v40, v174, s30
	v_add3_u32 v172, v178, v172, s30
	v_add3_u32 v167, v179, v167, s30
	v_and_b32_e32 v41, 0xffff0000, v41
	v_and_b32_e32 v40, 0xffff0000, v40
	v_or_b32_sdwa v41, v41, v167 dst_sel:DWORD dst_unused:UNUSED_PAD src0_sel:DWORD src1_sel:WORD_1
	v_or_b32_sdwa v40, v40, v172 dst_sel:DWORD dst_unused:UNUSED_PAD src0_sel:DWORD src1_sel:WORD_1
	v_lshlrev_b32_e32 v172, 16, v164
	global_store_dwordx2 v[158:159], v[40:41], off offset:1184
	v_mul_f32_e32 v40, 0xbfb8aa3b, v172
	v_and_b32_e32 v164, 0xffff0000, v164
	v_exp_f32_e32 v40, v40
	v_mul_f32_e32 v41, 0xbfb8aa3b, v164
	v_lshlrev_b32_e32 v173, 16, v165
	v_exp_f32_e32 v41, v41
	v_mul_f32_e32 v167, 0xbfb8aa3b, v173
	v_exp_f32_e32 v167, v167
	v_add_f32_e32 v40, 1.0, v40
	v_rcp_f32_e32 v174, v40
	v_add_f32_e32 v40, 1.0, v41
	v_rcp_f32_e32 v176, v40
	v_mov_b32_e32 v40, v170
	v_mov_b32_e32 v41, v168
	v_and_b32_e32 v165, 0xffff0000, v165
	v_pk_mul_f32 v[178:179], v[40:41], v[166:167] op_sel_hi:[1,0]
	s_waitcnt vmcnt(7)
	v_mov_b32_e32 v40, v36
	v_add_f32_e32 v36, 1.0, v167
	v_rcp_f32_e32 v175, v36
	v_mul_f32_e32 v36, 0xbfb8aa3b, v165
	v_exp_f32_e32 v36, v36
	v_mov_b32_e32 v168, v171
	v_mov_b32_e32 v41, v38
	v_pk_mul_f32 v[168:169], v[168:169], v[166:167] op_sel_hi:[1,0]
	v_add_f32_e32 v36, 1.0, v36
	v_rcp_f32_e32 v177, v36
	v_mov_b32_e32 v38, v37
	v_pk_mul_f32 v[36:37], v[38:39], v[168:169]
	v_pk_mul_f32 v[178:179], v[40:41], v[178:179]
	v_pk_mul_f32 v[164:165], v[176:177], v[164:165]
	v_pk_mul_f32 v[172:173], v[174:175], v[172:173]
	v_pk_mul_f32 v[36:37], v[164:165], v[36:37]
	v_pk_mul_f32 v[172:173], v[172:173], v[178:179]
	v_and_b32_sdwa v167, v37, v207 dst_sel:DWORD dst_unused:UNUSED_PAD src0_sel:WORD_1 src1_sel:DWORD
	v_and_b32_sdwa v168, v36, v207 dst_sel:DWORD dst_unused:UNUSED_PAD src0_sel:WORD_1 src1_sel:DWORD
	v_and_b32_sdwa v164, v173, v207 dst_sel:DWORD dst_unused:UNUSED_PAD src0_sel:WORD_1 src1_sel:DWORD
	v_and_b32_sdwa v165, v172, v207 dst_sel:DWORD dst_unused:UNUSED_PAD src0_sel:WORD_1 src1_sel:DWORD
	v_add3_u32 v37, v37, v167, s30
	v_add3_u32 v36, v36, v168, s30
	v_add3_u32 v165, v172, v165, s30
	v_add3_u32 v164, v173, v164, s30
	v_and_b32_e32 v37, 0xffff0000, v37
	v_and_b32_e32 v36, 0xffff0000, v36
	v_or_b32_sdwa v37, v37, v164 dst_sel:DWORD dst_unused:UNUSED_PAD src0_sel:DWORD src1_sel:WORD_1
	v_or_b32_sdwa v36, v36, v165 dst_sel:DWORD dst_unused:UNUSED_PAD src0_sel:DWORD src1_sel:WORD_1
	v_lshlrev_b32_e32 v164, 16, v160
	global_store_dwordx2 v[158:159], v[36:37], off offset:1216
	v_mul_f32_e32 v36, 0xbfb8aa3b, v164
	v_and_b32_e32 v160, 0xffff0000, v160
	v_exp_f32_e32 v36, v36
	v_mul_f32_e32 v37, 0xbfb8aa3b, v160
	v_exp_f32_e32 v37, v37
	v_lshlrev_b32_e32 v165, 16, v161
	v_add_f32_e32 v36, 1.0, v36
	v_rcp_f32_e32 v168, v36
	v_add_f32_e32 v36, 1.0, v37
	v_mov_b32_e32 v37, v130
	v_mul_f32_e32 v130, 0xbfb8aa3b, v165
	v_exp_f32_e32 v130, v130
	v_rcp_f32_e32 v170, v36
	v_mov_b32_e32 v36, v162
	v_and_b32_e32 v161, 0xffff0000, v161
	v_pk_mul_f32 v[172:173], v[36:37], v[166:167] op_sel_hi:[1,0]
	s_waitcnt vmcnt(7)
; __device__ __forceinline__ unsigned pk2(float lo, float hi) { return f2bf(lo) | (f2bf(hi) << 16); }
; __device__ __forceinline__ float silu_f(float g) { return g * __builtin_amdgcn_rcpf(1.0f + __expf(-g)); }
; __device__ __forceinline__ void gla_out_unit(const bf16* PROJ, const bf16* ST, const float* norm_o, bf16* Y, int unit, int lane) {
;     ...
;     for (int ni = 0; ni < 4; ++ni) {
;         u32x2 gg1[8];
; #pragma unroll
;         for (int mi = 0; mi < 8; ++mi) gg1[mi] = *(const u32x2*)(PROJ + (size_t)(tok0 + 16 * ni + fr) * NPROJ + 2048 + h * 128 + 16 * mi + 4 * fq);
;         asm volatile("" : "+v"(gg1[0]), "+v"(gg1[1]), "+v"(gg1[2]), "+v"(gg1[3]), "+v"(gg1[4]), "+v"(gg1[5]), "+v"(gg1[6]), "+v"(gg1[7]));
;         float ss = 0.f;
; #pragma unroll
;         for (int mi = 0; mi < 8; ++mi) { acc[mi][ni] = acc[mi][ni] * 0.125f; const f32x4 o = acc[mi][ni]; ss += (o[0] * o[0] + o[1] * o[1]) + (o[2] * o[2] + o[3] * o[3]); }
;         ss += __shfl_xor(ss, 16); ss += __shfl_xor(ss, 32);
;         const float rs = __builtin_amdgcn_rsqf(ss * (1.f / 128.f) + EPS);
;         const size_t tok = (size_t)(tok0 + 16 * ni + fr);
; #pragma unroll
;         for (int mi = 0; mi < 8; ++mi) {
;             const int v = h * 128 + 16 * mi + 4 * fq;
;             const f32x4 no = nov[mi]; const u32x2 g2 = gg1[mi];
;             const f32x4 o = acc[mi][ni];
;             const float y0 = o[0] * rs * no[0] * silu_f(bf_lo(g2.x)), y1 = o[1] * rs * no[1] * silu_f(bf_hi(g2.x));
;             const float y2 = o[2] * rs * no[2] * silu_f(bf_lo(g2.y)), y3 = o[3] * rs * no[3] * silu_f(bf_hi(g2.y));
;             u32x2 w; w.x = pk2(y0, y1); w.y = pk2(y2, y3);
;             *(u32x2*)(Y + tok * D + 512 + v) = w;
;         }
	v_mov_b32_e32 v36, v32
	v_add_f32_e32 v32, 1.0, v130
	v_rcp_f32_e32 v169, v32
	v_mul_f32_e32 v32, 0xbfb8aa3b, v161
	v_exp_f32_e32 v32, v32
	v_mov_b32_e32 v130, v163
	v_mov_b32_e32 v37, v34
	v_pk_mul_f32 v[130:131], v[130:131], v[166:167] op_sel_hi:[1,0]
	v_add_f32_e32 v32, 1.0, v32
	v_rcp_f32_e32 v171, v32
	v_mov_b32_e32 v34, v33
	v_pk_mul_f32 v[32:33], v[34:35], v[130:131]
	v_pk_mul_f32 v[172:173], v[36:37], v[172:173]
	v_pk_mul_f32 v[130:131], v[170:171], v[160:161]
	v_pk_mul_f32 v[164:165], v[168:169], v[164:165]
	v_pk_mul_f32 v[32:33], v[130:131], v[32:33]
	v_pk_mul_f32 v[164:165], v[164:165], v[172:173]
	v_and_b32_sdwa v160, v33, v207 dst_sel:DWORD dst_unused:UNUSED_PAD src0_sel:WORD_1 src1_sel:DWORD
	v_and_b32_sdwa v161, v32, v207 dst_sel:DWORD dst_unused:UNUSED_PAD src0_sel:WORD_1 src1_sel:DWORD
	v_and_b32_sdwa v130, v165, v207 dst_sel:DWORD dst_unused:UNUSED_PAD src0_sel:WORD_1 src1_sel:DWORD
	v_and_b32_sdwa v131, v164, v207 dst_sel:DWORD dst_unused:UNUSED_PAD src0_sel:WORD_1 src1_sel:DWORD
	v_add3_u32 v33, v33, v160, s30
	v_add3_u32 v32, v32, v161, s30
	v_add3_u32 v131, v164, v131, s30
	v_add3_u32 v130, v165, v130, s30
	v_and_b32_e32 v33, 0xffff0000, v33
	v_and_b32_e32 v32, 0xffff0000, v32
	v_or_b32_sdwa v33, v33, v130 dst_sel:DWORD dst_unused:UNUSED_PAD src0_sel:DWORD src1_sel:WORD_1
	v_or_b32_sdwa v32, v32, v131 dst_sel:DWORD dst_unused:UNUSED_PAD src0_sel:DWORD src1_sel:WORD_1
	global_store_dwordx2 v[158:159], v[32:33], off offset:1248
	v_lshl_add_u64 v[32:33], v[156:157], 0, s[6:7]
	v_lshl_add_u64 v[32:33], v[32:33], 0, v[132:133]
	v_lshl_add_u64 v[164:165], v[32:33], 0, s[64:65]
	v_add_co_u32_e32 v32, vcc, s29, v32
	v_pk_mul_f32 v[174:175], v[124:125], s[66:67] op_sel_hi:[1,0]
	s_nop 0
	v_addc_co_u32_e32 v33, vcc, 0, v33, vcc
	global_load_dwordx2 v[168:169], v[164:165], off offset:32 nt
	global_load_dwordx2 v[162:163], v[164:165], off offset:64 nt
	global_load_dwordx2 v[160:161], v[164:165], off offset:96 nt
	global_load_dwordx2 v[158:159], v[164:165], off offset:128 nt
	global_load_dwordx2 v[170:171], v[32:33], off nt
	global_load_dwordx2 v[156:157], v[164:165], off offset:160 nt
	global_load_dwordx2 v[130:131], v[164:165], off offset:192 nt
	s_nop 0
	global_load_dwordx2 v[32:33], v[164:165], off offset:224 nt
	v_pk_mul_f32 v[178:179], v[120:121], s[66:67] op_sel_hi:[1,0]
	v_pk_mul_f32 v[172:173], v[126:127], s[66:67] op_sel_hi:[1,0]
	v_pk_mul_f32 v[176:177], v[122:123], s[66:67] op_sel_hi:[1,0]
	v_mov_b32_e32 v122, v175
	v_mov_b32_e32 v123, v179
	v_mov_b32_e32 v120, v174
	v_mov_b32_e32 v121, v178
	v_pk_mul_f32 v[122:123], v[122:123], v[122:123]
	v_mov_b32_e32 v124, v173
	v_mov_b32_e32 v125, v177
	v_pk_fma_f32 v[120:121], v[120:121], v[120:121], v[122:123]
	v_mov_b32_e32 v122, v172
	v_mov_b32_e32 v123, v176
	v_pk_mul_f32 v[124:125], v[124:125], v[124:125]
	v_pk_mul_f32 v[164:165], v[114:115], s[66:67] op_sel_hi:[1,0]
	v_pk_mul_f32 v[166:167], v[112:113], s[66:67] op_sel_hi:[1,0]
	v_pk_fma_f32 v[122:123], v[122:123], v[122:123], v[124:125]
	v_pk_mul_f32 v[112:113], v[164:165], v[164:165]
	v_pk_mul_f32 v[114:115], v[166:167], v[166:167]
	v_pk_add_f32 v[180:181], v[120:121], v[122:123]
	v_pk_mov_b32 v[120:121], v[114:115], v[112:113] op_sel:[1,0]
	v_mov_b32_e32 v115, v113
	v_pk_mul_f32 v[122:123], v[100:101], s[66:67] op_sel_hi:[1,0]
	v_pk_add_f32 v[112:113], v[120:121], v[114:115]
	v_pk_mul_f32 v[120:121], v[102:103], s[66:67] op_sel_hi:[1,0]
	v_mul_f32_e32 v102, v122, v122
	v_pk_add_f32 v[100:101], v[180:181], v[180:181] op_sel:[0,1] op_sel_hi:[1,0]
	v_pk_mul_f32 v[126:127], v[104:105], s[66:67] op_sel_hi:[1,0]
	v_mul_f32_e32 v104, v123, v123
	v_mov_b32_e32 v101, v102
	v_pk_add_f32 v[102:103], v[112:113], v[112:113] op_sel:[0,1] op_sel_hi:[1,0]
	v_pk_mul_f32 v[124:125], v[106:107], s[66:67] op_sel_hi:[1,0]
	v_mov_b32_e32 v103, v104
	v_pk_add_f32 v[100:101], v[100:101], v[102:103]
	v_mul_f32_e32 v102, v127, v127
	v_mul_f32_e32 v105, v120, v120
	v_pk_fma_f32 v[102:103], v[126:127], v[126:127], v[102:103] op_sel_hi:[1,1,0]
	v_mul_f32_e32 v104, v125, v125
	v_mul_f32_e32 v106, v121, v121
	v_mov_b32_e32 v103, v105
	v_pk_fma_f32 v[104:105], v[124:125], v[124:125], v[104:105] op_sel_hi:[1,1,0]
	v_pk_mul_f32 v[112:113], v[98:99], s[66:67] op_sel_hi:[1,0]
	v_mov_b32_e32 v105, v106
	v_pk_mul_f32 v[114:115], v[96:97], s[66:67] op_sel_hi:[1,0]
	v_pk_add_f32 v[102:103], v[102:103], v[104:105]
	v_pk_mul_f32 v[96:97], v[112:113], v[112:113]
	v_pk_mul_f32 v[98:99], v[114:115], v[114:115]
	v_pk_add_f32 v[100:101], v[100:101], v[102:103]
	v_pk_mov_b32 v[102:103], v[98:99], v[96:97] op_sel:[1,0]
	v_mov_b32_e32 v99, v97
	v_pk_add_f32 v[106:107], v[102:103], v[98:99]
	v_pk_mul_f32 v[98:99], v[116:117], s[66:67] op_sel_hi:[1,0]
	v_pk_mul_f32 v[104:105], v[108:109], s[66:67] op_sel_hi:[1,0]
	v_mul_f32_e32 v108, v98, v98
	v_mul_f32_e32 v109, v99, v99
	v_pk_add_f32 v[100:101], v[100:101], v[100:101] op_sel:[0,1] op_sel_hi:[1,0]
	v_pk_add_f32 v[106:107], v[106:107], v[106:107] op_sel:[0,1] op_sel_hi:[1,0]
	v_pk_mul_f32 v[102:103], v[110:111], s[66:67] op_sel_hi:[1,0]
	v_mov_b32_e32 v101, v108
	v_mov_b32_e32 v107, v109
	v_pk_mul_f32 v[96:97], v[118:119], s[66:67] op_sel_hi:[1,0]
	v_pk_add_f32 v[100:101], v[100:101], v[106:107]
	v_mul_f32_e32 v106, v105, v105
	v_mul_f32_e32 v108, v103, v103
	v_mul_f32_e32 v110, v96, v96
	v_mul_f32_e32 v111, v97, v97
	v_pk_fma_f32 v[106:107], v[104:105], v[104:105], v[106:107] op_sel_hi:[1,1,0]
	v_pk_fma_f32 v[108:109], v[102:103], v[102:103], v[108:109] op_sel_hi:[1,1,0]
	v_mov_b32_e32 v107, v110
	v_mov_b32_e32 v109, v111
	v_pk_add_f32 v[106:107], v[106:107], v[108:109]
	s_waitcnt vmcnt(0)
; __device__ __forceinline__ unsigned pk2(float lo, float hi) { return f2bf(lo) | (f2bf(hi) << 16); }
; __device__ __forceinline__ float silu_f(float g) { return g * __builtin_amdgcn_rcpf(1.0f + __expf(-g)); }
; __device__ __forceinline__ void gla_out_unit(const bf16* PROJ, const bf16* ST, const float* norm_o, bf16* Y, int unit, int lane) {
;     ...
;     for (int ni = 0; ni < 4; ++ni) {
;         u32x2 gg1[8];
; #pragma unroll
;         for (int mi = 0; mi < 8; ++mi) gg1[mi] = *(const u32x2*)(PROJ + (size_t)(tok0 + 16 * ni + fr) * NPROJ + 2048 + h * 128 + 16 * mi + 4 * fq);
;         asm volatile("" : "+v"(gg1[0]), "+v"(gg1[1]), "+v"(gg1[2]), "+v"(gg1[3]), "+v"(gg1[4]), "+v"(gg1[5]), "+v"(gg1[6]), "+v"(gg1[7]));
;         float ss = 0.f;
; #pragma unroll
;         for (int mi = 0; mi < 8; ++mi) { acc[mi][ni] = acc[mi][ni] * 0.125f; const f32x4 o = acc[mi][ni]; ss += (o[0] * o[0] + o[1] * o[1]) + (o[2] * o[2] + o[3] * o[3]); }
;         ss += __shfl_xor(ss, 16); ss += __shfl_xor(ss, 32);
;         const float rs = __builtin_amdgcn_rsqf(ss * (1.f / 128.f) + EPS);
;         const size_t tok = (size_t)(tok0 + 16 * ni + fr);
; #pragma unroll
;         for (int mi = 0; mi < 8; ++mi) {
;             const int v = h * 128 + 16 * mi + 4 * fq;
;             const f32x4 no = nov[mi]; const u32x2 g2 = gg1[mi];
;             const f32x4 o = acc[mi][ni];
;             const float y0 = o[0] * rs * no[0] * silu_f(bf_lo(g2.x)), y1 = o[1] * rs * no[1] * silu_f(bf_hi(g2.x));
;             const float y2 = o[2] * rs * no[2] * silu_f(bf_lo(g2.y)), y3 = o[3] * rs * no[3] * silu_f(bf_hi(g2.y));
;             u32x2 w; w.x = pk2(y0, y1); w.y = pk2(y2, y3);
;             *(u32x2*)(Y + tok * D + 512 + v) = w;
;         }
	v_pk_add_f32 v[100:101], v[100:101], v[106:107]
	v_lshlrev_b32_e32 v108, 16, v170
	v_add_f32_e32 v100, v100, v101
	ds_bpermute_b32 v101, v208, v100
	v_and_b32_e32 v110, 0xffff0000, v170
	v_mul_f32_e32 v111, 0xbfb8aa3b, v110
	v_exp_f32_e32 v117, v111
	v_lshlrev_b32_e32 v109, 16, v171
	s_waitcnt lgkmcnt(0)
	v_add_f32_e32 v100, v100, v101
	ds_bpermute_b32 v101, v209, v100
	v_lshlrev_b64 v[106:107], 11, v[154:155]
	v_mov_b32_e32 v154, v174
	v_mov_b32_e32 v155, v172
	v_and_b32_e32 v111, 0xffff0000, v171
	s_waitcnt lgkmcnt(0)
	v_add_f32_e32 v100, v100, v101
	v_mul_f32_e32 v101, 0xbfb8aa3b, v108
	v_exp_f32_e32 v101, v101
	v_fmamk_f32 v100, v100, 0x3c000000, v145
	v_rsq_f32_e32 v100, v100
	v_mov_b32_e32 v172, v175
	v_add_f32_e32 v101, 1.0, v101
	v_rcp_f32_e32 v116, v101
	v_add_f32_e32 v101, 1.0, v117
	v_rcp_f32_e32 v118, v101
	v_mul_f32_e32 v101, 0xbfb8aa3b, v109
	v_exp_f32_e32 v101, v101
	v_lshl_add_u64 v[106:107], v[138:139], 0, v[106:107]
	v_pk_mul_f32 v[154:155], v[154:155], v[100:101] op_sel_hi:[1,0]
	v_add_f32_e32 v101, 1.0, v101
	v_rcp_f32_e32 v117, v101
	v_mul_f32_e32 v101, 0xbfb8aa3b, v111
	v_exp_f32_e32 v101, v101
	v_pk_mul_f32 v[154:155], v[128:129], v[154:155]
	v_pk_mul_f32 v[108:109], v[116:117], v[108:109]
	v_add_f32_e32 v101, 1.0, v101
	v_rcp_f32_e32 v119, v101
	v_pk_mul_f32 v[116:117], v[172:173], v[100:101] op_sel_hi:[1,0]
	v_pk_mul_f32 v[108:109], v[154:155], v[108:109]
	v_pk_mul_f32 v[116:117], v[54:55], v[116:117]
	v_pk_mul_f32 v[110:111], v[118:119], v[110:111]
	v_and_b32_sdwa v101, v109, v207 dst_sel:DWORD dst_unused:UNUSED_PAD src0_sel:WORD_1 src1_sel:DWORD
	v_pk_mul_f32 v[110:111], v[116:117], v[110:111]
	v_and_b32_sdwa v116, v108, v207 dst_sel:DWORD dst_unused:UNUSED_PAD src0_sel:WORD_1 src1_sel:DWORD
	v_add3_u32 v108, v108, v116, s30
	v_add3_u32 v101, v109, v101, s30
	v_and_b32_sdwa v109, v111, v207 dst_sel:DWORD dst_unused:UNUSED_PAD src0_sel:WORD_1 src1_sel:DWORD
	v_and_b32_sdwa v116, v110, v207 dst_sel:DWORD dst_unused:UNUSED_PAD src0_sel:WORD_1 src1_sel:DWORD
	v_add3_u32 v109, v111, v109, s30
	v_add3_u32 v110, v110, v116, s30
	v_and_b32_e32 v109, 0xffff0000, v109
	v_and_b32_e32 v110, 0xffff0000, v110
	v_or_b32_sdwa v109, v109, v101 dst_sel:DWORD dst_unused:UNUSED_PAD src0_sel:DWORD src1_sel:WORD_1
	v_or_b32_sdwa v108, v110, v108 dst_sel:DWORD dst_unused:UNUSED_PAD src0_sel:DWORD src1_sel:WORD_1
	global_store_dwordx2 v[106:107], v[108:109], off offset:1024
	v_lshlrev_b32_e32 v108, 16, v168
	v_mul_f32_e32 v101, 0xbfb8aa3b, v108
	v_and_b32_e32 v110, 0xffff0000, v168
	v_exp_f32_e32 v101, v101
	v_mul_f32_e32 v111, 0xbfb8aa3b, v110
	v_exp_f32_e32 v117, v111
	v_lshlrev_b32_e32 v109, 16, v169
	v_add_f32_e32 v101, 1.0, v101
	v_rcp_f32_e32 v116, v101
	v_add_f32_e32 v101, 1.0, v117
	v_rcp_f32_e32 v118, v101
	v_mul_f32_e32 v101, 0xbfb8aa3b, v109
	v_exp_f32_e32 v101, v101
	v_mov_b32_e32 v154, v178
	v_mov_b32_e32 v155, v176
	v_and_b32_e32 v111, 0xffff0000, v169
	v_pk_mul_f32 v[154:155], v[154:155], v[100:101] op_sel_hi:[1,0]
	v_add_f32_e32 v101, 1.0, v101
	v_rcp_f32_e32 v117, v101
	v_mul_f32_e32 v101, 0xbfb8aa3b, v111
	v_exp_f32_e32 v101, v101
	v_mov_b32_e32 v176, v179
	v_pk_mul_f32 v[154:155], v[52:53], v[154:155]
	v_pk_mul_f32 v[108:109], v[116:117], v[108:109]
	v_add_f32_e32 v101, 1.0, v101
	v_rcp_f32_e32 v119, v101
	v_pk_mul_f32 v[116:117], v[176:177], v[100:101] op_sel_hi:[1,0]
	v_pk_mul_f32 v[108:109], v[154:155], v[108:109]
	v_pk_mul_f32 v[116:117], v[66:67], v[116:117]
	v_pk_mul_f32 v[110:111], v[118:119], v[110:111]
	v_and_b32_sdwa v101, v109, v207 dst_sel:DWORD dst_unused:UNUSED_PAD src0_sel:WORD_1 src1_sel:DWORD
	v_pk_mul_f32 v[110:111], v[116:117], v[110:111]
	v_and_b32_sdwa v116, v108, v207 dst_sel:DWORD dst_unused:UNUSED_PAD src0_sel:WORD_1 src1_sel:DWORD
	v_add3_u32 v108, v108, v116, s30
	v_add3_u32 v101, v109, v101, s30
	v_and_b32_sdwa v109, v111, v207 dst_sel:DWORD dst_unused:UNUSED_PAD src0_sel:WORD_1 src1_sel:DWORD
	v_and_b32_sdwa v116, v110, v207 dst_sel:DWORD dst_unused:UNUSED_PAD src0_sel:WORD_1 src1_sel:DWORD
	v_add3_u32 v109, v111, v109, s30
	v_add3_u32 v110, v110, v116, s30
	v_and_b32_e32 v109, 0xffff0000, v109
	v_and_b32_e32 v110, 0xffff0000, v110
	v_or_b32_sdwa v109, v109, v101 dst_sel:DWORD dst_unused:UNUSED_PAD src0_sel:DWORD src1_sel:WORD_1
	v_or_b32_sdwa v108, v110, v108 dst_sel:DWORD dst_unused:UNUSED_PAD src0_sel:DWORD src1_sel:WORD_1
	global_store_dwordx2 v[106:107], v[108:109], off offset:1056
	v_lshlrev_b32_e32 v108, 16, v162
	v_mul_f32_e32 v101, 0xbfb8aa3b, v108
	v_and_b32_e32 v110, 0xffff0000, v162
	v_exp_f32_e32 v101, v101
	v_mul_f32_e32 v111, 0xbfb8aa3b, v110
	v_exp_f32_e32 v117, v111
	v_lshlrev_b32_e32 v109, 16, v163
	v_add_f32_e32 v101, 1.0, v101
	v_rcp_f32_e32 v116, v101
	v_add_f32_e32 v101, 1.0, v117
	v_rcp_f32_e32 v118, v101
	v_mul_f32_e32 v101, 0xbfb8aa3b, v109
	v_exp_f32_e32 v101, v101
	v_mov_b32_e32 v154, v166
	v_mov_b32_e32 v155, v164
	v_and_b32_e32 v111, 0xffff0000, v163
	v_pk_mul_f32 v[154:155], v[154:155], v[100:101] op_sel_hi:[1,0]
	v_add_f32_e32 v101, 1.0, v101
	v_rcp_f32_e32 v117, v101
	v_mul_f32_e32 v101, 0xbfb8aa3b, v111
	v_exp_f32_e32 v101, v101
	v_mov_b32_e32 v164, v167
	v_pk_mul_f32 v[154:155], v[64:65], v[154:155]
	v_pk_mul_f32 v[108:109], v[116:117], v[108:109]
	v_add_f32_e32 v101, 1.0, v101
	v_rcp_f32_e32 v119, v101
	v_pk_mul_f32 v[116:117], v[164:165], v[100:101] op_sel_hi:[1,0]
	v_pk_mul_f32 v[108:109], v[154:155], v[108:109]
	v_pk_mul_f32 v[116:117], v[58:59], v[116:117]
	v_pk_mul_f32 v[110:111], v[118:119], v[110:111]
	v_and_b32_sdwa v101, v109, v207 dst_sel:DWORD dst_unused:UNUSED_PAD src0_sel:WORD_1 src1_sel:DWORD
	v_pk_mul_f32 v[110:111], v[116:117], v[110:111]
; __device__ __forceinline__ unsigned pk2(float lo, float hi) { return f2bf(lo) | (f2bf(hi) << 16); }
; __device__ __forceinline__ float silu_f(float g) { return g * __builtin_amdgcn_rcpf(1.0f + __expf(-g)); }
; __device__ __forceinline__ void gla_out_unit(const bf16* PROJ, const bf16* ST, const float* norm_o, bf16* Y, int unit, int lane) {
;     ...
; #pragma unroll
;         for (int mi = 0; mi < 8; ++mi) {
;             const int v = h * 128 + 16 * mi + 4 * fq;
;             const f32x4 no = nov[mi]; const u32x2 g2 = gg1[mi];
;             const f32x4 o = acc[mi][ni];
;             const float y0 = o[0] * rs * no[0] * silu_f(bf_lo(g2.x)), y1 = o[1] * rs * no[1] * silu_f(bf_hi(g2.x));
;             const float y2 = o[2] * rs * no[2] * silu_f(bf_lo(g2.y)), y3 = o[3] * rs * no[3] * silu_f(bf_hi(g2.y));
;             u32x2 w; w.x = pk2(y0, y1); w.y = pk2(y2, y3);
;             *(u32x2*)(Y + tok * D + 512 + v) = w;
;         }
	v_and_b32_sdwa v116, v108, v207 dst_sel:DWORD dst_unused:UNUSED_PAD src0_sel:WORD_1 src1_sel:DWORD
	v_add3_u32 v108, v108, v116, s30
	v_add3_u32 v101, v109, v101, s30
	v_and_b32_sdwa v109, v111, v207 dst_sel:DWORD dst_unused:UNUSED_PAD src0_sel:WORD_1 src1_sel:DWORD
	v_and_b32_sdwa v116, v110, v207 dst_sel:DWORD dst_unused:UNUSED_PAD src0_sel:WORD_1 src1_sel:DWORD
	v_add3_u32 v109, v111, v109, s30
	v_add3_u32 v110, v110, v116, s30
	v_and_b32_e32 v109, 0xffff0000, v109
	v_and_b32_e32 v110, 0xffff0000, v110
	v_or_b32_sdwa v109, v109, v101 dst_sel:DWORD dst_unused:UNUSED_PAD src0_sel:DWORD src1_sel:WORD_1
	v_or_b32_sdwa v108, v110, v108 dst_sel:DWORD dst_unused:UNUSED_PAD src0_sel:DWORD src1_sel:WORD_1
	global_store_dwordx2 v[106:107], v[108:109], off offset:1088
	v_lshlrev_b32_e32 v108, 16, v160
	v_mul_f32_e32 v101, 0xbfb8aa3b, v108
	v_and_b32_e32 v110, 0xffff0000, v160
	v_exp_f32_e32 v101, v101
	v_mul_f32_e32 v111, 0xbfb8aa3b, v110
	v_exp_f32_e32 v117, v111
	v_lshlrev_b32_e32 v109, 16, v161
	v_add_f32_e32 v101, 1.0, v101
	v_rcp_f32_e32 v116, v101
	v_add_f32_e32 v101, 1.0, v117
	v_rcp_f32_e32 v118, v101
	v_mul_f32_e32 v101, 0xbfb8aa3b, v109
	v_exp_f32_e32 v101, v101
	v_mov_b32_e32 v154, v126
	v_mov_b32_e32 v155, v124
	v_and_b32_e32 v111, 0xffff0000, v161
	v_pk_mul_f32 v[154:155], v[154:155], v[100:101] op_sel_hi:[1,0]
	v_add_f32_e32 v101, 1.0, v101
	v_rcp_f32_e32 v117, v101
	v_mul_f32_e32 v101, 0xbfb8aa3b, v111
	v_exp_f32_e32 v101, v101
	v_mov_b32_e32 v124, v127
	v_pk_mul_f32 v[154:155], v[56:57], v[154:155]
	v_pk_mul_f32 v[108:109], v[116:117], v[108:109]
	v_add_f32_e32 v101, 1.0, v101
	v_rcp_f32_e32 v119, v101
	v_pk_mul_f32 v[116:117], v[124:125], v[100:101] op_sel_hi:[1,0]
	v_pk_mul_f32 v[108:109], v[154:155], v[108:109]
	v_pk_mul_f32 v[116:117], v[50:51], v[116:117]
	v_pk_mul_f32 v[110:111], v[118:119], v[110:111]
	v_and_b32_sdwa v101, v109, v207 dst_sel:DWORD dst_unused:UNUSED_PAD src0_sel:WORD_1 src1_sel:DWORD
	v_pk_mul_f32 v[110:111], v[116:117], v[110:111]
	v_and_b32_sdwa v116, v108, v207 dst_sel:DWORD dst_unused:UNUSED_PAD src0_sel:WORD_1 src1_sel:DWORD
	v_add3_u32 v108, v108, v116, s30
	v_add3_u32 v101, v109, v101, s30
	v_and_b32_sdwa v109, v111, v207 dst_sel:DWORD dst_unused:UNUSED_PAD src0_sel:WORD_1 src1_sel:DWORD
	v_and_b32_sdwa v116, v110, v207 dst_sel:DWORD dst_unused:UNUSED_PAD src0_sel:WORD_1 src1_sel:DWORD
	v_add3_u32 v109, v111, v109, s30
	v_add3_u32 v110, v110, v116, s30
	v_and_b32_e32 v109, 0xffff0000, v109
	v_and_b32_e32 v110, 0xffff0000, v110
	v_or_b32_sdwa v109, v109, v101 dst_sel:DWORD dst_unused:UNUSED_PAD src0_sel:DWORD src1_sel:WORD_1
	v_or_b32_sdwa v108, v110, v108 dst_sel:DWORD dst_unused:UNUSED_PAD src0_sel:DWORD src1_sel:WORD_1
	global_store_dwordx2 v[106:107], v[108:109], off offset:1120
	v_lshlrev_b32_e32 v108, 16, v158
	v_mul_f32_e32 v101, 0xbfb8aa3b, v108
	v_and_b32_e32 v110, 0xffff0000, v158
	v_exp_f32_e32 v101, v101
	v_mul_f32_e32 v111, 0xbfb8aa3b, v110
	v_exp_f32_e32 v117, v111
	v_lshlrev_b32_e32 v109, 16, v159
	v_add_f32_e32 v101, 1.0, v101
	v_rcp_f32_e32 v116, v101
	v_add_f32_e32 v101, 1.0, v117
	v_rcp_f32_e32 v118, v101
	v_mul_f32_e32 v101, 0xbfb8aa3b, v109
	v_exp_f32_e32 v101, v101
	v_mov_b32_e32 v124, v122
	v_mov_b32_e32 v125, v120
	v_and_b32_e32 v111, 0xffff0000, v159
	v_pk_mul_f32 v[124:125], v[124:125], v[100:101] op_sel_hi:[1,0]
	v_add_f32_e32 v101, 1.0, v101
	v_rcp_f32_e32 v117, v101
	v_mul_f32_e32 v101, 0xbfb8aa3b, v111
	v_exp_f32_e32 v101, v101
	v_mov_b32_e32 v120, v123
	v_pk_mul_f32 v[124:125], v[48:49], v[124:125]
	v_pk_mul_f32 v[108:109], v[116:117], v[108:109]
	v_add_f32_e32 v101, 1.0, v101
	v_rcp_f32_e32 v119, v101
	v_pk_mul_f32 v[116:117], v[120:121], v[100:101] op_sel_hi:[1,0]
	v_pk_mul_f32 v[108:109], v[124:125], v[108:109]
	v_pk_mul_f32 v[116:117], v[46:47], v[116:117]
	v_pk_mul_f32 v[110:111], v[118:119], v[110:111]
	v_and_b32_sdwa v101, v109, v207 dst_sel:DWORD dst_unused:UNUSED_PAD src0_sel:WORD_1 src1_sel:DWORD
	v_pk_mul_f32 v[110:111], v[116:117], v[110:111]
	v_and_b32_sdwa v116, v108, v207 dst_sel:DWORD dst_unused:UNUSED_PAD src0_sel:WORD_1 src1_sel:DWORD
	v_add3_u32 v108, v108, v116, s30
	v_add3_u32 v101, v109, v101, s30
	v_and_b32_sdwa v109, v111, v207 dst_sel:DWORD dst_unused:UNUSED_PAD src0_sel:WORD_1 src1_sel:DWORD
	v_and_b32_sdwa v116, v110, v207 dst_sel:DWORD dst_unused:UNUSED_PAD src0_sel:WORD_1 src1_sel:DWORD
	v_add3_u32 v109, v111, v109, s30
	v_add3_u32 v110, v110, v116, s30
	v_and_b32_e32 v109, 0xffff0000, v109
	v_and_b32_e32 v110, 0xffff0000, v110
	v_or_b32_sdwa v109, v109, v101 dst_sel:DWORD dst_unused:UNUSED_PAD src0_sel:DWORD src1_sel:WORD_1
	v_or_b32_sdwa v108, v110, v108 dst_sel:DWORD dst_unused:UNUSED_PAD src0_sel:DWORD src1_sel:WORD_1
	global_store_dwordx2 v[106:107], v[108:109], off offset:1152
	v_lshlrev_b32_e32 v108, 16, v156
	v_mul_f32_e32 v101, 0xbfb8aa3b, v108
	v_and_b32_e32 v110, 0xffff0000, v156
	v_exp_f32_e32 v101, v101
	v_mul_f32_e32 v111, 0xbfb8aa3b, v110
	v_exp_f32_e32 v117, v111
	v_lshlrev_b32_e32 v109, 16, v157
	v_add_f32_e32 v101, 1.0, v101
	v_rcp_f32_e32 v116, v101
	v_add_f32_e32 v101, 1.0, v117
	v_rcp_f32_e32 v118, v101
	v_mul_f32_e32 v101, 0xbfb8aa3b, v109
	v_exp_f32_e32 v101, v101
	v_mov_b32_e32 v120, v114
	v_mov_b32_e32 v121, v112
	v_and_b32_e32 v111, 0xffff0000, v157
	v_pk_mul_f32 v[120:121], v[120:121], v[100:101] op_sel_hi:[1,0]
	v_add_f32_e32 v101, 1.0, v101
	v_rcp_f32_e32 v117, v101
	v_mul_f32_e32 v101, 0xbfb8aa3b, v111
	v_exp_f32_e32 v101, v101
	v_mov_b32_e32 v112, v115
	v_pk_mul_f32 v[120:121], v[44:45], v[120:121]
	v_pk_mul_f32 v[108:109], v[116:117], v[108:109]
	v_add_f32_e32 v101, 1.0, v101
	v_rcp_f32_e32 v119, v101
; __device__ __forceinline__ unsigned pk2(float lo, float hi) { return f2bf(lo) | (f2bf(hi) << 16); }
; __device__ __forceinline__ float silu_f(float g) { return g * __builtin_amdgcn_rcpf(1.0f + __expf(-g)); }
; __device__ __forceinline__ void gla_out_unit(const bf16* PROJ, const bf16* ST, const float* norm_o, bf16* Y, int unit, int lane) {
;     ...
;     for (int ni = 0; ni < 4; ++ni) {
;         u32x2 gg1[8];
; #pragma unroll
;         for (int mi = 0; mi < 8; ++mi) gg1[mi] = *(const u32x2*)(PROJ + (size_t)(tok0 + 16 * ni + fr) * NPROJ + 2048 + h * 128 + 16 * mi + 4 * fq);
;         asm volatile("" : "+v"(gg1[0]), "+v"(gg1[1]), "+v"(gg1[2]), "+v"(gg1[3]), "+v"(gg1[4]), "+v"(gg1[5]), "+v"(gg1[6]), "+v"(gg1[7]));
;         float ss = 0.f;
; #pragma unroll
;         for (int mi = 0; mi < 8; ++mi) { acc[mi][ni] = acc[mi][ni] * 0.125f; const f32x4 o = acc[mi][ni]; ss += (o[0] * o[0] + o[1] * o[1]) + (o[2] * o[2] + o[3] * o[3]); }
;         ss += __shfl_xor(ss, 16); ss += __shfl_xor(ss, 32);
;         const float rs = __builtin_amdgcn_rsqf(ss * (1.f / 128.f) + EPS);
;         const size_t tok = (size_t)(tok0 + 16 * ni + fr);
; #pragma unroll
;         for (int mi = 0; mi < 8; ++mi) {
;             const int v = h * 128 + 16 * mi + 4 * fq;
;             const f32x4 no = nov[mi]; const u32x2 g2 = gg1[mi];
;             const f32x4 o = acc[mi][ni];
;             const float y0 = o[0] * rs * no[0] * silu_f(bf_lo(g2.x)), y1 = o[1] * rs * no[1] * silu_f(bf_hi(g2.x));
;             const float y2 = o[2] * rs * no[2] * silu_f(bf_lo(g2.y)), y3 = o[3] * rs * no[3] * silu_f(bf_hi(g2.y));
;             u32x2 w; w.x = pk2(y0, y1); w.y = pk2(y2, y3);
;             *(u32x2*)(Y + tok * D + 512 + v) = w;
;         }
	v_pk_mul_f32 v[112:113], v[112:113], v[100:101] op_sel_hi:[1,0]
	v_pk_mul_f32 v[108:109], v[120:121], v[108:109]
	v_pk_mul_f32 v[112:113], v[42:43], v[112:113]
	v_pk_mul_f32 v[110:111], v[118:119], v[110:111]
	v_and_b32_sdwa v101, v109, v207 dst_sel:DWORD dst_unused:UNUSED_PAD src0_sel:WORD_1 src1_sel:DWORD
	v_pk_mul_f32 v[110:111], v[112:113], v[110:111]
	v_and_b32_sdwa v112, v108, v207 dst_sel:DWORD dst_unused:UNUSED_PAD src0_sel:WORD_1 src1_sel:DWORD
	v_add3_u32 v108, v108, v112, s30
	v_add3_u32 v101, v109, v101, s30
	v_and_b32_sdwa v109, v111, v207 dst_sel:DWORD dst_unused:UNUSED_PAD src0_sel:WORD_1 src1_sel:DWORD
	v_and_b32_sdwa v112, v110, v207 dst_sel:DWORD dst_unused:UNUSED_PAD src0_sel:WORD_1 src1_sel:DWORD
	v_add3_u32 v109, v111, v109, s30
	v_add3_u32 v110, v110, v112, s30
	v_and_b32_e32 v109, 0xffff0000, v109
	v_and_b32_e32 v110, 0xffff0000, v110
	v_or_b32_sdwa v109, v109, v101 dst_sel:DWORD dst_unused:UNUSED_PAD src0_sel:DWORD src1_sel:WORD_1
	v_or_b32_sdwa v108, v110, v108 dst_sel:DWORD dst_unused:UNUSED_PAD src0_sel:DWORD src1_sel:WORD_1
	global_store_dwordx2 v[106:107], v[108:109], off offset:1184
	v_lshlrev_b32_e32 v108, 16, v130
	v_mul_f32_e32 v101, 0xbfb8aa3b, v108
	v_and_b32_e32 v110, 0xffff0000, v130
	v_exp_f32_e32 v101, v101
	v_mul_f32_e32 v111, 0xbfb8aa3b, v110
	v_exp_f32_e32 v113, v111
	v_lshlrev_b32_e32 v109, 16, v131
	v_add_f32_e32 v101, 1.0, v101
	v_rcp_f32_e32 v112, v101
	v_add_f32_e32 v101, 1.0, v113
	v_rcp_f32_e32 v114, v101
	v_mul_f32_e32 v101, 0xbfb8aa3b, v109
	v_exp_f32_e32 v101, v101
	v_mov_b32_e32 v116, v104
	v_mov_b32_e32 v117, v102
	v_and_b32_e32 v111, 0xffff0000, v131
	v_pk_mul_f32 v[116:117], v[116:117], v[100:101] op_sel_hi:[1,0]
	v_add_f32_e32 v101, 1.0, v101
	v_rcp_f32_e32 v113, v101
	v_mul_f32_e32 v101, 0xbfb8aa3b, v111
	v_exp_f32_e32 v101, v101
	v_mov_b32_e32 v102, v105
	v_pk_mul_f32 v[116:117], v[40:41], v[116:117]
	v_pk_mul_f32 v[108:109], v[112:113], v[108:109]
	v_add_f32_e32 v101, 1.0, v101
	v_rcp_f32_e32 v115, v101
	v_pk_mul_f32 v[102:103], v[102:103], v[100:101] op_sel_hi:[1,0]
	v_pk_mul_f32 v[108:109], v[116:117], v[108:109]
	v_pk_mul_f32 v[102:103], v[38:39], v[102:103]
	v_pk_mul_f32 v[104:105], v[114:115], v[110:111]
	v_and_b32_sdwa v101, v109, v207 dst_sel:DWORD dst_unused:UNUSED_PAD src0_sel:WORD_1 src1_sel:DWORD
	v_pk_mul_f32 v[102:103], v[102:103], v[104:105]
	v_and_b32_sdwa v104, v108, v207 dst_sel:DWORD dst_unused:UNUSED_PAD src0_sel:WORD_1 src1_sel:DWORD
	v_add3_u32 v104, v108, v104, s30
	v_and_b32_sdwa v105, v103, v207 dst_sel:DWORD dst_unused:UNUSED_PAD src0_sel:WORD_1 src1_sel:DWORD
	v_and_b32_sdwa v108, v102, v207 dst_sel:DWORD dst_unused:UNUSED_PAD src0_sel:WORD_1 src1_sel:DWORD
	v_add3_u32 v103, v103, v105, s30
	v_add3_u32 v102, v102, v108, s30
	v_add3_u32 v101, v109, v101, s30
	v_and_b32_e32 v103, 0xffff0000, v103
	v_and_b32_e32 v102, 0xffff0000, v102
	v_or_b32_sdwa v103, v103, v101 dst_sel:DWORD dst_unused:UNUSED_PAD src0_sel:DWORD src1_sel:WORD_1
	v_or_b32_sdwa v102, v102, v104 dst_sel:DWORD dst_unused:UNUSED_PAD src0_sel:DWORD src1_sel:WORD_1
	global_store_dwordx2 v[106:107], v[102:103], off offset:1216
	v_lshlrev_b32_e32 v102, 16, v32
	v_mul_f32_e32 v101, 0xbfb8aa3b, v102
	v_and_b32_e32 v32, 0xffff0000, v32
	v_exp_f32_e32 v101, v101
	v_mul_f32_e32 v104, 0xbfb8aa3b, v32
	v_exp_f32_e32 v105, v104
	v_lshlrev_b32_e32 v103, 16, v33
	v_add_f32_e32 v101, 1.0, v101
	v_rcp_f32_e32 v104, v101
	v_add_f32_e32 v101, 1.0, v105
	v_rcp_f32_e32 v108, v101
	v_mul_f32_e32 v101, 0xbfb8aa3b, v103
	v_exp_f32_e32 v101, v101
	v_and_b32_e32 v33, 0xffff0000, v33
	v_mov_b32_e32 v111, v96
	v_mov_b32_e32 v110, v98
	v_add_f32_e32 v96, 1.0, v101
	v_rcp_f32_e32 v105, v96
	v_mul_f32_e32 v96, 0xbfb8aa3b, v33
	v_exp_f32_e32 v96, v96
	v_pk_mul_f32 v[110:111], v[110:111], v[100:101] op_sel_hi:[1,0]
	v_pk_mul_f32 v[102:103], v[104:105], v[102:103]
	v_pk_mul_f32 v[110:111], v[36:37], v[110:111]
	v_add_f32_e32 v96, 1.0, v96
	v_rcp_f32_e32 v109, v96
	v_mov_b32_e32 v96, v99
	v_pk_mul_f32 v[96:97], v[96:97], v[100:101] op_sel_hi:[1,0]
	v_pk_mul_f32 v[102:103], v[110:111], v[102:103]
	v_pk_mul_f32 v[96:97], v[34:35], v[96:97]
	v_pk_mul_f32 v[32:33], v[108:109], v[32:33]
	v_pk_mul_f32 v[116:117], v[92:93], s[66:67] op_sel_hi:[1,0]
	v_pk_mul_f32 v[32:33], v[96:97], v[32:33]
	v_and_b32_sdwa v96, v103, v207 dst_sel:DWORD dst_unused:UNUSED_PAD src0_sel:WORD_1 src1_sel:DWORD
	v_and_b32_sdwa v98, v33, v207 dst_sel:DWORD dst_unused:UNUSED_PAD src0_sel:WORD_1 src1_sel:DWORD
	v_and_b32_sdwa v99, v32, v207 dst_sel:DWORD dst_unused:UNUSED_PAD src0_sel:WORD_1 src1_sel:DWORD
	v_and_b32_sdwa v97, v102, v207 dst_sel:DWORD dst_unused:UNUSED_PAD src0_sel:WORD_1 src1_sel:DWORD
	v_add3_u32 v33, v33, v98, s30
	v_add3_u32 v32, v32, v99, s30
	v_add3_u32 v97, v102, v97, s30
	v_add3_u32 v96, v103, v96, s30
	v_and_b32_e32 v33, 0xffff0000, v33
	v_and_b32_e32 v32, 0xffff0000, v32
	v_or_b32_sdwa v33, v33, v96 dst_sel:DWORD dst_unused:UNUSED_PAD src0_sel:DWORD src1_sel:WORD_1
	v_or_b32_sdwa v32, v32, v97 dst_sel:DWORD dst_unused:UNUSED_PAD src0_sel:DWORD src1_sel:WORD_1
	global_store_dwordx2 v[106:107], v[32:33], off offset:1248
	v_lshl_add_u64 v[32:33], v[152:153], 0, s[6:7]
	v_lshl_add_u64 v[32:33], v[32:33], 0, v[132:133]
	v_lshl_add_u64 v[106:107], v[32:33], 0, s[64:65]
	v_add_co_u32_e32 v32, vcc, s29, v32
	v_pk_mul_f32 v[120:121], v[88:89], s[66:67] op_sel_hi:[1,0]
	s_nop 0
	v_addc_co_u32_e32 v33, vcc, 0, v33, vcc
	global_load_dwordx2 v[110:111], v[106:107], off offset:32 nt
	global_load_dwordx2 v[104:105], v[106:107], off offset:64 nt
	global_load_dwordx2 v[102:103], v[106:107], off offset:96 nt
	global_load_dwordx2 v[100:101], v[106:107], off offset:128 nt
; __device__ __forceinline__ unsigned pk2(float lo, float hi) { return f2bf(lo) | (f2bf(hi) << 16); }
; __device__ __forceinline__ float silu_f(float g) { return g * __builtin_amdgcn_rcpf(1.0f + __expf(-g)); }
; __device__ __forceinline__ void gla_out_unit(const bf16* PROJ, const bf16* ST, const float* norm_o, bf16* Y, int unit, int lane) {
;     ...
;     for (int ni = 0; ni < 4; ++ni) {
;         u32x2 gg1[8];
; #pragma unroll
;         for (int mi = 0; mi < 8; ++mi) gg1[mi] = *(const u32x2*)(PROJ + (size_t)(tok0 + 16 * ni + fr) * NPROJ + 2048 + h * 128 + 16 * mi + 4 * fq);
;         asm volatile("" : "+v"(gg1[0]), "+v"(gg1[1]), "+v"(gg1[2]), "+v"(gg1[3]), "+v"(gg1[4]), "+v"(gg1[5]), "+v"(gg1[6]), "+v"(gg1[7]));
;         float ss = 0.f;
; #pragma unroll
;         for (int mi = 0; mi < 8; ++mi) { acc[mi][ni] = acc[mi][ni] * 0.125f; const f32x4 o = acc[mi][ni]; ss += (o[0] * o[0] + o[1] * o[1]) + (o[2] * o[2] + o[3] * o[3]); }
;         ss += __shfl_xor(ss, 16); ss += __shfl_xor(ss, 32);
;         const float rs = __builtin_amdgcn_rsqf(ss * (1.f / 128.f) + EPS);
;         const size_t tok = (size_t)(tok0 + 16 * ni + fr);
; #pragma unroll
;         for (int mi = 0; mi < 8; ++mi) {
;             const int v = h * 128 + 16 * mi + 4 * fq;
;             const f32x4 no = nov[mi]; const u32x2 g2 = gg1[mi];
;             const f32x4 o = acc[mi][ni];
;             const float y0 = o[0] * rs * no[0] * silu_f(bf_lo(g2.x)), y1 = o[1] * rs * no[1] * silu_f(bf_hi(g2.x));
;             const float y2 = o[2] * rs * no[2] * silu_f(bf_lo(g2.y)), y3 = o[3] * rs * no[3] * silu_f(bf_hi(g2.y));
;             u32x2 w; w.x = pk2(y0, y1); w.y = pk2(y2, y3);
;             *(u32x2*)(Y + tok * D + 512 + v) = w;
;         }
	global_load_dwordx2 v[112:113], v[32:33], off nt
	global_load_dwordx2 v[98:99], v[106:107], off offset:160 nt
	global_load_dwordx2 v[96:97], v[106:107], off offset:192 nt
	s_nop 0
	global_load_dwordx2 v[32:33], v[106:107], off offset:224 nt
	v_pk_mul_f32 v[114:115], v[94:95], s[66:67] op_sel_hi:[1,0]
	v_pk_mul_f32 v[118:119], v[90:91], s[66:67] op_sel_hi:[1,0]
	v_mov_b32_e32 v90, v117
	v_mov_b32_e32 v91, v121
	v_mov_b32_e32 v88, v116
	v_mov_b32_e32 v89, v120
	v_pk_mul_f32 v[90:91], v[90:91], v[90:91]
	v_mov_b32_e32 v92, v115
	v_mov_b32_e32 v93, v119
	v_pk_fma_f32 v[88:89], v[88:89], v[88:89], v[90:91]
	v_mov_b32_e32 v90, v114
	v_mov_b32_e32 v91, v118
	v_pk_mul_f32 v[92:93], v[92:93], v[92:93]
	v_pk_mul_f32 v[106:107], v[82:83], s[66:67] op_sel_hi:[1,0]
	v_pk_mul_f32 v[108:109], v[80:81], s[66:67] op_sel_hi:[1,0]
	v_pk_fma_f32 v[90:91], v[90:91], v[90:91], v[92:93]
	v_pk_mul_f32 v[80:81], v[106:107], v[106:107]
	v_pk_mul_f32 v[82:83], v[108:109], v[108:109]
	v_pk_add_f32 v[122:123], v[88:89], v[90:91]
	v_pk_mov_b32 v[88:89], v[82:83], v[80:81] op_sel:[1,0]
	v_mov_b32_e32 v83, v81
	v_pk_mul_f32 v[90:91], v[68:69], s[66:67] op_sel_hi:[1,0]
	v_pk_add_f32 v[80:81], v[88:89], v[82:83]
	v_pk_mul_f32 v[88:89], v[70:71], s[66:67] op_sel_hi:[1,0]
	v_mul_f32_e32 v70, v90, v90
	v_pk_add_f32 v[68:69], v[122:123], v[122:123] op_sel:[0,1] op_sel_hi:[1,0]
	v_pk_mul_f32 v[94:95], v[72:73], s[66:67] op_sel_hi:[1,0]
	v_mul_f32_e32 v72, v91, v91
	v_mov_b32_e32 v69, v70
	v_pk_add_f32 v[70:71], v[80:81], v[80:81] op_sel:[0,1] op_sel_hi:[1,0]
	v_pk_mul_f32 v[92:93], v[74:75], s[66:67] op_sel_hi:[1,0]
	v_mov_b32_e32 v71, v72
	v_pk_add_f32 v[68:69], v[68:69], v[70:71]
	v_mul_f32_e32 v70, v95, v95
	v_mul_f32_e32 v73, v88, v88
	v_pk_fma_f32 v[70:71], v[94:95], v[94:95], v[70:71] op_sel_hi:[1,1,0]
	v_mul_f32_e32 v72, v93, v93
	v_mul_f32_e32 v74, v89, v89
	v_mov_b32_e32 v71, v73
	v_pk_fma_f32 v[72:73], v[92:93], v[92:93], v[72:73] op_sel_hi:[1,1,0]
	v_pk_mul_f32 v[80:81], v[62:63], s[66:67] op_sel_hi:[1,0]
	v_mov_b32_e32 v73, v74
	v_pk_mul_f32 v[82:83], v[60:61], s[66:67] op_sel_hi:[1,0]
	v_pk_add_f32 v[70:71], v[70:71], v[72:73]
	v_pk_mul_f32 v[60:61], v[80:81], v[80:81]
	v_pk_mul_f32 v[62:63], v[82:83], v[82:83]
	v_pk_add_f32 v[68:69], v[68:69], v[70:71]
	v_pk_mov_b32 v[70:71], v[62:63], v[60:61] op_sel:[1,0]
	v_mov_b32_e32 v63, v61
	v_pk_add_f32 v[74:75], v[70:71], v[62:63]
	v_pk_mul_f32 v[62:63], v[84:85], s[66:67] op_sel_hi:[1,0]
	v_pk_mul_f32 v[72:73], v[76:77], s[66:67] op_sel_hi:[1,0]
	v_mul_f32_e32 v76, v62, v62
	v_mul_f32_e32 v77, v63, v63
	v_pk_add_f32 v[68:69], v[68:69], v[68:69] op_sel:[0,1] op_sel_hi:[1,0]
	v_pk_add_f32 v[74:75], v[74:75], v[74:75] op_sel:[0,1] op_sel_hi:[1,0]
	v_pk_mul_f32 v[70:71], v[78:79], s[66:67] op_sel_hi:[1,0]
	v_mov_b32_e32 v69, v76
	v_mov_b32_e32 v75, v77
	v_pk_mul_f32 v[60:61], v[86:87], s[66:67] op_sel_hi:[1,0]
	v_pk_add_f32 v[68:69], v[68:69], v[74:75]
	v_mul_f32_e32 v74, v73, v73
	v_mul_f32_e32 v76, v71, v71
	v_mul_f32_e32 v78, v60, v60
	v_mul_f32_e32 v79, v61, v61
	v_pk_fma_f32 v[74:75], v[72:73], v[72:73], v[74:75] op_sel_hi:[1,1,0]
	v_pk_fma_f32 v[76:77], v[70:71], v[70:71], v[76:77] op_sel_hi:[1,1,0]
	v_mov_b32_e32 v75, v78
	v_mov_b32_e32 v77, v79
	v_pk_add_f32 v[74:75], v[74:75], v[76:77]
	s_waitcnt vmcnt(0)
	v_pk_add_f32 v[68:69], v[68:69], v[74:75]
	v_lshlrev_b32_e32 v76, 16, v112
	v_add_f32_e32 v68, v68, v69
	ds_bpermute_b32 v69, v208, v68
	v_and_b32_e32 v78, 0xffff0000, v112
	v_mul_f32_e32 v79, 0xbfb8aa3b, v78
	v_exp_f32_e32 v85, v79
	v_lshlrev_b32_e32 v77, 16, v113
	s_waitcnt lgkmcnt(0)
	v_add_f32_e32 v68, v68, v69
	ds_bpermute_b32 v69, v209, v68
	v_and_b32_e32 v79, 0xffff0000, v113
	v_mov_b32_e32 v112, v116
	v_mov_b32_e32 v113, v114
	v_mov_b32_e32 v114, v117
	s_waitcnt lgkmcnt(0)
	v_add_f32_e32 v68, v68, v69
	v_mul_f32_e32 v69, 0xbfb8aa3b, v76
	v_exp_f32_e32 v69, v69
	v_fmamk_f32 v68, v68, 0x3c000000, v145
	v_rsq_f32_e32 v68, v68
	v_lshlrev_b64 v[74:75], 11, v[150:151]
	v_add_f32_e32 v69, 1.0, v69
	v_rcp_f32_e32 v84, v69
	v_add_f32_e32 v69, 1.0, v85
	v_rcp_f32_e32 v86, v69
	v_mul_f32_e32 v69, 0xbfb8aa3b, v77
	v_exp_f32_e32 v69, v69
	v_lshl_add_u64 v[74:75], v[138:139], 0, v[74:75]
	v_pk_mul_f32 v[112:113], v[112:113], v[68:69] op_sel_hi:[1,0]
	v_add_f32_e32 v69, 1.0, v69
	v_rcp_f32_e32 v85, v69
	v_mul_f32_e32 v69, 0xbfb8aa3b, v79
	v_exp_f32_e32 v69, v69
	v_pk_mul_f32 v[112:113], v[128:129], v[112:113]
	v_pk_mul_f32 v[76:77], v[84:85], v[76:77]
	v_add_f32_e32 v69, 1.0, v69
	v_rcp_f32_e32 v87, v69
	v_pk_mul_f32 v[84:85], v[114:115], v[68:69] op_sel_hi:[1,0]
	v_pk_mul_f32 v[76:77], v[112:113], v[76:77]
	v_pk_mul_f32 v[84:85], v[54:55], v[84:85]
	v_pk_mul_f32 v[78:79], v[86:87], v[78:79]
	v_and_b32_sdwa v69, v77, v207 dst_sel:DWORD dst_unused:UNUSED_PAD src0_sel:WORD_1 src1_sel:DWORD
	v_pk_mul_f32 v[78:79], v[84:85], v[78:79]
	v_and_b32_sdwa v84, v76, v207 dst_sel:DWORD dst_unused:UNUSED_PAD src0_sel:WORD_1 src1_sel:DWORD
	v_add3_u32 v76, v76, v84, s30
	v_add3_u32 v69, v77, v69, s30
	v_and_b32_sdwa v77, v79, v207 dst_sel:DWORD dst_unused:UNUSED_PAD src0_sel:WORD_1 src1_sel:DWORD
	v_and_b32_sdwa v84, v78, v207 dst_sel:DWORD dst_unused:UNUSED_PAD src0_sel:WORD_1 src1_sel:DWORD
	v_add3_u32 v77, v79, v77, s30
	v_add3_u32 v78, v78, v84, s30
	v_and_b32_e32 v77, 0xffff0000, v77
	v_and_b32_e32 v78, 0xffff0000, v78
	v_or_b32_sdwa v77, v77, v69 dst_sel:DWORD dst_unused:UNUSED_PAD src0_sel:DWORD src1_sel:WORD_1
	v_or_b32_sdwa v76, v78, v76 dst_sel:DWORD dst_unused:UNUSED_PAD src0_sel:DWORD src1_sel:WORD_1
	global_store_dwordx2 v[74:75], v[76:77], off offset:1024
	v_lshlrev_b32_e32 v76, 16, v110
	v_mul_f32_e32 v69, 0xbfb8aa3b, v76
; __device__ __forceinline__ unsigned pk2(float lo, float hi) { return f2bf(lo) | (f2bf(hi) << 16); }
; __device__ __forceinline__ float silu_f(float g) { return g * __builtin_amdgcn_rcpf(1.0f + __expf(-g)); }
; __device__ __forceinline__ void gla_out_unit(const bf16* PROJ, const bf16* ST, const float* norm_o, bf16* Y, int unit, int lane) {
;     ...
; #pragma unroll
;         for (int mi = 0; mi < 8; ++mi) {
;             const int v = h * 128 + 16 * mi + 4 * fq;
;             const f32x4 no = nov[mi]; const u32x2 g2 = gg1[mi];
;             const f32x4 o = acc[mi][ni];
;             const float y0 = o[0] * rs * no[0] * silu_f(bf_lo(g2.x)), y1 = o[1] * rs * no[1] * silu_f(bf_hi(g2.x));
;             const float y2 = o[2] * rs * no[2] * silu_f(bf_lo(g2.y)), y3 = o[3] * rs * no[3] * silu_f(bf_hi(g2.y));
;             u32x2 w; w.x = pk2(y0, y1); w.y = pk2(y2, y3);
;             *(u32x2*)(Y + tok * D + 512 + v) = w;
;         }
	v_and_b32_e32 v78, 0xffff0000, v110
	v_exp_f32_e32 v69, v69
	v_mul_f32_e32 v79, 0xbfb8aa3b, v78
	v_exp_f32_e32 v85, v79
	v_lshlrev_b32_e32 v77, 16, v111
	v_add_f32_e32 v69, 1.0, v69
	v_rcp_f32_e32 v84, v69
	v_add_f32_e32 v69, 1.0, v85
	v_rcp_f32_e32 v86, v69
	v_mul_f32_e32 v69, 0xbfb8aa3b, v77
	v_exp_f32_e32 v69, v69
	v_and_b32_e32 v79, 0xffff0000, v111
	v_mov_b32_e32 v110, v120
	v_mov_b32_e32 v111, v118
	v_pk_mul_f32 v[110:111], v[110:111], v[68:69] op_sel_hi:[1,0]
	v_add_f32_e32 v69, 1.0, v69
	v_rcp_f32_e32 v85, v69
	v_mul_f32_e32 v69, 0xbfb8aa3b, v79
	v_exp_f32_e32 v69, v69
	v_mov_b32_e32 v118, v121
	v_pk_mul_f32 v[110:111], v[52:53], v[110:111]
	v_pk_mul_f32 v[76:77], v[84:85], v[76:77]
	v_add_f32_e32 v69, 1.0, v69
	v_rcp_f32_e32 v87, v69
	v_pk_mul_f32 v[84:85], v[118:119], v[68:69] op_sel_hi:[1,0]
	v_pk_mul_f32 v[76:77], v[110:111], v[76:77]
	v_pk_mul_f32 v[84:85], v[66:67], v[84:85]
	v_pk_mul_f32 v[78:79], v[86:87], v[78:79]
	v_and_b32_sdwa v69, v77, v207 dst_sel:DWORD dst_unused:UNUSED_PAD src0_sel:WORD_1 src1_sel:DWORD
	v_pk_mul_f32 v[78:79], v[84:85], v[78:79]
	v_and_b32_sdwa v84, v76, v207 dst_sel:DWORD dst_unused:UNUSED_PAD src0_sel:WORD_1 src1_sel:DWORD
	v_add3_u32 v76, v76, v84, s30
	v_add3_u32 v69, v77, v69, s30
	v_and_b32_sdwa v77, v79, v207 dst_sel:DWORD dst_unused:UNUSED_PAD src0_sel:WORD_1 src1_sel:DWORD
	v_and_b32_sdwa v84, v78, v207 dst_sel:DWORD dst_unused:UNUSED_PAD src0_sel:WORD_1 src1_sel:DWORD
	v_add3_u32 v77, v79, v77, s30
	v_add3_u32 v78, v78, v84, s30
	v_and_b32_e32 v77, 0xffff0000, v77
	v_and_b32_e32 v78, 0xffff0000, v78
	v_or_b32_sdwa v77, v77, v69 dst_sel:DWORD dst_unused:UNUSED_PAD src0_sel:DWORD src1_sel:WORD_1
	v_or_b32_sdwa v76, v78, v76 dst_sel:DWORD dst_unused:UNUSED_PAD src0_sel:DWORD src1_sel:WORD_1
	global_store_dwordx2 v[74:75], v[76:77], off offset:1056
	v_lshlrev_b32_e32 v76, 16, v104
	v_mul_f32_e32 v69, 0xbfb8aa3b, v76
	v_and_b32_e32 v78, 0xffff0000, v104
	v_exp_f32_e32 v69, v69
	v_mul_f32_e32 v79, 0xbfb8aa3b, v78
	v_exp_f32_e32 v85, v79
	v_lshlrev_b32_e32 v77, 16, v105
	v_add_f32_e32 v69, 1.0, v69
	v_rcp_f32_e32 v84, v69
	v_add_f32_e32 v69, 1.0, v85
	v_rcp_f32_e32 v86, v69
	v_mul_f32_e32 v69, 0xbfb8aa3b, v77
	v_exp_f32_e32 v69, v69
	v_and_b32_e32 v79, 0xffff0000, v105
	v_mov_b32_e32 v104, v108
	v_mov_b32_e32 v105, v106
	v_pk_mul_f32 v[104:105], v[104:105], v[68:69] op_sel_hi:[1,0]
	v_add_f32_e32 v69, 1.0, v69
	v_rcp_f32_e32 v85, v69
	v_mul_f32_e32 v69, 0xbfb8aa3b, v79
	v_exp_f32_e32 v69, v69
	v_mov_b32_e32 v106, v109
	v_pk_mul_f32 v[104:105], v[64:65], v[104:105]
	v_pk_mul_f32 v[76:77], v[84:85], v[76:77]
	v_add_f32_e32 v69, 1.0, v69
	v_rcp_f32_e32 v87, v69
	v_pk_mul_f32 v[84:85], v[106:107], v[68:69] op_sel_hi:[1,0]
	v_pk_mul_f32 v[76:77], v[104:105], v[76:77]
	v_pk_mul_f32 v[84:85], v[58:59], v[84:85]
	v_pk_mul_f32 v[78:79], v[86:87], v[78:79]
	v_and_b32_sdwa v69, v77, v207 dst_sel:DWORD dst_unused:UNUSED_PAD src0_sel:WORD_1 src1_sel:DWORD
	v_pk_mul_f32 v[78:79], v[84:85], v[78:79]
	v_and_b32_sdwa v84, v76, v207 dst_sel:DWORD dst_unused:UNUSED_PAD src0_sel:WORD_1 src1_sel:DWORD
	v_add3_u32 v76, v76, v84, s30
	v_add3_u32 v69, v77, v69, s30
	v_and_b32_sdwa v77, v79, v207 dst_sel:DWORD dst_unused:UNUSED_PAD src0_sel:WORD_1 src1_sel:DWORD
	v_and_b32_sdwa v84, v78, v207 dst_sel:DWORD dst_unused:UNUSED_PAD src0_sel:WORD_1 src1_sel:DWORD
	v_add3_u32 v77, v79, v77, s30
	v_add3_u32 v78, v78, v84, s30
	v_and_b32_e32 v77, 0xffff0000, v77
	v_and_b32_e32 v78, 0xffff0000, v78
	v_or_b32_sdwa v77, v77, v69 dst_sel:DWORD dst_unused:UNUSED_PAD src0_sel:DWORD src1_sel:WORD_1
	v_or_b32_sdwa v76, v78, v76 dst_sel:DWORD dst_unused:UNUSED_PAD src0_sel:DWORD src1_sel:WORD_1
	global_store_dwordx2 v[74:75], v[76:77], off offset:1088
	v_lshlrev_b32_e32 v76, 16, v102
	v_mul_f32_e32 v69, 0xbfb8aa3b, v76
	v_and_b32_e32 v78, 0xffff0000, v102
	v_exp_f32_e32 v69, v69
	v_mul_f32_e32 v79, 0xbfb8aa3b, v78
	v_exp_f32_e32 v85, v79
	v_lshlrev_b32_e32 v77, 16, v103
	v_add_f32_e32 v69, 1.0, v69
	v_rcp_f32_e32 v84, v69
	v_add_f32_e32 v69, 1.0, v85
	v_rcp_f32_e32 v86, v69
	v_mul_f32_e32 v69, 0xbfb8aa3b, v77
	v_exp_f32_e32 v69, v69
	v_and_b32_e32 v79, 0xffff0000, v103
	v_mov_b32_e32 v102, v94
	v_mov_b32_e32 v103, v92
	v_pk_mul_f32 v[102:103], v[102:103], v[68:69] op_sel_hi:[1,0]
	v_add_f32_e32 v69, 1.0, v69
	v_rcp_f32_e32 v85, v69
	v_mul_f32_e32 v69, 0xbfb8aa3b, v79
	v_exp_f32_e32 v69, v69
	v_mov_b32_e32 v92, v95
	v_pk_mul_f32 v[102:103], v[56:57], v[102:103]
	v_pk_mul_f32 v[76:77], v[84:85], v[76:77]
	v_add_f32_e32 v69, 1.0, v69
	v_rcp_f32_e32 v87, v69
	v_pk_mul_f32 v[84:85], v[92:93], v[68:69] op_sel_hi:[1,0]
	v_pk_mul_f32 v[76:77], v[102:103], v[76:77]
	v_pk_mul_f32 v[84:85], v[50:51], v[84:85]
	v_pk_mul_f32 v[78:79], v[86:87], v[78:79]
	v_and_b32_sdwa v69, v77, v207 dst_sel:DWORD dst_unused:UNUSED_PAD src0_sel:WORD_1 src1_sel:DWORD
	v_pk_mul_f32 v[78:79], v[84:85], v[78:79]
	v_and_b32_sdwa v84, v76, v207 dst_sel:DWORD dst_unused:UNUSED_PAD src0_sel:WORD_1 src1_sel:DWORD
	v_add3_u32 v76, v76, v84, s30
	v_add3_u32 v69, v77, v69, s30
	v_and_b32_sdwa v77, v79, v207 dst_sel:DWORD dst_unused:UNUSED_PAD src0_sel:WORD_1 src1_sel:DWORD
	v_and_b32_sdwa v84, v78, v207 dst_sel:DWORD dst_unused:UNUSED_PAD src0_sel:WORD_1 src1_sel:DWORD
	v_add3_u32 v77, v79, v77, s30
	v_add3_u32 v78, v78, v84, s30
	v_and_b32_e32 v77, 0xffff0000, v77
	v_and_b32_e32 v78, 0xffff0000, v78
	v_or_b32_sdwa v77, v77, v69 dst_sel:DWORD dst_unused:UNUSED_PAD src0_sel:DWORD src1_sel:WORD_1
	v_or_b32_sdwa v76, v78, v76 dst_sel:DWORD dst_unused:UNUSED_PAD src0_sel:DWORD src1_sel:WORD_1
	global_store_dwordx2 v[74:75], v[76:77], off offset:1120
	v_lshlrev_b32_e32 v76, 16, v100
; __device__ __forceinline__ unsigned pk2(float lo, float hi) { return f2bf(lo) | (f2bf(hi) << 16); }
; __device__ __forceinline__ float silu_f(float g) { return g * __builtin_amdgcn_rcpf(1.0f + __expf(-g)); }
; __device__ __forceinline__ void gla_out_unit(const bf16* PROJ, const bf16* ST, const float* norm_o, bf16* Y, int unit, int lane) {
;     ...
; #pragma unroll
;         for (int mi = 0; mi < 8; ++mi) {
;             const int v = h * 128 + 16 * mi + 4 * fq;
;             const f32x4 no = nov[mi]; const u32x2 g2 = gg1[mi];
;             const f32x4 o = acc[mi][ni];
;             const float y0 = o[0] * rs * no[0] * silu_f(bf_lo(g2.x)), y1 = o[1] * rs * no[1] * silu_f(bf_hi(g2.x));
;             const float y2 = o[2] * rs * no[2] * silu_f(bf_lo(g2.y)), y3 = o[3] * rs * no[3] * silu_f(bf_hi(g2.y));
;             u32x2 w; w.x = pk2(y0, y1); w.y = pk2(y2, y3);
;             *(u32x2*)(Y + tok * D + 512 + v) = w;
;         }
	v_mul_f32_e32 v69, 0xbfb8aa3b, v76
	v_and_b32_e32 v78, 0xffff0000, v100
	v_exp_f32_e32 v69, v69
	v_mul_f32_e32 v79, 0xbfb8aa3b, v78
	v_exp_f32_e32 v85, v79
	v_lshlrev_b32_e32 v77, 16, v101
	v_add_f32_e32 v69, 1.0, v69
	v_rcp_f32_e32 v84, v69
	v_add_f32_e32 v69, 1.0, v85
	v_rcp_f32_e32 v86, v69
	v_mul_f32_e32 v69, 0xbfb8aa3b, v77
	v_exp_f32_e32 v69, v69
	v_mov_b32_e32 v92, v90
	v_mov_b32_e32 v93, v88
	v_and_b32_e32 v79, 0xffff0000, v101
	v_pk_mul_f32 v[92:93], v[92:93], v[68:69] op_sel_hi:[1,0]
	v_add_f32_e32 v69, 1.0, v69
	v_rcp_f32_e32 v85, v69
	v_mul_f32_e32 v69, 0xbfb8aa3b, v79
	v_exp_f32_e32 v69, v69
	v_mov_b32_e32 v88, v91
	v_pk_mul_f32 v[92:93], v[48:49], v[92:93]
	v_pk_mul_f32 v[76:77], v[84:85], v[76:77]
	v_add_f32_e32 v69, 1.0, v69
	v_rcp_f32_e32 v87, v69
	v_pk_mul_f32 v[84:85], v[88:89], v[68:69] op_sel_hi:[1,0]
	v_pk_mul_f32 v[76:77], v[92:93], v[76:77]
	v_pk_mul_f32 v[84:85], v[46:47], v[84:85]
	v_pk_mul_f32 v[78:79], v[86:87], v[78:79]
	v_and_b32_sdwa v69, v77, v207 dst_sel:DWORD dst_unused:UNUSED_PAD src0_sel:WORD_1 src1_sel:DWORD
	v_pk_mul_f32 v[78:79], v[84:85], v[78:79]
	v_and_b32_sdwa v84, v76, v207 dst_sel:DWORD dst_unused:UNUSED_PAD src0_sel:WORD_1 src1_sel:DWORD
	v_add3_u32 v76, v76, v84, s30
	v_add3_u32 v69, v77, v69, s30
	v_and_b32_sdwa v77, v79, v207 dst_sel:DWORD dst_unused:UNUSED_PAD src0_sel:WORD_1 src1_sel:DWORD
	v_and_b32_sdwa v84, v78, v207 dst_sel:DWORD dst_unused:UNUSED_PAD src0_sel:WORD_1 src1_sel:DWORD
	v_add3_u32 v77, v79, v77, s30
	v_add3_u32 v78, v78, v84, s30
	v_and_b32_e32 v77, 0xffff0000, v77
	v_and_b32_e32 v78, 0xffff0000, v78
	v_or_b32_sdwa v77, v77, v69 dst_sel:DWORD dst_unused:UNUSED_PAD src0_sel:DWORD src1_sel:WORD_1
	v_or_b32_sdwa v76, v78, v76 dst_sel:DWORD dst_unused:UNUSED_PAD src0_sel:DWORD src1_sel:WORD_1
	global_store_dwordx2 v[74:75], v[76:77], off offset:1152
	v_lshlrev_b32_e32 v76, 16, v98
	v_mul_f32_e32 v69, 0xbfb8aa3b, v76
	v_and_b32_e32 v78, 0xffff0000, v98
	v_exp_f32_e32 v69, v69
	v_mul_f32_e32 v79, 0xbfb8aa3b, v78
	v_exp_f32_e32 v85, v79
	v_lshlrev_b32_e32 v77, 16, v99
	v_add_f32_e32 v69, 1.0, v69
	v_rcp_f32_e32 v84, v69
	v_add_f32_e32 v69, 1.0, v85
	v_rcp_f32_e32 v86, v69
	v_mul_f32_e32 v69, 0xbfb8aa3b, v77
	v_exp_f32_e32 v69, v69
	v_mov_b32_e32 v88, v82
	v_mov_b32_e32 v89, v80
	v_and_b32_e32 v79, 0xffff0000, v99
	v_pk_mul_f32 v[88:89], v[88:89], v[68:69] op_sel_hi:[1,0]
	v_add_f32_e32 v69, 1.0, v69
	v_rcp_f32_e32 v85, v69
	v_mul_f32_e32 v69, 0xbfb8aa3b, v79
	v_exp_f32_e32 v69, v69
	v_mov_b32_e32 v80, v83
	v_pk_mul_f32 v[88:89], v[44:45], v[88:89]
	v_pk_mul_f32 v[76:77], v[84:85], v[76:77]
	v_add_f32_e32 v69, 1.0, v69
	v_rcp_f32_e32 v87, v69
	v_pk_mul_f32 v[80:81], v[80:81], v[68:69] op_sel_hi:[1,0]
	v_pk_mul_f32 v[76:77], v[88:89], v[76:77]
	v_pk_mul_f32 v[80:81], v[42:43], v[80:81]
	v_pk_mul_f32 v[78:79], v[86:87], v[78:79]
	v_and_b32_sdwa v69, v77, v207 dst_sel:DWORD dst_unused:UNUSED_PAD src0_sel:WORD_1 src1_sel:DWORD
	v_pk_mul_f32 v[78:79], v[80:81], v[78:79]
	v_and_b32_sdwa v80, v76, v207 dst_sel:DWORD dst_unused:UNUSED_PAD src0_sel:WORD_1 src1_sel:DWORD
	v_add3_u32 v76, v76, v80, s30
	v_add3_u32 v69, v77, v69, s30
	v_and_b32_sdwa v77, v79, v207 dst_sel:DWORD dst_unused:UNUSED_PAD src0_sel:WORD_1 src1_sel:DWORD
	v_and_b32_sdwa v80, v78, v207 dst_sel:DWORD dst_unused:UNUSED_PAD src0_sel:WORD_1 src1_sel:DWORD
	v_add3_u32 v77, v79, v77, s30
	v_add3_u32 v78, v78, v80, s30
	v_and_b32_e32 v77, 0xffff0000, v77
	v_and_b32_e32 v78, 0xffff0000, v78
	v_or_b32_sdwa v77, v77, v69 dst_sel:DWORD dst_unused:UNUSED_PAD src0_sel:DWORD src1_sel:WORD_1
	v_or_b32_sdwa v76, v78, v76 dst_sel:DWORD dst_unused:UNUSED_PAD src0_sel:DWORD src1_sel:WORD_1
	global_store_dwordx2 v[74:75], v[76:77], off offset:1184
	v_lshlrev_b32_e32 v76, 16, v96
	v_mul_f32_e32 v69, 0xbfb8aa3b, v76
	v_and_b32_e32 v78, 0xffff0000, v96
	v_exp_f32_e32 v69, v69
	v_mul_f32_e32 v79, 0xbfb8aa3b, v78
	v_exp_f32_e32 v81, v79
	v_lshlrev_b32_e32 v77, 16, v97
	v_add_f32_e32 v69, 1.0, v69
	v_rcp_f32_e32 v80, v69
	v_add_f32_e32 v69, 1.0, v81
	v_rcp_f32_e32 v82, v69
	v_mul_f32_e32 v69, 0xbfb8aa3b, v77
	v_exp_f32_e32 v69, v69
	v_mov_b32_e32 v84, v72
	v_mov_b32_e32 v85, v70
	v_and_b32_e32 v79, 0xffff0000, v97
	v_pk_mul_f32 v[84:85], v[84:85], v[68:69] op_sel_hi:[1,0]
	v_add_f32_e32 v69, 1.0, v69
	v_rcp_f32_e32 v81, v69
	v_mul_f32_e32 v69, 0xbfb8aa3b, v79
	v_exp_f32_e32 v69, v69
	v_mov_b32_e32 v70, v73
	v_pk_mul_f32 v[84:85], v[40:41], v[84:85]
	v_pk_mul_f32 v[76:77], v[80:81], v[76:77]
	v_add_f32_e32 v69, 1.0, v69
	v_rcp_f32_e32 v83, v69
	v_pk_mul_f32 v[70:71], v[70:71], v[68:69] op_sel_hi:[1,0]
	v_pk_mul_f32 v[76:77], v[84:85], v[76:77]
	v_pk_mul_f32 v[70:71], v[38:39], v[70:71]
	v_pk_mul_f32 v[72:73], v[82:83], v[78:79]
	v_and_b32_sdwa v69, v77, v207 dst_sel:DWORD dst_unused:UNUSED_PAD src0_sel:WORD_1 src1_sel:DWORD
	v_pk_mul_f32 v[70:71], v[70:71], v[72:73]
	v_and_b32_sdwa v72, v76, v207 dst_sel:DWORD dst_unused:UNUSED_PAD src0_sel:WORD_1 src1_sel:DWORD
	v_add3_u32 v72, v76, v72, s30
	v_and_b32_sdwa v73, v71, v207 dst_sel:DWORD dst_unused:UNUSED_PAD src0_sel:WORD_1 src1_sel:DWORD
	v_and_b32_sdwa v76, v70, v207 dst_sel:DWORD dst_unused:UNUSED_PAD src0_sel:WORD_1 src1_sel:DWORD
	v_add3_u32 v71, v71, v73, s30
	v_add3_u32 v70, v70, v76, s30
	v_add3_u32 v69, v77, v69, s30
	v_and_b32_e32 v71, 0xffff0000, v71
	v_and_b32_e32 v70, 0xffff0000, v70
	v_or_b32_sdwa v71, v71, v69 dst_sel:DWORD dst_unused:UNUSED_PAD src0_sel:DWORD src1_sel:WORD_1
	v_or_b32_sdwa v70, v70, v72 dst_sel:DWORD dst_unused:UNUSED_PAD src0_sel:DWORD src1_sel:WORD_1
	global_store_dwordx2 v[74:75], v[70:71], off offset:1216
	v_lshlrev_b32_e32 v70, 16, v32
; __device__ __forceinline__ unsigned pk2(float lo, float hi) { return f2bf(lo) | (f2bf(hi) << 16); }
; __device__ __forceinline__ float silu_f(float g) { return g * __builtin_amdgcn_rcpf(1.0f + __expf(-g)); }
; __device__ __forceinline__ void gla_out_unit(const bf16* PROJ, const bf16* ST, const float* norm_o, bf16* Y, int unit, int lane) {
;     ...
;         for (int mi = 0; mi < 8; ++mi) gg1[mi] = *(const u32x2*)(PROJ + (size_t)(tok0 + 16 * ni + fr) * NPROJ + 2048 + h * 128 + 16 * mi + 4 * fq);
;         asm volatile("" : "+v"(gg1[0]), "+v"(gg1[1]), "+v"(gg1[2]), "+v"(gg1[3]), "+v"(gg1[4]), "+v"(gg1[5]), "+v"(gg1[6]), "+v"(gg1[7]));
;         float ss = 0.f;
; #pragma unroll
;         for (int mi = 0; mi < 8; ++mi) { acc[mi][ni] = acc[mi][ni] * 0.125f; const f32x4 o = acc[mi][ni]; ss += (o[0] * o[0] + o[1] * o[1]) + (o[2] * o[2] + o[3] * o[3]); }
;         ss += __shfl_xor(ss, 16); ss += __shfl_xor(ss, 32);
;         const float rs = __builtin_amdgcn_rsqf(ss * (1.f / 128.f) + EPS);
;         const size_t tok = (size_t)(tok0 + 16 * ni + fr);
; #pragma unroll
;         for (int mi = 0; mi < 8; ++mi) {
;             const int v = h * 128 + 16 * mi + 4 * fq;
;             const f32x4 no = nov[mi]; const u32x2 g2 = gg1[mi];
;             const f32x4 o = acc[mi][ni];
;             const float y0 = o[0] * rs * no[0] * silu_f(bf_lo(g2.x)), y1 = o[1] * rs * no[1] * silu_f(bf_hi(g2.x));
;             const float y2 = o[2] * rs * no[2] * silu_f(bf_lo(g2.y)), y3 = o[3] * rs * no[3] * silu_f(bf_hi(g2.y));
;             u32x2 w; w.x = pk2(y0, y1); w.y = pk2(y2, y3);
;             *(u32x2*)(Y + tok * D + 512 + v) = w;
;         }
	v_mul_f32_e32 v69, 0xbfb8aa3b, v70
	v_and_b32_e32 v32, 0xffff0000, v32
	v_exp_f32_e32 v69, v69
	v_mul_f32_e32 v72, 0xbfb8aa3b, v32
	v_exp_f32_e32 v73, v72
	v_lshlrev_b32_e32 v71, 16, v33
	v_add_f32_e32 v69, 1.0, v69
	v_rcp_f32_e32 v72, v69
	v_add_f32_e32 v69, 1.0, v73
	v_rcp_f32_e32 v76, v69
	v_mul_f32_e32 v69, 0xbfb8aa3b, v71
	v_exp_f32_e32 v69, v69
	v_and_b32_e32 v33, 0xffff0000, v33
	v_mov_b32_e32 v79, v60
	v_mov_b32_e32 v78, v62
	v_add_f32_e32 v60, 1.0, v69
	v_rcp_f32_e32 v73, v60
	v_mul_f32_e32 v60, 0xbfb8aa3b, v33
	v_exp_f32_e32 v60, v60
	v_pk_mul_f32 v[78:79], v[78:79], v[68:69] op_sel_hi:[1,0]
	v_pk_mul_f32 v[70:71], v[72:73], v[70:71]
	v_pk_mul_f32 v[78:79], v[36:37], v[78:79]
	v_add_f32_e32 v60, 1.0, v60
	v_rcp_f32_e32 v77, v60
	v_mov_b32_e32 v60, v63
	v_pk_mul_f32 v[60:61], v[60:61], v[68:69] op_sel_hi:[1,0]
	v_pk_mul_f32 v[70:71], v[78:79], v[70:71]
	v_pk_mul_f32 v[60:61], v[34:35], v[60:61]
	v_pk_mul_f32 v[32:33], v[76:77], v[32:33]
	v_pk_mul_f32 v[84:85], v[28:29], s[66:67] op_sel_hi:[1,0]
	v_pk_mul_f32 v[32:33], v[60:61], v[32:33]
	v_and_b32_sdwa v60, v71, v207 dst_sel:DWORD dst_unused:UNUSED_PAD src0_sel:WORD_1 src1_sel:DWORD
	v_and_b32_sdwa v62, v33, v207 dst_sel:DWORD dst_unused:UNUSED_PAD src0_sel:WORD_1 src1_sel:DWORD
	v_and_b32_sdwa v63, v32, v207 dst_sel:DWORD dst_unused:UNUSED_PAD src0_sel:WORD_1 src1_sel:DWORD
	v_and_b32_sdwa v61, v70, v207 dst_sel:DWORD dst_unused:UNUSED_PAD src0_sel:WORD_1 src1_sel:DWORD
	v_add3_u32 v33, v33, v62, s30
	v_add3_u32 v32, v32, v63, s30
	v_add3_u32 v61, v70, v61, s30
	v_add3_u32 v60, v71, v60, s30
	v_and_b32_e32 v33, 0xffff0000, v33
	v_and_b32_e32 v32, 0xffff0000, v32
	v_or_b32_sdwa v33, v33, v60 dst_sel:DWORD dst_unused:UNUSED_PAD src0_sel:DWORD src1_sel:WORD_1
	v_or_b32_sdwa v32, v32, v61 dst_sel:DWORD dst_unused:UNUSED_PAD src0_sel:DWORD src1_sel:WORD_1
	global_store_dwordx2 v[74:75], v[32:33], off offset:1248
	v_lshl_add_u64 v[32:33], v[148:149], 0, s[6:7]
	v_lshl_add_u64 v[32:33], v[32:33], 0, v[132:133]
	v_lshl_add_u64 v[74:75], v[32:33], 0, s[64:65]
	v_add_co_u32_e32 v32, vcc, s29, v32
	v_pk_mul_f32 v[88:89], v[24:25], s[66:67] op_sel_hi:[1,0]
	s_nop 0
	v_addc_co_u32_e32 v33, vcc, 0, v33, vcc
	global_load_dwordx2 v[78:79], v[74:75], off offset:32 nt
	global_load_dwordx2 v[72:73], v[74:75], off offset:64 nt
	global_load_dwordx2 v[70:71], v[74:75], off offset:96 nt
	global_load_dwordx2 v[68:69], v[74:75], off offset:128 nt
	global_load_dwordx2 v[80:81], v[32:33], off nt
	global_load_dwordx2 v[62:63], v[74:75], off offset:160 nt
	global_load_dwordx2 v[60:61], v[74:75], off offset:192 nt
	s_nop 0
	global_load_dwordx2 v[32:33], v[74:75], off offset:224 nt
	v_pk_mul_f32 v[82:83], v[30:31], s[66:67] op_sel_hi:[1,0]
	v_pk_mul_f32 v[86:87], v[26:27], s[66:67] op_sel_hi:[1,0]
	v_mov_b32_e32 v26, v85
	v_mov_b32_e32 v27, v89
	v_mov_b32_e32 v24, v84
	v_mov_b32_e32 v25, v88
	v_pk_mul_f32 v[26:27], v[26:27], v[26:27]
	v_mov_b32_e32 v28, v83
	v_mov_b32_e32 v29, v87
	v_pk_fma_f32 v[24:25], v[24:25], v[24:25], v[26:27]
	v_mov_b32_e32 v26, v82
	v_mov_b32_e32 v27, v86
	v_pk_mul_f32 v[28:29], v[28:29], v[28:29]
	v_pk_mul_f32 v[74:75], v[14:15], s[66:67] op_sel_hi:[1,0]
	v_pk_mul_f32 v[76:77], v[12:13], s[66:67] op_sel_hi:[1,0]
	v_pk_fma_f32 v[26:27], v[26:27], v[26:27], v[28:29]
	v_pk_mul_f32 v[12:13], v[74:75], v[74:75]
	v_pk_mul_f32 v[14:15], v[76:77], v[76:77]
	v_pk_add_f32 v[90:91], v[24:25], v[26:27]
	v_pk_mov_b32 v[24:25], v[14:15], v[12:13] op_sel:[1,0]
	v_mov_b32_e32 v15, v13
	v_pk_mul_f32 v[26:27], v[4:5], s[66:67] op_sel_hi:[1,0]
	v_pk_add_f32 v[12:13], v[24:25], v[14:15]
	v_pk_mul_f32 v[24:25], v[6:7], s[66:67] op_sel_hi:[1,0]
	v_mul_f32_e32 v6, v26, v26
	v_pk_add_f32 v[4:5], v[90:91], v[90:91] op_sel:[0,1] op_sel_hi:[1,0]
	v_pk_mul_f32 v[30:31], v[8:9], s[66:67] op_sel_hi:[1,0]
	v_mul_f32_e32 v8, v27, v27
	v_mov_b32_e32 v5, v6
	v_pk_add_f32 v[6:7], v[12:13], v[12:13] op_sel:[0,1] op_sel_hi:[1,0]
	v_pk_mul_f32 v[28:29], v[10:11], s[66:67] op_sel_hi:[1,0]
	v_mov_b32_e32 v7, v8
	v_pk_add_f32 v[4:5], v[4:5], v[6:7]
	v_mul_f32_e32 v6, v31, v31
	v_mul_f32_e32 v9, v24, v24
	v_pk_fma_f32 v[6:7], v[30:31], v[30:31], v[6:7] op_sel_hi:[1,1,0]
	v_mul_f32_e32 v8, v29, v29
	v_mul_f32_e32 v10, v25, v25
	v_mov_b32_e32 v7, v9
	v_pk_fma_f32 v[8:9], v[28:29], v[28:29], v[8:9] op_sel_hi:[1,1,0]
	v_pk_mul_f32 v[12:13], v[2:3], s[66:67] op_sel_hi:[1,0]
	v_mov_b32_e32 v9, v10
	v_pk_mul_f32 v[14:15], v[0:1], s[66:67] op_sel_hi:[1,0]
	v_pk_add_f32 v[6:7], v[6:7], v[8:9]
	v_pk_mul_f32 v[0:1], v[12:13], v[12:13]
	v_pk_mul_f32 v[2:3], v[14:15], v[14:15]
	v_pk_add_f32 v[4:5], v[4:5], v[6:7]
	v_pk_mov_b32 v[6:7], v[2:3], v[0:1] op_sel:[1,0]
	v_mov_b32_e32 v3, v1
	v_pk_add_f32 v[10:11], v[6:7], v[2:3]
	v_pk_mul_f32 v[2:3], v[20:21], s[66:67] op_sel_hi:[1,0]
	v_pk_mul_f32 v[8:9], v[16:17], s[66:67] op_sel_hi:[1,0]
	v_mul_f32_e32 v16, v2, v2
	v_mul_f32_e32 v17, v3, v3
	v_pk_add_f32 v[4:5], v[4:5], v[4:5] op_sel:[0,1] op_sel_hi:[1,0]
	v_pk_add_f32 v[10:11], v[10:11], v[10:11] op_sel:[0,1] op_sel_hi:[1,0]
	v_pk_mul_f32 v[6:7], v[18:19], s[66:67] op_sel_hi:[1,0]
	v_mov_b32_e32 v5, v16
	v_mov_b32_e32 v11, v17
	v_pk_mul_f32 v[0:1], v[22:23], s[66:67] op_sel_hi:[1,0]
	v_pk_add_f32 v[4:5], v[4:5], v[10:11]
	v_mul_f32_e32 v10, v9, v9
	v_mul_f32_e32 v16, v7, v7
	v_mul_f32_e32 v18, v0, v0
	v_mul_f32_e32 v19, v1, v1
	v_pk_fma_f32 v[10:11], v[8:9], v[8:9], v[10:11] op_sel_hi:[1,1,0]
	v_pk_fma_f32 v[16:17], v[6:7], v[6:7], v[16:17] op_sel_hi:[1,1,0]
	v_mov_b32_e32 v11, v18
	v_mov_b32_e32 v17, v19
	v_pk_add_f32 v[10:11], v[10:11], v[16:17]
	s_waitcnt vmcnt(0)
; __device__ __forceinline__ unsigned pk2(float lo, float hi) { return f2bf(lo) | (f2bf(hi) << 16); }
; __device__ __forceinline__ float silu_f(float g) { return g * __builtin_amdgcn_rcpf(1.0f + __expf(-g)); }
; __device__ __forceinline__ void gla_out_unit(const bf16* PROJ, const bf16* ST, const float* norm_o, bf16* Y, int unit, int lane) {
;     ...
;         ss += __shfl_xor(ss, 16); ss += __shfl_xor(ss, 32);
;         const float rs = __builtin_amdgcn_rsqf(ss * (1.f / 128.f) + EPS);
;         const size_t tok = (size_t)(tok0 + 16 * ni + fr);
; #pragma unroll
;         for (int mi = 0; mi < 8; ++mi) {
;             const int v = h * 128 + 16 * mi + 4 * fq;
;             const f32x4 no = nov[mi]; const u32x2 g2 = gg1[mi];
;             const f32x4 o = acc[mi][ni];
;             const float y0 = o[0] * rs * no[0] * silu_f(bf_lo(g2.x)), y1 = o[1] * rs * no[1] * silu_f(bf_hi(g2.x));
;             const float y2 = o[2] * rs * no[2] * silu_f(bf_lo(g2.y)), y3 = o[3] * rs * no[3] * silu_f(bf_hi(g2.y));
;             u32x2 w; w.x = pk2(y0, y1); w.y = pk2(y2, y3);
;             *(u32x2*)(Y + tok * D + 512 + v) = w;
;         }
	v_pk_add_f32 v[4:5], v[4:5], v[10:11]
	v_lshlrev_b32_e32 v16, 16, v80
	v_add_f32_e32 v4, v4, v5
	ds_bpermute_b32 v5, v208, v4
	v_and_b32_e32 v18, 0xffff0000, v80
	v_mul_f32_e32 v19, 0xbfb8aa3b, v18
	v_exp_f32_e32 v21, v19
	v_lshlrev_b32_e32 v17, 16, v81
	s_waitcnt lgkmcnt(0)
	v_add_f32_e32 v4, v4, v5
	ds_bpermute_b32 v5, v209, v4
	v_and_b32_e32 v19, 0xffff0000, v81
	v_mov_b32_e32 v80, v84
	v_mov_b32_e32 v81, v82
	v_mov_b32_e32 v82, v85
	s_waitcnt lgkmcnt(0)
	v_add_f32_e32 v4, v4, v5
	v_mul_f32_e32 v5, 0xbfb8aa3b, v16
	v_exp_f32_e32 v5, v5
	v_fmamk_f32 v4, v4, 0x3c000000, v145
	v_rsq_f32_e32 v4, v4
	v_lshlrev_b64 v[10:11], 11, v[146:147]
	v_add_f32_e32 v5, 1.0, v5
	v_rcp_f32_e32 v20, v5
	v_add_f32_e32 v5, 1.0, v21
	v_rcp_f32_e32 v22, v5
	v_mul_f32_e32 v5, 0xbfb8aa3b, v17
	v_exp_f32_e32 v5, v5
	v_lshl_add_u64 v[10:11], v[138:139], 0, v[10:11]
	v_pk_mul_f32 v[80:81], v[80:81], v[4:5] op_sel_hi:[1,0]
	v_add_f32_e32 v5, 1.0, v5
	v_rcp_f32_e32 v21, v5
	v_mul_f32_e32 v5, 0xbfb8aa3b, v19
	v_exp_f32_e32 v5, v5
	v_pk_mul_f32 v[80:81], v[128:129], v[80:81]
	v_pk_mul_f32 v[16:17], v[20:21], v[16:17]
	v_add_f32_e32 v5, 1.0, v5
	v_rcp_f32_e32 v23, v5
	v_pk_mul_f32 v[20:21], v[82:83], v[4:5] op_sel_hi:[1,0]
	v_pk_mul_f32 v[16:17], v[80:81], v[16:17]
	v_pk_mul_f32 v[20:21], v[54:55], v[20:21]
	v_pk_mul_f32 v[18:19], v[22:23], v[18:19]
	v_and_b32_sdwa v5, v17, v207 dst_sel:DWORD dst_unused:UNUSED_PAD src0_sel:WORD_1 src1_sel:DWORD
	v_pk_mul_f32 v[18:19], v[20:21], v[18:19]
	v_and_b32_sdwa v20, v16, v207 dst_sel:DWORD dst_unused:UNUSED_PAD src0_sel:WORD_1 src1_sel:DWORD
	v_add3_u32 v16, v16, v20, s30
	v_add3_u32 v5, v17, v5, s30
	v_and_b32_sdwa v17, v19, v207 dst_sel:DWORD dst_unused:UNUSED_PAD src0_sel:WORD_1 src1_sel:DWORD
	v_and_b32_sdwa v20, v18, v207 dst_sel:DWORD dst_unused:UNUSED_PAD src0_sel:WORD_1 src1_sel:DWORD
	v_add3_u32 v17, v19, v17, s30
	v_add3_u32 v18, v18, v20, s30
	v_and_b32_e32 v17, 0xffff0000, v17
	v_and_b32_e32 v18, 0xffff0000, v18
	v_or_b32_sdwa v17, v17, v5 dst_sel:DWORD dst_unused:UNUSED_PAD src0_sel:DWORD src1_sel:WORD_1
	v_or_b32_sdwa v16, v18, v16 dst_sel:DWORD dst_unused:UNUSED_PAD src0_sel:DWORD src1_sel:WORD_1
	global_store_dwordx2 v[10:11], v[16:17], off offset:1024
	v_lshlrev_b32_e32 v16, 16, v78
	v_mul_f32_e32 v5, 0xbfb8aa3b, v16
	v_and_b32_e32 v18, 0xffff0000, v78
	v_exp_f32_e32 v5, v5
	v_mul_f32_e32 v19, 0xbfb8aa3b, v18
	v_exp_f32_e32 v21, v19
	v_lshlrev_b32_e32 v17, 16, v79
	v_add_f32_e32 v5, 1.0, v5
	v_rcp_f32_e32 v20, v5
	v_add_f32_e32 v5, 1.0, v21
	v_rcp_f32_e32 v22, v5
	v_mul_f32_e32 v5, 0xbfb8aa3b, v17
	v_exp_f32_e32 v5, v5
	v_mov_b32_e32 v54, v88
	v_mov_b32_e32 v55, v86
	v_and_b32_e32 v19, 0xffff0000, v79
	v_pk_mul_f32 v[54:55], v[54:55], v[4:5] op_sel_hi:[1,0]
	v_add_f32_e32 v5, 1.0, v5
	v_rcp_f32_e32 v21, v5
	v_mul_f32_e32 v5, 0xbfb8aa3b, v19
	v_exp_f32_e32 v5, v5
	v_mov_b32_e32 v86, v89
	v_pk_mul_f32 v[52:53], v[52:53], v[54:55]
	v_pk_mul_f32 v[16:17], v[20:21], v[16:17]
	v_add_f32_e32 v5, 1.0, v5
	v_rcp_f32_e32 v23, v5
	v_pk_mul_f32 v[20:21], v[86:87], v[4:5] op_sel_hi:[1,0]
	v_pk_mul_f32 v[16:17], v[52:53], v[16:17]
	v_pk_mul_f32 v[20:21], v[66:67], v[20:21]
	v_pk_mul_f32 v[18:19], v[22:23], v[18:19]
	v_and_b32_sdwa v5, v17, v207 dst_sel:DWORD dst_unused:UNUSED_PAD src0_sel:WORD_1 src1_sel:DWORD
	v_pk_mul_f32 v[18:19], v[20:21], v[18:19]
	v_and_b32_sdwa v20, v16, v207 dst_sel:DWORD dst_unused:UNUSED_PAD src0_sel:WORD_1 src1_sel:DWORD
	v_add3_u32 v16, v16, v20, s30
	v_add3_u32 v5, v17, v5, s30
	v_and_b32_sdwa v17, v19, v207 dst_sel:DWORD dst_unused:UNUSED_PAD src0_sel:WORD_1 src1_sel:DWORD
	v_and_b32_sdwa v20, v18, v207 dst_sel:DWORD dst_unused:UNUSED_PAD src0_sel:WORD_1 src1_sel:DWORD
	v_add3_u32 v17, v19, v17, s30
	v_add3_u32 v18, v18, v20, s30
	v_and_b32_e32 v17, 0xffff0000, v17
	v_and_b32_e32 v18, 0xffff0000, v18
	v_or_b32_sdwa v17, v17, v5 dst_sel:DWORD dst_unused:UNUSED_PAD src0_sel:DWORD src1_sel:WORD_1
	v_or_b32_sdwa v16, v18, v16 dst_sel:DWORD dst_unused:UNUSED_PAD src0_sel:DWORD src1_sel:WORD_1
	global_store_dwordx2 v[10:11], v[16:17], off offset:1056
	v_lshlrev_b32_e32 v16, 16, v72
	v_mul_f32_e32 v5, 0xbfb8aa3b, v16
	v_and_b32_e32 v18, 0xffff0000, v72
	v_exp_f32_e32 v5, v5
	v_mul_f32_e32 v19, 0xbfb8aa3b, v18
	v_exp_f32_e32 v21, v19
	v_lshlrev_b32_e32 v17, 16, v73
	v_add_f32_e32 v5, 1.0, v5
	v_rcp_f32_e32 v20, v5
	v_add_f32_e32 v5, 1.0, v21
	v_rcp_f32_e32 v22, v5
	v_mul_f32_e32 v5, 0xbfb8aa3b, v17
	v_exp_f32_e32 v5, v5
	v_mov_b32_e32 v52, v76
	v_mov_b32_e32 v53, v74
	v_and_b32_e32 v19, 0xffff0000, v73
	v_pk_mul_f32 v[52:53], v[52:53], v[4:5] op_sel_hi:[1,0]
	v_add_f32_e32 v5, 1.0, v5
	v_rcp_f32_e32 v21, v5
	v_mul_f32_e32 v5, 0xbfb8aa3b, v19
	v_exp_f32_e32 v5, v5
	v_mov_b32_e32 v74, v77
	v_pk_mul_f32 v[52:53], v[64:65], v[52:53]
	v_pk_mul_f32 v[16:17], v[20:21], v[16:17]
	v_add_f32_e32 v5, 1.0, v5
	v_rcp_f32_e32 v23, v5
	v_pk_mul_f32 v[20:21], v[74:75], v[4:5] op_sel_hi:[1,0]
	v_pk_mul_f32 v[16:17], v[52:53], v[16:17]
	v_pk_mul_f32 v[20:21], v[58:59], v[20:21]
	v_pk_mul_f32 v[18:19], v[22:23], v[18:19]
	v_and_b32_sdwa v5, v17, v207 dst_sel:DWORD dst_unused:UNUSED_PAD src0_sel:WORD_1 src1_sel:DWORD
	v_pk_mul_f32 v[18:19], v[20:21], v[18:19]
	v_and_b32_sdwa v20, v16, v207 dst_sel:DWORD dst_unused:UNUSED_PAD src0_sel:WORD_1 src1_sel:DWORD
	v_add3_u32 v16, v16, v20, s30
	v_add3_u32 v5, v17, v5, s30
	v_and_b32_sdwa v17, v19, v207 dst_sel:DWORD dst_unused:UNUSED_PAD src0_sel:WORD_1 src1_sel:DWORD
	v_and_b32_sdwa v20, v18, v207 dst_sel:DWORD dst_unused:UNUSED_PAD src0_sel:WORD_1 src1_sel:DWORD
	v_add3_u32 v17, v19, v17, s30
	v_add3_u32 v18, v18, v20, s30
	v_and_b32_e32 v17, 0xffff0000, v17
; __device__ __forceinline__ unsigned pk2(float lo, float hi) { return f2bf(lo) | (f2bf(hi) << 16); }
; __device__ __forceinline__ float silu_f(float g) { return g * __builtin_amdgcn_rcpf(1.0f + __expf(-g)); }
; __device__ __forceinline__ void gla_out_unit(const bf16* PROJ, const bf16* ST, const float* norm_o, bf16* Y, int unit, int lane) {
;     ...
; #pragma unroll
;         for (int mi = 0; mi < 8; ++mi) {
;             const int v = h * 128 + 16 * mi + 4 * fq;
;             const f32x4 no = nov[mi]; const u32x2 g2 = gg1[mi];
;             const f32x4 o = acc[mi][ni];
;             const float y0 = o[0] * rs * no[0] * silu_f(bf_lo(g2.x)), y1 = o[1] * rs * no[1] * silu_f(bf_hi(g2.x));
;             const float y2 = o[2] * rs * no[2] * silu_f(bf_lo(g2.y)), y3 = o[3] * rs * no[3] * silu_f(bf_hi(g2.y));
;             u32x2 w; w.x = pk2(y0, y1); w.y = pk2(y2, y3);
;             *(u32x2*)(Y + tok * D + 512 + v) = w;
;         }
	v_and_b32_e32 v18, 0xffff0000, v18
	v_or_b32_sdwa v17, v17, v5 dst_sel:DWORD dst_unused:UNUSED_PAD src0_sel:DWORD src1_sel:WORD_1
	v_or_b32_sdwa v16, v18, v16 dst_sel:DWORD dst_unused:UNUSED_PAD src0_sel:DWORD src1_sel:WORD_1
	global_store_dwordx2 v[10:11], v[16:17], off offset:1088
	v_lshlrev_b32_e32 v16, 16, v70
	v_mul_f32_e32 v5, 0xbfb8aa3b, v16
	v_and_b32_e32 v18, 0xffff0000, v70
	v_exp_f32_e32 v5, v5
	v_mul_f32_e32 v19, 0xbfb8aa3b, v18
	v_exp_f32_e32 v21, v19
	v_lshlrev_b32_e32 v17, 16, v71
	v_add_f32_e32 v5, 1.0, v5
	v_rcp_f32_e32 v20, v5
	v_add_f32_e32 v5, 1.0, v21
	v_rcp_f32_e32 v22, v5
	v_mul_f32_e32 v5, 0xbfb8aa3b, v17
	v_exp_f32_e32 v5, v5
	v_mov_b32_e32 v52, v30
	v_mov_b32_e32 v53, v28
	v_and_b32_e32 v19, 0xffff0000, v71
	v_pk_mul_f32 v[52:53], v[52:53], v[4:5] op_sel_hi:[1,0]
	v_add_f32_e32 v5, 1.0, v5
	v_rcp_f32_e32 v21, v5
	v_mul_f32_e32 v5, 0xbfb8aa3b, v19
	v_exp_f32_e32 v5, v5
	v_mov_b32_e32 v28, v31
	v_pk_mul_f32 v[52:53], v[56:57], v[52:53]
	v_pk_mul_f32 v[16:17], v[20:21], v[16:17]
	v_add_f32_e32 v5, 1.0, v5
	v_rcp_f32_e32 v23, v5
	v_pk_mul_f32 v[20:21], v[28:29], v[4:5] op_sel_hi:[1,0]
	v_pk_mul_f32 v[16:17], v[52:53], v[16:17]
	v_pk_mul_f32 v[20:21], v[50:51], v[20:21]
	v_pk_mul_f32 v[18:19], v[22:23], v[18:19]
	v_and_b32_sdwa v5, v17, v207 dst_sel:DWORD dst_unused:UNUSED_PAD src0_sel:WORD_1 src1_sel:DWORD
	v_pk_mul_f32 v[18:19], v[20:21], v[18:19]
	v_and_b32_sdwa v20, v16, v207 dst_sel:DWORD dst_unused:UNUSED_PAD src0_sel:WORD_1 src1_sel:DWORD
	v_add3_u32 v16, v16, v20, s30
	v_add3_u32 v5, v17, v5, s30
	v_and_b32_sdwa v17, v19, v207 dst_sel:DWORD dst_unused:UNUSED_PAD src0_sel:WORD_1 src1_sel:DWORD
	v_and_b32_sdwa v20, v18, v207 dst_sel:DWORD dst_unused:UNUSED_PAD src0_sel:WORD_1 src1_sel:DWORD
	v_add3_u32 v17, v19, v17, s30
	v_add3_u32 v18, v18, v20, s30
	v_and_b32_e32 v17, 0xffff0000, v17
	v_and_b32_e32 v18, 0xffff0000, v18
	v_or_b32_sdwa v17, v17, v5 dst_sel:DWORD dst_unused:UNUSED_PAD src0_sel:DWORD src1_sel:WORD_1
	v_or_b32_sdwa v16, v18, v16 dst_sel:DWORD dst_unused:UNUSED_PAD src0_sel:DWORD src1_sel:WORD_1
	global_store_dwordx2 v[10:11], v[16:17], off offset:1120
	v_lshlrev_b32_e32 v16, 16, v68
	v_mul_f32_e32 v5, 0xbfb8aa3b, v16
	v_and_b32_e32 v18, 0xffff0000, v68
	v_exp_f32_e32 v5, v5
	v_mul_f32_e32 v19, 0xbfb8aa3b, v18
	v_exp_f32_e32 v21, v19
	v_lshlrev_b32_e32 v17, 16, v69
	v_add_f32_e32 v5, 1.0, v5
	v_rcp_f32_e32 v20, v5
	v_add_f32_e32 v5, 1.0, v21
	v_rcp_f32_e32 v22, v5
	v_mul_f32_e32 v5, 0xbfb8aa3b, v17
	v_exp_f32_e32 v5, v5
	v_mov_b32_e32 v28, v26
	v_mov_b32_e32 v29, v24
	v_and_b32_e32 v19, 0xffff0000, v69
	v_pk_mul_f32 v[28:29], v[28:29], v[4:5] op_sel_hi:[1,0]
	v_add_f32_e32 v5, 1.0, v5
	v_rcp_f32_e32 v21, v5
	v_mul_f32_e32 v5, 0xbfb8aa3b, v19
	v_exp_f32_e32 v5, v5
	v_mov_b32_e32 v24, v27
	v_pk_mul_f32 v[28:29], v[48:49], v[28:29]
	v_pk_mul_f32 v[16:17], v[20:21], v[16:17]
	v_add_f32_e32 v5, 1.0, v5
	v_rcp_f32_e32 v23, v5
	v_pk_mul_f32 v[20:21], v[24:25], v[4:5] op_sel_hi:[1,0]
	v_pk_mul_f32 v[16:17], v[28:29], v[16:17]
	v_pk_mul_f32 v[20:21], v[46:47], v[20:21]
	v_pk_mul_f32 v[18:19], v[22:23], v[18:19]
	v_and_b32_sdwa v5, v17, v207 dst_sel:DWORD dst_unused:UNUSED_PAD src0_sel:WORD_1 src1_sel:DWORD
	v_pk_mul_f32 v[18:19], v[20:21], v[18:19]
	v_and_b32_sdwa v20, v16, v207 dst_sel:DWORD dst_unused:UNUSED_PAD src0_sel:WORD_1 src1_sel:DWORD
	v_add3_u32 v16, v16, v20, s30
	v_add3_u32 v5, v17, v5, s30
	v_and_b32_sdwa v17, v19, v207 dst_sel:DWORD dst_unused:UNUSED_PAD src0_sel:WORD_1 src1_sel:DWORD
	v_and_b32_sdwa v20, v18, v207 dst_sel:DWORD dst_unused:UNUSED_PAD src0_sel:WORD_1 src1_sel:DWORD
	v_add3_u32 v17, v19, v17, s30
	v_add3_u32 v18, v18, v20, s30
	v_and_b32_e32 v17, 0xffff0000, v17
	v_and_b32_e32 v18, 0xffff0000, v18
	v_or_b32_sdwa v17, v17, v5 dst_sel:DWORD dst_unused:UNUSED_PAD src0_sel:DWORD src1_sel:WORD_1
	v_or_b32_sdwa v16, v18, v16 dst_sel:DWORD dst_unused:UNUSED_PAD src0_sel:DWORD src1_sel:WORD_1
	global_store_dwordx2 v[10:11], v[16:17], off offset:1152
	v_lshlrev_b32_e32 v16, 16, v62
	v_mul_f32_e32 v5, 0xbfb8aa3b, v16
	v_and_b32_e32 v18, 0xffff0000, v62
	v_exp_f32_e32 v5, v5
	v_mul_f32_e32 v19, 0xbfb8aa3b, v18
	v_exp_f32_e32 v21, v19
	v_lshlrev_b32_e32 v17, 16, v63
	v_add_f32_e32 v5, 1.0, v5
	v_rcp_f32_e32 v20, v5
	v_add_f32_e32 v5, 1.0, v21
	v_rcp_f32_e32 v22, v5
	v_mul_f32_e32 v5, 0xbfb8aa3b, v17
	v_exp_f32_e32 v5, v5
	v_mov_b32_e32 v24, v14
	v_mov_b32_e32 v25, v12
	v_and_b32_e32 v19, 0xffff0000, v63
	v_pk_mul_f32 v[24:25], v[24:25], v[4:5] op_sel_hi:[1,0]
	v_add_f32_e32 v5, 1.0, v5
	v_rcp_f32_e32 v21, v5
	v_mul_f32_e32 v5, 0xbfb8aa3b, v19
	v_exp_f32_e32 v5, v5
	v_mov_b32_e32 v12, v15
	v_pk_mul_f32 v[24:25], v[44:45], v[24:25]
	v_pk_mul_f32 v[16:17], v[20:21], v[16:17]
; __device__ __forceinline__ unsigned pk2(float lo, float hi) { return f2bf(lo) | (f2bf(hi) << 16); }
; __device__ __forceinline__ float silu_f(float g) { return g * __builtin_amdgcn_rcpf(1.0f + __expf(-g)); }
; __device__ __forceinline__ void gla_out_unit(const bf16* PROJ, const bf16* ST, const float* norm_o, bf16* Y, int unit, int lane) {
;     ...
; #pragma unroll
;         for (int mi = 0; mi < 8; ++mi) {
;             const int v = h * 128 + 16 * mi + 4 * fq;
;             const f32x4 no = nov[mi]; const u32x2 g2 = gg1[mi];
;             const f32x4 o = acc[mi][ni];
;             const float y0 = o[0] * rs * no[0] * silu_f(bf_lo(g2.x)), y1 = o[1] * rs * no[1] * silu_f(bf_hi(g2.x));
;             const float y2 = o[2] * rs * no[2] * silu_f(bf_lo(g2.y)), y3 = o[3] * rs * no[3] * silu_f(bf_hi(g2.y));
;             u32x2 w; w.x = pk2(y0, y1); w.y = pk2(y2, y3);
;             *(u32x2*)(Y + tok * D + 512 + v) = w;
;         }
	v_add_f32_e32 v5, 1.0, v5
	v_rcp_f32_e32 v23, v5
	v_pk_mul_f32 v[12:13], v[12:13], v[4:5] op_sel_hi:[1,0]
	v_pk_mul_f32 v[16:17], v[24:25], v[16:17]
	v_pk_mul_f32 v[12:13], v[42:43], v[12:13]
	v_pk_mul_f32 v[14:15], v[22:23], v[18:19]
	v_and_b32_sdwa v5, v17, v207 dst_sel:DWORD dst_unused:UNUSED_PAD src0_sel:WORD_1 src1_sel:DWORD
	v_pk_mul_f32 v[12:13], v[12:13], v[14:15]
	v_and_b32_sdwa v14, v16, v207 dst_sel:DWORD dst_unused:UNUSED_PAD src0_sel:WORD_1 src1_sel:DWORD
	v_add3_u32 v14, v16, v14, s30
	v_and_b32_sdwa v15, v13, v207 dst_sel:DWORD dst_unused:UNUSED_PAD src0_sel:WORD_1 src1_sel:DWORD
	v_and_b32_sdwa v16, v12, v207 dst_sel:DWORD dst_unused:UNUSED_PAD src0_sel:WORD_1 src1_sel:DWORD
	v_add3_u32 v13, v13, v15, s30
	v_add3_u32 v12, v12, v16, s30
	v_add3_u32 v5, v17, v5, s30
	v_and_b32_e32 v13, 0xffff0000, v13
	v_and_b32_e32 v12, 0xffff0000, v12
	v_or_b32_sdwa v13, v13, v5 dst_sel:DWORD dst_unused:UNUSED_PAD src0_sel:DWORD src1_sel:WORD_1
	v_or_b32_sdwa v12, v12, v14 dst_sel:DWORD dst_unused:UNUSED_PAD src0_sel:DWORD src1_sel:WORD_1
	global_store_dwordx2 v[10:11], v[12:13], off offset:1184
	v_lshlrev_b32_e32 v12, 16, v60
	v_mul_f32_e32 v5, 0xbfb8aa3b, v12
	v_and_b32_e32 v14, 0xffff0000, v60
	v_exp_f32_e32 v5, v5
	v_mul_f32_e32 v15, 0xbfb8aa3b, v14
	v_exp_f32_e32 v17, v15
	v_lshlrev_b32_e32 v13, 16, v61
	v_add_f32_e32 v5, 1.0, v5
	v_rcp_f32_e32 v16, v5
	v_add_f32_e32 v5, 1.0, v17
	v_rcp_f32_e32 v18, v5
	v_mul_f32_e32 v5, 0xbfb8aa3b, v13
	v_exp_f32_e32 v5, v5
	v_mov_b32_e32 v20, v8
	v_mov_b32_e32 v21, v6
	v_and_b32_e32 v15, 0xffff0000, v61
	v_pk_mul_f32 v[20:21], v[20:21], v[4:5] op_sel_hi:[1,0]
	v_add_f32_e32 v5, 1.0, v5
	v_rcp_f32_e32 v17, v5
	v_mul_f32_e32 v5, 0xbfb8aa3b, v15
	v_exp_f32_e32 v5, v5
	v_mov_b32_e32 v6, v9
	v_pk_mul_f32 v[20:21], v[40:41], v[20:21]
	v_pk_mul_f32 v[12:13], v[16:17], v[12:13]
	v_add_f32_e32 v5, 1.0, v5
	v_rcp_f32_e32 v19, v5
	v_pk_mul_f32 v[6:7], v[6:7], v[4:5] op_sel_hi:[1,0]
	v_pk_mul_f32 v[12:13], v[20:21], v[12:13]
	v_pk_mul_f32 v[6:7], v[38:39], v[6:7]
	v_pk_mul_f32 v[8:9], v[18:19], v[14:15]
	v_and_b32_sdwa v5, v13, v207 dst_sel:DWORD dst_unused:UNUSED_PAD src0_sel:WORD_1 src1_sel:DWORD
	v_pk_mul_f32 v[6:7], v[6:7], v[8:9]
	v_and_b32_sdwa v8, v12, v207 dst_sel:DWORD dst_unused:UNUSED_PAD src0_sel:WORD_1 src1_sel:DWORD
	v_add3_u32 v8, v12, v8, s30
	v_and_b32_sdwa v9, v7, v207 dst_sel:DWORD dst_unused:UNUSED_PAD src0_sel:WORD_1 src1_sel:DWORD
	v_and_b32_sdwa v12, v6, v207 dst_sel:DWORD dst_unused:UNUSED_PAD src0_sel:WORD_1 src1_sel:DWORD
	v_add3_u32 v7, v7, v9, s30
	v_add3_u32 v6, v6, v12, s30
	v_add3_u32 v5, v13, v5, s30
	v_and_b32_e32 v7, 0xffff0000, v7
	v_and_b32_e32 v6, 0xffff0000, v6
	v_or_b32_sdwa v7, v7, v5 dst_sel:DWORD dst_unused:UNUSED_PAD src0_sel:DWORD src1_sel:WORD_1
	v_or_b32_sdwa v6, v6, v8 dst_sel:DWORD dst_unused:UNUSED_PAD src0_sel:DWORD src1_sel:WORD_1
	global_store_dwordx2 v[10:11], v[6:7], off offset:1216
	v_lshlrev_b32_e32 v6, 16, v32
	v_mul_f32_e32 v5, 0xbfb8aa3b, v6
	v_and_b32_e32 v8, 0xffff0000, v32
	v_exp_f32_e32 v5, v5
	v_mul_f32_e32 v9, 0xbfb8aa3b, v8
	v_exp_f32_e32 v13, v9
	v_lshlrev_b32_e32 v7, 16, v33
	v_add_f32_e32 v5, 1.0, v5
	v_rcp_f32_e32 v12, v5
	v_add_f32_e32 v5, 1.0, v13
	v_rcp_f32_e32 v14, v5
	v_mul_f32_e32 v5, 0xbfb8aa3b, v7
	v_exp_f32_e32 v5, v5
	v_and_b32_e32 v9, 0xffff0000, v33
	v_mov_b32_e32 v17, v0
	v_mov_b32_e32 v16, v2
	v_add_f32_e32 v0, 1.0, v5
	v_rcp_f32_e32 v13, v0
	v_mul_f32_e32 v0, 0xbfb8aa3b, v9
	v_exp_f32_e32 v0, v0
	v_pk_mul_f32 v[16:17], v[16:17], v[4:5] op_sel_hi:[1,0]
	v_pk_mul_f32 v[6:7], v[12:13], v[6:7]
	v_pk_mul_f32 v[16:17], v[36:37], v[16:17]
	v_add_f32_e32 v0, 1.0, v0
	v_rcp_f32_e32 v15, v0
	v_mov_b32_e32 v0, v3
	v_pk_mul_f32 v[0:1], v[0:1], v[4:5] op_sel_hi:[1,0]
	v_pk_mul_f32 v[6:7], v[16:17], v[6:7]
	v_pk_mul_f32 v[0:1], v[34:35], v[0:1]
	v_pk_mul_f32 v[2:3], v[14:15], v[8:9]
	s_nop 0
	v_pk_mul_f32 v[0:1], v[0:1], v[2:3]
	v_and_b32_sdwa v2, v7, v207 dst_sel:DWORD dst_unused:UNUSED_PAD src0_sel:WORD_1 src1_sel:DWORD
	v_and_b32_sdwa v4, v1, v207 dst_sel:DWORD dst_unused:UNUSED_PAD src0_sel:WORD_1 src1_sel:DWORD
	v_and_b32_sdwa v5, v0, v207 dst_sel:DWORD dst_unused:UNUSED_PAD src0_sel:WORD_1 src1_sel:DWORD
	v_and_b32_sdwa v3, v6, v207 dst_sel:DWORD dst_unused:UNUSED_PAD src0_sel:WORD_1 src1_sel:DWORD
	v_add3_u32 v1, v1, v4, s30
	v_add3_u32 v0, v0, v5, s30
	v_add3_u32 v3, v6, v3, s30
	v_add3_u32 v2, v7, v2, s30
	v_and_b32_e32 v1, 0xffff0000, v1
	v_and_b32_e32 v0, 0xffff0000, v0
	v_or_b32_sdwa v1, v1, v2 dst_sel:DWORD dst_unused:UNUSED_PAD src0_sel:DWORD src1_sel:WORD_1
	v_or_b32_sdwa v0, v0, v3 dst_sel:DWORD dst_unused:UNUSED_PAD src0_sel:DWORD src1_sel:WORD_1
	global_store_dwordx2 v[10:11], v[0:1], off offset:1248
	s_cbranch_scc1 .LBB0_522

; __device__ __forceinline__ unsigned pk2(float lo, float hi) { return f2bf(lo) | (f2bf(hi) << 16); }
; __device__ __forceinline__ void gla_scan(const float* UPD, const float* DEC, bf16* ST, int gtid, int gthreads) {
;     for (int p = gtid; p < 4 * 128 * 16; p += gthreads) {
;         const int h = p >> 11, rem = p & 2047, v = rem >> 4, kq = rem & 15;
;         f32x4 s = (f32x4){0.f, 0.f, 0.f, 0.f};
; #pragma unroll 1
;         for (int c0 = 0; c0 < 64; c0 += 16) {
;             f32x4 dv[16], uv[16];
; #pragma unroll
;             for (int i = 0; i < 16; ++i) { const size_t unit = (size_t)((c0 + i) * 4 + h); dv[i] = *(const f32x4*)(DEC + unit * 64 + 4 * kq); uv[i] = *(const f32x4*)(UPD + unit * 8192 + v * 64 + 4 * kq); }
;             asm volatile("" : "+v"(dv[0]), "+v"(dv[1]), "+v"(dv[2]), "+v"(dv[3]), "+v"(dv[4]), "+v"(dv[5]), "+v"(dv[6]), "+v"(dv[7]) :: "memory");
;             asm volatile("" : "+v"(dv[8]), "+v"(dv[9]), "+v"(dv[10]), "+v"(dv[11]), "+v"(dv[12]), "+v"(dv[13]), "+v"(dv[14]), "+v"(dv[15]) :: "memory");
;             asm volatile("" : "+v"(uv[0]), "+v"(uv[1]), "+v"(uv[2]), "+v"(uv[3]), "+v"(uv[4]), "+v"(uv[5]), "+v"(uv[6]), "+v"(uv[7]) :: "memory");
;             asm volatile("" : "+v"(uv[8]), "+v"(uv[9]), "+v"(uv[10]), "+v"(uv[11]), "+v"(uv[12]), "+v"(uv[13]), "+v"(uv[14]), "+v"(uv[15]) :: "memory");
; #pragma unroll
;             for (int i = 0; i < 16; ++i) {
;                 const size_t unit = (size_t)((c0 + i) * 4 + h);
;                 s = dv[i] * s + uv[i];
;                 u32x2 w; w.x = pk2(s[0], s[1]); w.y = pk2(s[2], s[3]);
;                 *(u32x2*)(ST + unit * 8192 + v * 64 + 4 * kq) = w;
;             }
.LBB0_1106:
	v_lshl_add_u64 v[26:27], s[34:35], 0, v[18:19]
	v_add_co_u32_e32 v0, vcc, 0x401000, v26
	v_lshl_add_u64 v[24:25], s[34:35], 0, v[16:17]
	s_nop 0
	v_addc_co_u32_e32 v1, vcc, 0, v27, vcc
	v_add_co_u32_e32 v2, vcc, 0x400000, v26
	global_load_dwordx4 v[48:51], v[0:1], off offset:3072
	global_load_dwordx4 v[52:55], v[0:1], off offset:2048
	global_load_dwordx4 v[56:59], v[0:1], off offset:1024
	global_load_dwordx4 v[60:63], v[0:1], off
	v_addc_co_u32_e32 v3, vcc, 0, v27, vcc
	v_add_co_u32_e32 v80, vcc, 0x403000, v26
	global_load_dwordx4 v[64:67], v[2:3], off offset:3072
	global_load_dwordx4 v[68:71], v[2:3], off offset:2048
	global_load_dwordx4 v[72:75], v[2:3], off offset:1024
	global_load_dwordx4 v[76:79], v[2:3], off
	v_addc_co_u32_e32 v81, vcc, 0, v27, vcc
	v_add_co_u32_e32 v26, vcc, 0x402000, v26
	global_load_dwordx4 v[0:3], v[80:81], off offset:3072
	global_load_dwordx4 v[4:7], v[80:81], off offset:2048
	global_load_dwordx4 v[8:11], v[80:81], off offset:1024
	s_nop 0
	global_load_dwordx4 v[80:83], v[80:81], off
	v_addc_co_u32_e32 v27, vcc, 0, v27, vcc
	v_add_co_u32_e32 v100, vcc, 0x190e0000, v24
	global_load_dwordx4 v[84:87], v[26:27], off offset:3072
	global_load_dwordx4 v[88:91], v[26:27], off offset:2048
	global_load_dwordx4 v[92:95], v[26:27], off offset:1024
	global_load_dwordx4 v[96:99], v[26:27], off
	v_addc_co_u32_e32 v101, vcc, 0, v25, vcc
	v_add_co_u32_e32 v26, vcc, 0x190c0000, v24
	v_lshl_add_u64 v[28:29], s[34:35], 0, v[14:15]
	s_nop 0
	v_addc_co_u32_e32 v27, vcc, 0, v25, vcc
	v_add_co_u32_e32 v108, vcc, 0x190a0000, v24
	global_load_dwordx4 v[100:103], v[100:101], off nt
	s_nop 0
	global_load_dwordx4 v[104:107], v[26:27], off nt
	v_addc_co_u32_e32 v109, vcc, 0, v25, vcc
	v_add_co_u32_e32 v26, vcc, 0x19080000, v24
	v_add_co_u32_e64 v162, s[0:1], s29, v28
	s_nop 0
	v_addc_co_u32_e32 v27, vcc, 0, v25, vcc
	v_add_co_u32_e32 v116, vcc, 0x19060000, v24
	global_load_dwordx4 v[108:111], v[108:109], off nt
	s_nop 0
	global_load_dwordx4 v[112:115], v[26:27], off nt
	v_addc_co_u32_e32 v117, vcc, 0, v25, vcc
	v_add_co_u32_e32 v26, vcc, 0x19040000, v24
	v_addc_co_u32_e64 v163, s[0:1], 0, v29, s[0:1]
	s_nop 0
	v_addc_co_u32_e32 v27, vcc, 0, v25, vcc
	v_add_co_u32_e32 v124, vcc, 0x19020000, v24
	global_load_dwordx4 v[116:119], v[116:117], off nt
	s_nop 0
	global_load_dwordx4 v[120:123], v[26:27], off nt
	v_addc_co_u32_e32 v125, vcc, 0, v25, vcc
	v_add_co_u32_e32 v26, vcc, 0x19000000, v24
	v_add_co_u32_e64 v164, s[0:1], s30, v28
	s_nop 0
	v_addc_co_u32_e32 v27, vcc, 0, v25, vcc
	v_add_co_u32_e32 v132, vcc, 0x191e0000, v24
	global_load_dwordx4 v[124:127], v[124:125], off nt
	s_nop 0
	global_load_dwordx4 v[128:131], v[26:27], off nt
	v_addc_co_u32_e32 v133, vcc, 0, v25, vcc
	v_add_co_u32_e32 v26, vcc, 0x191c0000, v24
	v_addc_co_u32_e64 v165, s[0:1], 0, v29, s[0:1]
	s_nop 0
	v_addc_co_u32_e32 v27, vcc, 0, v25, vcc
	v_add_co_u32_e32 v140, vcc, 0x191a0000, v24
	global_load_dwordx4 v[132:135], v[132:133], off nt
	s_nop 0
	global_load_dwordx4 v[136:139], v[26:27], off nt
	v_addc_co_u32_e32 v141, vcc, 0, v25, vcc
	v_add_co_u32_e32 v26, vcc, 0x19180000, v24
	v_add_co_u32_e64 v166, s[0:1], s31, v28
	s_nop 0
	v_addc_co_u32_e32 v27, vcc, 0, v25, vcc
	v_add_co_u32_e32 v150, vcc, 0x19160000, v24
	global_load_dwordx4 v[140:143], v[140:141], off nt
	s_nop 0
	global_load_dwordx4 v[146:149], v[26:27], off nt
	v_addc_co_u32_e32 v151, vcc, 0, v25, vcc
	v_add_co_u32_e32 v26, vcc, 0x19140000, v24
	v_addc_co_u32_e64 v167, s[0:1], 0, v29, s[0:1]
	s_nop 0
	v_addc_co_u32_e32 v27, vcc, 0, v25, vcc
	v_add_co_u32_e32 v158, vcc, 0x19120000, v24
	global_load_dwordx4 v[150:153], v[150:151], off nt
	s_nop 0
	global_load_dwordx4 v[154:157], v[26:27], off nt
	v_addc_co_u32_e32 v159, vcc, 0, v25, vcc
	v_add_co_u32_e32 v160, vcc, 0x19100000, v24
	v_add_co_u32_e64 v168, s[0:1], s37, v28
	s_nop 0
	v_addc_co_u32_e32 v161, vcc, 0, v25, vcc
	global_load_dwordx4 v[24:27], v[158:159], off nt
	s_nop 0
	global_load_dwordx4 v[158:161], v[160:161], off nt
	v_addc_co_u32_e64 v169, s[0:1], 0, v29, s[0:1]
	v_add_co_u32_e64 v170, s[0:1], s39, v28
	s_waitcnt vmcnt(24)
	s_waitcnt vmcnt(16)
	s_waitcnt vmcnt(8)
	v_addc_co_u32_e64 v171, s[0:1], 0, v29, s[0:1]
	v_add_co_u32_e64 v172, s[0:1], s46, v28
	v_pk_fma_f32 v[22:23], v[22:23], v[78:79], v[130:131]
	s_nop 0
	v_addc_co_u32_e64 v173, s[0:1], 0, v29, s[0:1]
	v_pk_fma_f32 v[20:21], v[20:21], v[76:77], v[128:129]
	v_add_co_u32_e64 v174, s[0:1], s47, v28
	v_bfe_u32 v12, v20, 16, 1
	v_bfe_u32 v47, v21, 16, 1
	v_bfe_u32 v76, v22, 16, 1
	v_bfe_u32 v77, v23, 16, 1
	v_pk_fma_f32 v[74:75], v[74:75], v[22:23], v[126:127]
	v_pk_fma_f32 v[72:73], v[72:73], v[20:21], v[124:125]
	v_addc_co_u32_e64 v175, s[0:1], 0, v29, s[0:1]
	v_add3_u32 v12, v20, v12, s21
	v_add3_u32 v47, v21, v47, s21
	v_add3_u32 v76, v22, v76, s21
	v_add3_u32 v77, v23, v77, s21
	v_bfe_u32 v78, v72, 16, 1
	v_bfe_u32 v79, v73, 16, 1
	v_bfe_u32 v124, v74, 16, 1
	v_bfe_u32 v125, v75, 16, 1
	v_pk_fma_f32 v[20:21], v[70:71], v[74:75], v[122:123]
	v_pk_fma_f32 v[22:23], v[68:69], v[72:73], v[120:121]
	v_add_co_u32_e64 v44, s[0:1], s48, v28
	v_lshrrev_b32_e32 v12, 16, v12
	v_lshrrev_b32_e32 v69, 16, v76
	v_add3_u32 v70, v72, v78, s21
	v_add3_u32 v71, v73, v79, s21
	v_add3_u32 v72, v74, v124, s21
	v_add3_u32 v73, v75, v125, s21
	v_bfe_u32 v74, v22, 16, 1
	v_bfe_u32 v75, v23, 16, 1
	v_bfe_u32 v76, v20, 16, 1
	v_bfe_u32 v78, v21, 16, 1
	v_pk_fma_f32 v[66:67], v[66:67], v[20:21], v[118:119]
	v_pk_fma_f32 v[64:65], v[64:65], v[22:23], v[116:117]
	v_addc_co_u32_e64 v45, s[0:1], 0, v29, s[0:1]
	v_and_or_b32 v68, v47, s28, v12
	v_and_or_b32 v69, v77, s28, v69
	v_lshrrev_b32_e32 v12, 16, v70
	v_lshrrev_b32_e32 v47, 16, v72
	v_add3_u32 v70, v22, v74, s21
	v_add3_u32 v72, v23, v75, s21
	v_add3_u32 v74, v20, v76, s21
	v_add3_u32 v75, v21, v78, s21
	v_bfe_u32 v76, v64, 16, 1
	v_bfe_u32 v77, v65, 16, 1
	v_bfe_u32 v78, v66, 16, 1
	v_bfe_u32 v79, v67, 16, 1
	v_pk_fma_f32 v[20:21], v[62:63], v[66:67], v[114:115]
	v_pk_fma_f32 v[22:23], v[60:61], v[64:65], v[112:113]
	v_add_co_u32_e64 v42, s[0:1], s49, v28
	s_waitcnt vmcnt(0)
; __device__ __forceinline__ unsigned pk2(float lo, float hi) { return f2bf(lo) | (f2bf(hi) << 16); }
; __device__ __forceinline__ void gla_scan(const float* UPD, const float* DEC, bf16* ST, int gtid, int gthreads) {
;     ...
;             for (int i = 0; i < 16; ++i) {
;                 const size_t unit = (size_t)((c0 + i) * 4 + h);
;                 s = dv[i] * s + uv[i];
;                 u32x2 w; w.x = pk2(s[0], s[1]); w.y = pk2(s[2], s[3]);
;                 *(u32x2*)(ST + unit * 8192 + v * 64 + 4 * kq) = w;
;             }
	global_store_dwordx2 v[162:163], v[68:69], off
	v_and_or_b32 v60, v71, s28, v12
	v_and_or_b32 v61, v73, s28, v47
	v_lshrrev_b32_e32 v12, 16, v70
	v_lshrrev_b32_e32 v47, 16, v74
	v_add3_u32 v62, v64, v76, s21
	v_add3_u32 v63, v65, v77, s21
	v_add3_u32 v64, v66, v78, s21
	v_add3_u32 v65, v67, v79, s21
	v_bfe_u32 v66, v22, 16, 1
	v_bfe_u32 v67, v23, 16, 1
	v_bfe_u32 v68, v20, 16, 1
	v_bfe_u32 v69, v21, 16, 1
	v_pk_fma_f32 v[58:59], v[58:59], v[20:21], v[110:111]
	v_pk_fma_f32 v[56:57], v[56:57], v[22:23], v[108:109]
	v_addc_co_u32_e64 v43, s[0:1], 0, v29, s[0:1]
	global_store_dwordx2 v[164:165], v[60:61], off
	v_and_or_b32 v60, v72, s28, v12
	v_and_or_b32 v61, v75, s28, v47
	v_lshrrev_b32_e32 v12, 16, v62
	v_lshrrev_b32_e32 v47, 16, v64
	v_add3_u32 v62, v22, v66, s21
	v_add3_u32 v64, v23, v67, s21
	v_add3_u32 v66, v20, v68, s21
	v_add3_u32 v67, v21, v69, s21
	v_bfe_u32 v68, v56, 16, 1
	v_bfe_u32 v69, v57, 16, 1
	v_bfe_u32 v70, v58, 16, 1
	v_bfe_u32 v71, v59, 16, 1
	v_pk_fma_f32 v[20:21], v[54:55], v[58:59], v[106:107]
	v_pk_fma_f32 v[22:23], v[52:53], v[56:57], v[104:105]
	v_add_co_u32_e64 v40, s[0:1], s56, v28
	global_store_dwordx2 v[166:167], v[60:61], off
	v_and_or_b32 v52, v63, s28, v12
	v_and_or_b32 v53, v65, s28, v47
	v_lshrrev_b32_e32 v12, 16, v62
	v_lshrrev_b32_e32 v47, 16, v66
	v_add3_u32 v54, v56, v68, s21
	v_add3_u32 v55, v57, v69, s21
	v_add3_u32 v56, v58, v70, s21
	v_add3_u32 v57, v59, v71, s21
	v_bfe_u32 v58, v22, 16, 1
	v_bfe_u32 v59, v23, 16, 1
	v_bfe_u32 v60, v20, 16, 1
	v_bfe_u32 v61, v21, 16, 1
	v_pk_fma_f32 v[50:51], v[50:51], v[20:21], v[102:103]
	v_pk_fma_f32 v[48:49], v[48:49], v[22:23], v[100:101]
	v_addc_co_u32_e64 v41, s[0:1], 0, v29, s[0:1]
	global_store_dwordx2 v[168:169], v[52:53], off
	v_and_or_b32 v52, v64, s28, v12
	v_and_or_b32 v53, v67, s28, v47
	v_lshrrev_b32_e32 v12, 16, v54
	v_lshrrev_b32_e32 v47, 16, v56
	v_add3_u32 v54, v22, v58, s21
	v_add3_u32 v56, v23, v59, s21
	v_add3_u32 v58, v20, v60, s21
	v_add3_u32 v59, v21, v61, s21
	v_bfe_u32 v60, v48, 16, 1
	v_bfe_u32 v61, v49, 16, 1
	v_bfe_u32 v62, v50, 16, 1
	v_pk_fma_f32 v[20:21], v[98:99], v[50:51], v[160:161]
	v_pk_fma_f32 v[22:23], v[96:97], v[48:49], v[158:159]
	v_add_co_u32_e64 v38, s[0:1], s57, v28
	v_bfe_u32 v63, v51, 16, 1
	global_store_dwordx2 v[170:171], v[52:53], off
	v_and_or_b32 v52, v55, s28, v12
	v_and_or_b32 v53, v57, s28, v47
	v_lshrrev_b32_e32 v12, 16, v54
	v_lshrrev_b32_e32 v47, 16, v58
	v_add3_u32 v54, v48, v60, s21
	v_add3_u32 v55, v49, v61, s21
	v_add3_u32 v50, v50, v62, s21
	v_bfe_u32 v57, v22, 16, 1
	v_bfe_u32 v58, v23, 16, 1
	v_bfe_u32 v60, v20, 16, 1
	v_bfe_u32 v61, v21, 16, 1
	v_pk_fma_f32 v[26:27], v[94:95], v[20:21], v[26:27]
	v_pk_fma_f32 v[24:25], v[92:93], v[22:23], v[24:25]
	v_addc_co_u32_e64 v39, s[0:1], 0, v29, s[0:1]
	v_add3_u32 v51, v51, v63, s21
	global_store_dwordx2 v[172:173], v[52:53], off
	v_and_or_b32 v48, v56, s28, v12
	v_and_or_b32 v49, v59, s28, v47
	v_lshrrev_b32_e32 v12, 16, v54
	v_lshrrev_b32_e32 v47, 16, v50
	v_add3_u32 v50, v22, v57, s21
	v_add3_u32 v52, v23, v58, s21
	v_add3_u32 v53, v20, v60, s21
	v_add3_u32 v54, v21, v61, s21
	v_bfe_u32 v56, v24, 16, 1
	v_bfe_u32 v57, v25, 16, 1
	v_bfe_u32 v58, v26, 16, 1
	v_bfe_u32 v59, v27, 16, 1
	v_pk_fma_f32 v[20:21], v[90:91], v[26:27], v[156:157]
	v_pk_fma_f32 v[22:23], v[88:89], v[24:25], v[154:155]
	v_add_co_u32_e64 v36, s[0:1], s58, v28
	global_store_dwordx2 v[174:175], v[48:49], off
	v_and_or_b32 v48, v55, s28, v12
	v_and_or_b32 v49, v51, s28, v47
	v_lshrrev_b32_e32 v12, 16, v50
	v_lshrrev_b32_e32 v47, 16, v53
	v_add3_u32 v50, v24, v56, s21
	v_add3_u32 v51, v25, v57, s21
	v_add3_u32 v53, v26, v58, s21
	v_add3_u32 v55, v27, v59, s21
	v_bfe_u32 v56, v22, 16, 1
	v_bfe_u32 v57, v23, 16, 1
	v_bfe_u32 v58, v20, 16, 1
	v_bfe_u32 v59, v21, 16, 1
	v_pk_fma_f32 v[24:25], v[86:87], v[20:21], v[152:153]
; __device__ __forceinline__ unsigned pk2(float lo, float hi) { return f2bf(lo) | (f2bf(hi) << 16); }
; __device__ __forceinline__ void gla_scan(const float* UPD, const float* DEC, bf16* ST, int gtid, int gthreads) {
;     for (int p = gtid; p < 4 * 128 * 16; p += gthreads) {
;         const int h = p >> 11, rem = p & 2047, v = rem >> 4, kq = rem & 15;
;         f32x4 s = (f32x4){0.f, 0.f, 0.f, 0.f};
; #pragma unroll 1
;         for (int c0 = 0; c0 < 64; c0 += 16) {
;             f32x4 dv[16], uv[16];
; #pragma unroll
;             for (int i = 0; i < 16; ++i) { const size_t unit = (size_t)((c0 + i) * 4 + h); dv[i] = *(const f32x4*)(DEC + unit * 64 + 4 * kq); uv[i] = *(const f32x4*)(UPD + unit * 8192 + v * 64 + 4 * kq); }
;             asm volatile("" : "+v"(dv[0]), "+v"(dv[1]), "+v"(dv[2]), "+v"(dv[3]), "+v"(dv[4]), "+v"(dv[5]), "+v"(dv[6]), "+v"(dv[7]) :: "memory");
;             asm volatile("" : "+v"(dv[8]), "+v"(dv[9]), "+v"(dv[10]), "+v"(dv[11]), "+v"(dv[12]), "+v"(dv[13]), "+v"(dv[14]), "+v"(dv[15]) :: "memory");
;             asm volatile("" : "+v"(uv[0]), "+v"(uv[1]), "+v"(uv[2]), "+v"(uv[3]), "+v"(uv[4]), "+v"(uv[5]), "+v"(uv[6]), "+v"(uv[7]) :: "memory");
;             asm volatile("" : "+v"(uv[8]), "+v"(uv[9]), "+v"(uv[10]), "+v"(uv[11]), "+v"(uv[12]), "+v"(uv[13]), "+v"(uv[14]), "+v"(uv[15]) :: "memory");
; #pragma unroll
;             for (int i = 0; i < 16; ++i) {
;                 const size_t unit = (size_t)((c0 + i) * 4 + h);
;                 s = dv[i] * s + uv[i];
;                 u32x2 w; w.x = pk2(s[0], s[1]); w.y = pk2(s[2], s[3]);
;                 *(u32x2*)(ST + unit * 8192 + v * 64 + 4 * kq) = w;
;             }
	v_pk_fma_f32 v[26:27], v[84:85], v[22:23], v[150:151]
	v_addc_co_u32_e64 v37, s[0:1], 0, v29, s[0:1]
	global_store_dwordx2 v[44:45], v[48:49], off
	v_and_or_b32 v44, v52, s28, v12
	v_and_or_b32 v45, v54, s28, v47
	v_lshrrev_b32_e32 v12, 16, v50
	v_lshrrev_b32_e32 v47, 16, v53
	v_add3_u32 v48, v22, v56, s21
	v_add3_u32 v49, v23, v57, s21
	v_add3_u32 v50, v20, v58, s21
	v_add3_u32 v52, v21, v59, s21
	v_bfe_u32 v53, v26, 16, 1
	v_bfe_u32 v56, v24, 16, 1
	v_pk_fma_f32 v[20:21], v[82:83], v[24:25], v[148:149]
	v_pk_fma_f32 v[22:23], v[80:81], v[26:27], v[146:147]
	v_add_co_u32_e64 v34, s[0:1], s59, v28
	v_bfe_u32 v54, v27, 16, 1
	v_bfe_u32 v57, v25, 16, 1
	global_store_dwordx2 v[42:43], v[44:45], off
	v_and_or_b32 v42, v51, s28, v12
	v_and_or_b32 v43, v55, s28, v47
	v_lshrrev_b32_e32 v12, 16, v48
	v_lshrrev_b32_e32 v44, 16, v50
	v_add3_u32 v26, v26, v53, s21
	v_add3_u32 v45, v24, v56, s21
	v_bfe_u32 v48, v22, 16, 1
	v_bfe_u32 v50, v23, 16, 1
	v_bfe_u32 v51, v20, 16, 1
	v_bfe_u32 v53, v21, 16, 1
	v_pk_fma_f32 v[10:11], v[10:11], v[20:21], v[142:143]
	v_pk_fma_f32 v[8:9], v[8:9], v[22:23], v[140:141]
	v_addc_co_u32_e64 v35, s[0:1], 0, v29, s[0:1]
	v_add3_u32 v27, v27, v54, s21
	v_add3_u32 v47, v25, v57, s21
	global_store_dwordx2 v[40:41], v[42:43], off
	v_and_or_b32 v24, v49, s28, v12
	v_and_or_b32 v25, v52, s28, v44
	v_lshrrev_b32_e32 v12, 16, v26
	v_lshrrev_b32_e32 v26, 16, v45
	v_add3_u32 v22, v22, v48, s21
	v_add3_u32 v40, v23, v50, s21
	v_add3_u32 v20, v20, v51, s21
	v_add3_u32 v41, v21, v53, s21
	v_bfe_u32 v21, v8, 16, 1
	v_bfe_u32 v23, v9, 16, 1
	v_bfe_u32 v42, v10, 16, 1
	v_pk_fma_f32 v[6:7], v[6:7], v[10:11], v[138:139]
	v_pk_fma_f32 v[4:5], v[4:5], v[8:9], v[136:137]
	v_add_co_u32_e64 v32, s[0:1], s64, v28
	v_bfe_u32 v43, v11, 16, 1
	global_store_dwordx2 v[38:39], v[24:25], off
	v_and_or_b32 v24, v27, s28, v12
	v_and_or_b32 v25, v47, s28, v26
	v_lshrrev_b32_e32 v12, 16, v22
	v_lshrrev_b32_e32 v26, 16, v20
	v_add3_u32 v8, v8, v21, s21
	v_add3_u32 v9, v9, v23, s21
	v_add3_u32 v10, v10, v42, s21
	v_bfe_u32 v27, v4, 16, 1
	v_bfe_u32 v39, v6, 16, 1
	v_pk_fma_f32 v[22:23], v[2:3], v[6:7], v[134:135]
	v_pk_fma_f32 v[20:21], v[0:1], v[4:5], v[132:133]
	v_addc_co_u32_e64 v33, s[0:1], 0, v29, s[0:1]
	v_add3_u32 v11, v11, v43, s21
	v_bfe_u32 v38, v5, 16, 1
	v_bfe_u32 v42, v7, 16, 1
	v_and_or_b32 v0, v40, s28, v12
	v_and_or_b32 v1, v41, s28, v26
	v_lshrrev_b32_e32 v2, 16, v8
	v_lshrrev_b32_e32 v3, 16, v10
	v_add3_u32 v4, v4, v27, s21
	v_add3_u32 v6, v6, v39, s21
	v_bfe_u32 v8, v20, 16, 1
	v_bfe_u32 v12, v22, 16, 1
	v_add_co_u32_e64 v30, s[0:1], s65, v28
	global_store_dwordx2 v[36:37], v[24:25], off
	v_add3_u32 v5, v5, v38, s21
	v_add3_u32 v7, v7, v42, s21
	v_bfe_u32 v10, v21, 16, 1
	v_bfe_u32 v24, v23, 16, 1
	global_store_dwordx2 v[34:35], v[0:1], off
	v_and_or_b32 v0, v9, s28, v2
	v_and_or_b32 v1, v11, s28, v3
	v_lshrrev_b32_e32 v2, 16, v4
	v_lshrrev_b32_e32 v3, 16, v6
	v_add3_u32 v4, v20, v8, s21
	v_add3_u32 v8, v22, v12, s21
	s_add_i32 s67, s67, 16
	v_addc_co_u32_e64 v31, s[0:1], 0, v29, s[0:1]
	v_add_co_u32_e32 v28, vcc, 0x1d0f0000, v28
	v_add3_u32 v6, v21, v10, s21
	v_add3_u32 v9, v23, v24, s21
	global_store_dwordx2 v[32:33], v[0:1], off
	v_and_or_b32 v0, v5, s28, v2
	v_and_or_b32 v1, v7, s28, v3
	v_lshrrev_b32_e32 v2, 16, v4
	v_lshrrev_b32_e32 v3, 16, v8
	v_lshl_add_u64 v[14:15], v[14:15], 0, s[12:13]
	v_lshl_add_u64 v[16:17], v[16:17], 0, s[14:15]
	v_lshl_add_u64 v[18:19], v[18:19], 0, s[16:17]
	s_cmp_gt_u32 s67, 47
	v_addc_co_u32_e32 v29, vcc, 0, v29, vcc
	global_store_dwordx2 v[30:31], v[0:1], off
	v_and_or_b32 v0, v6, s28, v2
	v_and_or_b32 v1, v9, s28, v3
	global_store_dwordx2 v[28:29], v[0:1], off
	s_cbranch_scc0 .LBB0_1106
	v_add_u32_e32 v203, s11, v203
	v_cmp_lt_i32_e32 vcc, s66, v203
	s_or_b64 s[6:7], vcc, s[6:7]
	v_add_u32_e32 v46, s20, v46
	s_andn2_b64 exec, exec, s[6:7]
	s_cbranch_execnz .LBB0_1105

; __device__ __forceinline__ void gla_out_unit(const bf16* PROJ, const bf16* ST, const float* norm_o, bf16* Y, int unit, int lane) {
;     ...
;     for (int ki = 0; ki < 2; ++ki) {
;         bf16x8 bq[4], as[8];
; #pragma unroll
;         for (int ni = 0; ni < 4; ++ni) bq[ni] = *(const bf16x8*)(PROJ + (size_t)(tok0 + 16 * ni + fr) * NPROJ + 1024 + h * 64 + 32 * ki + 8 * fq);
; #pragma unroll
;         for (int mi = 0; mi < 8; ++mi) as[mi] = *(const bf16x8*)(st + (16 * mi + fr) * 64 + 32 * ki + 8 * fq);
;         asm volatile("" : "+v"(as[0]), "+v"(as[1]), "+v"(as[2]), "+v"(as[3]), "+v"(as[4]), "+v"(as[5]), "+v"(as[6]), "+v"(as[7]), "+v"(bq[0]), "+v"(bq[1]), "+v"(bq[2]), "+v"(bq[3]));
; #pragma unroll
;         for (int mi = 0; mi < 8; ++mi)
; #pragma unroll
;             for (int ni = 0; ni < 4; ++ni) acc[mi][ni] = __builtin_amdgcn_mfma_f32_16x16x32_bf16(as[mi], bq[ni], acc[mi][ni], 0, 0, 0);
;     }
;     f32x4 nov[8];
; #pragma unroll
;     for (int mi = 0; mi < 8; ++mi) nov[mi] = *(const f32x4*)(norm_o + h * 128 + 16 * mi + 4 * fq);
; #pragma unroll
;     for (int ni = 0; ni < 4; ++ni) {
;         u32x2 gg1[8];
; #pragma unroll
;         for (int mi = 0; mi < 8; ++mi) gg1[mi] = *(const u32x2*)(PROJ + (size_t)(tok0 + 16 * ni + fr) * NPROJ + 2048 + h * 128 + 16 * mi + 4 * fq);
;         asm volatile("" : "+v"(gg1[0]), "+v"(gg1[1]), "+v"(gg1[2]), "+v"(gg1[3]), "+v"(gg1[4]), "+v"(gg1[5]), "+v"(gg1[6]), "+v"(gg1[7]));
;         float ss = 0.f;
; #pragma unroll
;         for (int mi = 0; mi < 8; ++mi) { acc[mi][ni] = acc[mi][ni] * 0.125f; const f32x4 o = acc[mi][ni]; ss += (o[0] * o[0] + o[1] * o[1]) + (o[2] * o[2] + o[3] * o[3]); }
.LBB0_1156:
	s_lshl_b64 s[18:19], s[18:19], 1
	v_lshl_add_u64 v[170:171], v[164:165], 0, s[18:19]
	v_add_co_u32_e32 v194, vcc, s20, v170
	v_lshl_add_u64 v[186:187], v[52:53], 0, s[18:19]
	s_nop 0
	v_addc_co_u32_e32 v195, vcc, 0, v171, vcc
	v_add_co_u32_e32 v210, vcc, s21, v170
	v_lshl_add_u64 v[182:183], v[54:55], 0, s[18:19]
	s_nop 0
	v_addc_co_u32_e32 v211, vcc, 0, v171, vcc
	v_add_co_u32_e32 v218, vcc, s28, v170
	v_lshl_add_u64 v[178:179], v[160:161], 0, s[18:19]
	v_lshl_add_u64 v[174:175], v[162:163], 0, s[18:19]
	v_addc_co_u32_e32 v219, vcc, 0, v171, vcc
	global_load_dwordx4 v[166:169], v[170:171], off offset:2048 nt
	s_nop 0
	global_load_dwordx4 v[170:173], v[170:171], off nt
	s_nop 0
	global_load_dwordx4 v[174:177], v[174:175], off offset:2048 nt
	s_nop 0
	global_load_dwordx4 v[178:181], v[178:179], off offset:2048 nt
	s_nop 0
	global_load_dwordx4 v[182:185], v[182:183], off offset:2048 nt
	s_nop 0
	global_load_dwordx4 v[186:189], v[186:187], off offset:2048 nt
	s_nop 0
	global_load_dwordx4 v[190:193], v[194:195], off offset:2048 nt
	s_nop 0
	global_load_dwordx4 v[194:197], v[194:195], off nt
	s_nop 0
	global_load_dwordx4 v[206:209], v[210:211], off offset:2048 nt
	s_nop 0
	global_load_dwordx4 v[210:213], v[210:211], off nt
	s_nop 0
	global_load_dwordx4 v[214:217], v[218:219], off offset:2048 nt
	s_nop 0
	global_load_dwordx4 v[218:221], v[218:219], off nt
	s_mov_b64 s[18:19], 32
	s_and_b64 vcc, exec, s[16:17]
	s_mov_b64 s[16:17], 0
	s_waitcnt vmcnt(0)
	s_nop 0
	v_mfma_f32_16x16x32_bf16 v[128:131], v[170:173], v[186:189], v[128:131]
	v_mfma_f32_16x16x32_bf16 v[124:127], v[170:173], v[182:185], v[124:127]
	v_mfma_f32_16x16x32_bf16 v[92:95], v[170:173], v[178:181], v[92:95]
	v_mfma_f32_16x16x32_bf16 v[28:31], v[170:173], v[174:177], v[28:31]
	v_mfma_f32_16x16x32_bf16 v[64:67], v[166:169], v[186:189], v[64:67]
	v_mfma_f32_16x16x32_bf16 v[120:123], v[166:169], v[182:185], v[120:123]
	v_mfma_f32_16x16x32_bf16 v[88:91], v[166:169], v[178:181], v[88:91]
	v_mfma_f32_16x16x32_bf16 v[24:27], v[166:169], v[174:177], v[24:27]
	v_mfma_f32_16x16x32_bf16 v[56:59], v[218:221], v[186:189], v[56:59]
	v_mfma_f32_16x16x32_bf16 v[112:115], v[218:221], v[182:185], v[112:115]
	v_mfma_f32_16x16x32_bf16 v[80:83], v[218:221], v[178:181], v[80:83]
	v_mfma_f32_16x16x32_bf16 v[12:15], v[218:221], v[174:177], v[12:15]
	v_mfma_f32_16x16x32_bf16 v[40:43], v[214:217], v[186:189], v[40:43]
	v_mfma_f32_16x16x32_bf16 v[104:107], v[214:217], v[182:185], v[104:107]
	v_mfma_f32_16x16x32_bf16 v[72:75], v[214:217], v[178:181], v[72:75]
	v_mfma_f32_16x16x32_bf16 v[8:11], v[214:217], v[174:177], v[8:11]
	v_mfma_f32_16x16x32_bf16 v[36:39], v[210:213], v[186:189], v[36:39]
	v_mfma_f32_16x16x32_bf16 v[100:103], v[210:213], v[182:185], v[100:103]
	v_mfma_f32_16x16x32_bf16 v[68:71], v[210:213], v[178:181], v[68:71]
	v_mfma_f32_16x16x32_bf16 v[4:7], v[210:213], v[174:177], v[4:7]
	v_mfma_f32_16x16x32_bf16 v[32:35], v[206:209], v[186:189], v[32:35]
	v_mfma_f32_16x16x32_bf16 v[96:99], v[206:209], v[182:185], v[96:99]
	v_mfma_f32_16x16x32_bf16 v[60:63], v[206:209], v[178:181], v[60:63]
	v_mfma_f32_16x16x32_bf16 v[0:3], v[206:209], v[174:177], v[0:3]
	v_mfma_f32_16x16x32_bf16 v[44:47], v[194:197], v[186:189], v[44:47]
	v_mfma_f32_16x16x32_bf16 v[108:111], v[194:197], v[182:185], v[108:111]
	v_mfma_f32_16x16x32_bf16 v[76:79], v[194:197], v[178:181], v[76:79]
	v_mfma_f32_16x16x32_bf16 v[16:19], v[194:197], v[174:177], v[16:19]
	v_mfma_f32_16x16x32_bf16 v[48:51], v[190:193], v[186:189], v[48:51]
	v_mfma_f32_16x16x32_bf16 v[116:119], v[190:193], v[182:185], v[116:119]
	v_mfma_f32_16x16x32_bf16 v[84:87], v[190:193], v[178:181], v[84:87]
	v_mfma_f32_16x16x32_bf16 v[20:23], v[190:193], v[174:177], v[20:23]
	s_cbranch_vccnz .LBB0_1156
	v_lshl_add_u64 v[158:159], v[158:159], 0, s[4:5]
	v_lshl_add_u64 v[158:159], v[158:159], 0, v[144:145]
	v_lshl_add_u64 v[160:161], v[158:159], 0, s[6:7]
	v_add_co_u32_e32 v158, vcc, 0x1000, v158
	global_load_dwordx4 v[52:55], v[134:135], off offset:2048 nt
	s_nop 0
	v_addc_co_u32_e32 v159, vcc, 0, v159, vcc
	global_load_dwordx2 v[208:209], v[160:161], off offset:32 nt
	global_load_dwordx2 v[188:189], v[160:161], off offset:64 nt
	global_load_dwordx2 v[182:183], v[160:161], off offset:96 nt
	global_load_dwordx2 v[176:177], v[160:161], off offset:128 nt
	global_load_dwordx2 v[210:211], v[158:159], off nt
	global_load_dwordx2 v[170:171], v[160:161], off offset:160 nt
	global_load_dwordx2 v[162:163], v[160:161], off offset:192 nt
	s_nop 0
	global_load_dwordx2 v[158:159], v[160:161], off offset:224 nt
	v_pk_mul_f32 v[214:215], v[128:129], s[12:13] op_sel_hi:[1,0]
	v_pk_mul_f32 v[196:197], v[64:65], s[12:13] op_sel_hi:[1,0]
	v_pk_mul_f32 v[212:213], v[130:131], s[12:13] op_sel_hi:[1,0]
	v_pk_mul_f32 v[194:195], v[66:67], s[12:13] op_sel_hi:[1,0]
	v_mov_b32_e32 v66, v215
	v_mov_b32_e32 v67, v197
	v_mov_b32_e32 v64, v214
	v_mov_b32_e32 v65, v196
	v_pk_mul_f32 v[66:67], v[66:67], v[66:67]
	v_mov_b32_e32 v128, v213
	v_mov_b32_e32 v129, v195
	v_pk_fma_f32 v[64:65], v[64:65], v[64:65], v[66:67]
	v_mov_b32_e32 v66, v212
	v_mov_b32_e32 v67, v194
	v_pk_mul_f32 v[128:129], v[128:129], v[128:129]
	v_pk_mul_f32 v[190:191], v[58:59], s[12:13] op_sel_hi:[1,0]
	v_pk_mul_f32 v[192:193], v[56:57], s[12:13] op_sel_hi:[1,0]
	v_pk_fma_f32 v[66:67], v[66:67], v[66:67], v[128:129]
	v_pk_mul_f32 v[56:57], v[190:191], v[190:191]
	v_pk_mul_f32 v[58:59], v[192:193], v[192:193]
	v_pk_add_f32 v[64:65], v[64:65], v[66:67]
	v_pk_mov_b32 v[66:67], v[58:59], v[56:57] op_sel:[1,0]
	v_mov_b32_e32 v59, v57
	v_pk_mul_f32 v[180:181], v[36:37], s[12:13] op_sel_hi:[1,0]
	v_pk_add_f32 v[56:57], v[66:67], v[58:59]
; __device__ __forceinline__ unsigned pk2(float lo, float hi) { return f2bf(lo) | (f2bf(hi) << 16); }
; __device__ __forceinline__ float silu_f(float g) { return g * __builtin_amdgcn_rcpf(1.0f + __expf(-g)); }
; __device__ __forceinline__ void gla_out_unit(const bf16* PROJ, const bf16* ST, const float* norm_o, bf16* Y, int unit, int lane) {
;     ...
;     f32x4 nov[8];
; #pragma unroll
;     for (int mi = 0; mi < 8; ++mi) nov[mi] = *(const f32x4*)(norm_o + h * 128 + 16 * mi + 4 * fq);
; #pragma unroll
;     for (int ni = 0; ni < 4; ++ni) {
;         u32x2 gg1[8];
; #pragma unroll
;         for (int mi = 0; mi < 8; ++mi) gg1[mi] = *(const u32x2*)(PROJ + (size_t)(tok0 + 16 * ni + fr) * NPROJ + 2048 + h * 128 + 16 * mi + 4 * fq);
;         asm volatile("" : "+v"(gg1[0]), "+v"(gg1[1]), "+v"(gg1[2]), "+v"(gg1[3]), "+v"(gg1[4]), "+v"(gg1[5]), "+v"(gg1[6]), "+v"(gg1[7]));
;         float ss = 0.f;
; #pragma unroll
;         for (int mi = 0; mi < 8; ++mi) { acc[mi][ni] = acc[mi][ni] * 0.125f; const f32x4 o = acc[mi][ni]; ss += (o[0] * o[0] + o[1] * o[1]) + (o[2] * o[2] + o[3] * o[3]); }
;         ss += __shfl_xor(ss, 16); ss += __shfl_xor(ss, 32);
;         const float rs = __builtin_amdgcn_rsqf(ss * (1.f / 128.f) + EPS);
;         const size_t tok = (size_t)(tok0 + 16 * ni + fr);
; #pragma unroll
;         for (int mi = 0; mi < 8; ++mi) {
;             const int v = h * 128 + 16 * mi + 4 * fq;
;             const f32x4 no = nov[mi]; const u32x2 g2 = gg1[mi];
;             const f32x4 o = acc[mi][ni];
;             const float y0 = o[0] * rs * no[0] * silu_f(bf_lo(g2.x)), y1 = o[1] * rs * no[1] * silu_f(bf_hi(g2.x));
;             const float y2 = o[2] * rs * no[2] * silu_f(bf_lo(g2.y)), y3 = o[3] * rs * no[3] * silu_f(bf_hi(g2.y));
;             u32x2 w; w.x = pk2(y0, y1); w.y = pk2(y2, y3);
;             *(u32x2*)(Y + tok * D + 512 + v) = w;
;         }
	v_pk_mul_f32 v[178:179], v[38:39], s[12:13] op_sel_hi:[1,0]
	v_mul_f32_e32 v38, v180, v180
	v_pk_add_f32 v[36:37], v[64:65], v[64:65] op_sel:[0,1] op_sel_hi:[1,0]
	v_pk_mul_f32 v[130:131], v[50:51], s[12:13] op_sel_hi:[1,0]
	v_mov_b32_e32 v37, v38
	v_pk_add_f32 v[38:39], v[56:57], v[56:57] op_sel:[0,1] op_sel_hi:[1,0]
	v_pk_mul_f32 v[160:161], v[48:49], s[12:13] op_sel_hi:[1,0]
	global_load_dwordx4 v[64:67], v[134:135], off offset:2112 nt
	global_load_dwordx4 v[56:59], v[134:135], off offset:2176 nt
	global_load_dwordx4 v[48:51], v[134:135], off offset:2240 nt
	v_pk_mul_f32 v[186:187], v[40:41], s[12:13] op_sel_hi:[1,0]
	v_mul_f32_e32 v40, v181, v181
	v_mov_b32_e32 v39, v40
	v_pk_mul_f32 v[184:185], v[42:43], s[12:13] op_sel_hi:[1,0]
	v_pk_add_f32 v[36:37], v[36:37], v[38:39]
	v_mul_f32_e32 v38, v187, v187
	v_mul_f32_e32 v41, v178, v178
	v_pk_fma_f32 v[38:39], v[186:187], v[186:187], v[38:39] op_sel_hi:[1,1,0]
	v_mul_f32_e32 v40, v185, v185
	v_mul_f32_e32 v42, v179, v179
	v_mov_b32_e32 v39, v41
	v_pk_fma_f32 v[40:41], v[184:185], v[184:185], v[40:41] op_sel_hi:[1,1,0]
	v_pk_mul_f32 v[172:173], v[34:35], s[12:13] op_sel_hi:[1,0]
	v_mov_b32_e32 v41, v42
	v_pk_mul_f32 v[174:175], v[32:33], s[12:13] op_sel_hi:[1,0]
	v_pk_add_f32 v[38:39], v[38:39], v[40:41]
	v_pk_mul_f32 v[32:33], v[172:173], v[172:173]
	v_pk_mul_f32 v[34:35], v[174:175], v[174:175]
	v_pk_add_f32 v[36:37], v[36:37], v[38:39]
	v_pk_mov_b32 v[38:39], v[34:35], v[32:33] op_sel:[1,0]
	v_mov_b32_e32 v35, v33
	v_pk_add_f32 v[32:33], v[38:39], v[34:35]
	v_mul_f32_e32 v38, v160, v160
	v_mul_f32_e32 v39, v161, v161
	v_pk_add_f32 v[34:35], v[36:37], v[36:37] op_sel:[0,1] op_sel_hi:[1,0]
	v_pk_add_f32 v[32:33], v[32:33], v[32:33] op_sel:[0,1] op_sel_hi:[1,0]
	v_pk_mul_f32 v[166:167], v[46:47], s[12:13] op_sel_hi:[1,0]
	v_pk_mul_f32 v[168:169], v[44:45], s[12:13] op_sel_hi:[1,0]
	v_mov_b32_e32 v35, v38
	v_mov_b32_e32 v33, v39
	v_pk_add_f32 v[32:33], v[34:35], v[32:33]
	v_mul_f32_e32 v34, v169, v169
	v_mul_f32_e32 v36, v167, v167
	v_mul_f32_e32 v40, v130, v130
	v_mul_f32_e32 v41, v131, v131
	v_pk_fma_f32 v[34:35], v[168:169], v[168:169], v[34:35] op_sel_hi:[1,1,0]
	v_pk_fma_f32 v[36:37], v[166:167], v[166:167], v[36:37] op_sel_hi:[1,1,0]
	v_mov_b32_e32 v35, v40
	v_mov_b32_e32 v37, v41
	v_pk_add_f32 v[34:35], v[34:35], v[36:37]
	v_lshlrev_b64 v[156:157], 11, v[156:157]
	v_pk_add_f32 v[32:33], v[32:33], v[34:35]
	v_and_b32_e32 v34, 64, v203
	v_add_f32_e32 v32, v32, v33
	v_xor_b32_e32 v33, 16, v203
	v_add_u32_e32 v34, 64, v34
	v_cmp_lt_i32_e32 vcc, v33, v34
	v_lshl_add_u64 v[156:157], v[136:137], 0, v[156:157]
	s_add_i32 s14, s14, s36
	v_cndmask_b32_e32 v33, v203, v33, vcc
	v_lshlrev_b32_e32 v205, 2, v33
	ds_bpermute_b32 v33, v205, v32
	s_cmpk_lt_i32 s14, 0x100
	s_waitcnt lgkmcnt(0)
	v_add_f32_e32 v128, v32, v33
	v_xor_b32_e32 v32, 32, v203
	v_cmp_lt_i32_e32 vcc, v32, v34
	s_nop 1
	v_cndmask_b32_e32 v32, v203, v32, vcc
	v_lshlrev_b32_e32 v206, 2, v32
	ds_bpermute_b32 v129, v206, v128
	global_load_dwordx4 v[44:47], v[134:135], off offset:2304 nt
	global_load_dwordx4 v[40:43], v[134:135], off offset:2368 nt
	global_load_dwordx4 v[36:39], v[134:135], off offset:2432 nt
	global_load_dwordx4 v[32:35], v[134:135], off offset:2496 nt
	s_waitcnt vmcnt(7)
	s_waitcnt lgkmcnt(0)
	v_add_f32_e32 v128, v128, v129
	v_fmamk_f32 v128, v128, 0x3c000000, v199
	v_lshlrev_b32_e32 v216, 16, v210
	v_rsq_f32_e32 v164, v128
	v_mul_f32_e32 v128, 0xbfb8aa3b, v216
	v_and_b32_e32 v210, 0xffff0000, v210
	v_exp_f32_e32 v128, v128
	v_mul_f32_e32 v129, 0xbfb8aa3b, v210
	v_lshlrev_b32_e32 v217, 16, v211
	v_exp_f32_e32 v129, v129
	v_mul_f32_e32 v165, 0xbfb8aa3b, v217
	v_exp_f32_e32 v165, v165
	v_add_f32_e32 v128, 1.0, v128
	v_rcp_f32_e32 v218, v128
	v_add_f32_e32 v128, 1.0, v129
	v_rcp_f32_e32 v220, v128
	v_mov_b32_e32 v128, v214
	v_mov_b32_e32 v129, v212
	v_and_b32_e32 v211, 0xffff0000, v211
	v_pk_mul_f32 v[222:223], v[128:129], v[164:165] op_sel_hi:[1,0]
	v_mov_b32_e32 v128, v52
	v_add_f32_e32 v52, 1.0, v165
	v_rcp_f32_e32 v219, v52
	v_mul_f32_e32 v52, 0xbfb8aa3b, v211
	v_exp_f32_e32 v52, v52
	v_mov_b32_e32 v212, v215
	v_mov_b32_e32 v129, v54
	v_pk_mul_f32 v[212:213], v[212:213], v[164:165] op_sel_hi:[1,0]
	v_add_f32_e32 v52, 1.0, v52
	v_rcp_f32_e32 v221, v52
	v_mov_b32_e32 v54, v53
	v_pk_mul_f32 v[52:53], v[54:55], v[212:213]
	v_pk_mul_f32 v[222:223], v[128:129], v[222:223]
	v_pk_mul_f32 v[210:211], v[220:221], v[210:211]
	v_pk_mul_f32 v[216:217], v[218:219], v[216:217]
	v_pk_mul_f32 v[52:53], v[210:211], v[52:53]
	v_pk_mul_f32 v[216:217], v[216:217], v[222:223]
	v_and_b32_sdwa v210, v53, v204 dst_sel:DWORD dst_unused:UNUSED_PAD src0_sel:WORD_1 src1_sel:DWORD
	v_and_b32_sdwa v211, v52, v204 dst_sel:DWORD dst_unused:UNUSED_PAD src0_sel:WORD_1 src1_sel:DWORD
	v_and_b32_sdwa v165, v217, v204 dst_sel:DWORD dst_unused:UNUSED_PAD src0_sel:WORD_1 src1_sel:DWORD
	v_and_b32_sdwa v207, v216, v204 dst_sel:DWORD dst_unused:UNUSED_PAD src0_sel:WORD_1 src1_sel:DWORD
	v_add3_u32 v53, v53, v210, s29
	v_add3_u32 v52, v52, v211, s29
	v_add3_u32 v207, v216, v207, s29
	v_add3_u32 v165, v217, v165, s29
	v_and_b32_e32 v53, 0xffff0000, v53
	v_and_b32_e32 v52, 0xffff0000, v52
	v_or_b32_sdwa v53, v53, v165 dst_sel:DWORD dst_unused:UNUSED_PAD src0_sel:DWORD src1_sel:WORD_1
	v_or_b32_sdwa v52, v52, v207 dst_sel:DWORD dst_unused:UNUSED_PAD src0_sel:DWORD src1_sel:WORD_1
	v_lshlrev_b32_e32 v210, 16, v208
	global_store_dwordx2 v[156:157], v[52:53], off offset:1024
	v_mul_f32_e32 v52, 0xbfb8aa3b, v210
	v_and_b32_e32 v208, 0xffff0000, v208
	v_exp_f32_e32 v52, v52
	v_mul_f32_e32 v53, 0xbfb8aa3b, v208
	v_lshlrev_b32_e32 v211, 16, v209
	v_exp_f32_e32 v53, v53
	v_mul_f32_e32 v165, 0xbfb8aa3b, v211
	v_exp_f32_e32 v165, v165
	v_add_f32_e32 v52, 1.0, v52
	v_rcp_f32_e32 v212, v52
	v_add_f32_e32 v52, 1.0, v53
	v_rcp_f32_e32 v214, v52
	v_mov_b32_e32 v52, v196
	v_mov_b32_e32 v53, v194
	v_and_b32_e32 v209, 0xffff0000, v209
	v_pk_mul_f32 v[216:217], v[52:53], v[164:165] op_sel_hi:[1,0]
	s_waitcnt vmcnt(7)
; __device__ __forceinline__ unsigned pk2(float lo, float hi) { return f2bf(lo) | (f2bf(hi) << 16); }
; __device__ __forceinline__ float silu_f(float g) { return g * __builtin_amdgcn_rcpf(1.0f + __expf(-g)); }
; __device__ __forceinline__ void gla_out_unit(const bf16* PROJ, const bf16* ST, const float* norm_o, bf16* Y, int unit, int lane) {
;     ...
; #pragma unroll
;         for (int mi = 0; mi < 8; ++mi) {
;             const int v = h * 128 + 16 * mi + 4 * fq;
;             const f32x4 no = nov[mi]; const u32x2 g2 = gg1[mi];
;             const f32x4 o = acc[mi][ni];
;             const float y0 = o[0] * rs * no[0] * silu_f(bf_lo(g2.x)), y1 = o[1] * rs * no[1] * silu_f(bf_hi(g2.x));
;             const float y2 = o[2] * rs * no[2] * silu_f(bf_lo(g2.y)), y3 = o[3] * rs * no[3] * silu_f(bf_hi(g2.y));
;             u32x2 w; w.x = pk2(y0, y1); w.y = pk2(y2, y3);
;             *(u32x2*)(Y + tok * D + 512 + v) = w;
;         }
	v_mov_b32_e32 v52, v64
	v_add_f32_e32 v64, 1.0, v165
	v_rcp_f32_e32 v213, v64
	v_mul_f32_e32 v64, 0xbfb8aa3b, v209
	v_exp_f32_e32 v64, v64
	v_mov_b32_e32 v194, v197
	v_mov_b32_e32 v53, v66
	v_pk_mul_f32 v[194:195], v[194:195], v[164:165] op_sel_hi:[1,0]
	v_add_f32_e32 v64, 1.0, v64
	v_rcp_f32_e32 v215, v64
	v_mov_b32_e32 v66, v65
	v_pk_mul_f32 v[64:65], v[66:67], v[194:195]
	v_pk_mul_f32 v[216:217], v[52:53], v[216:217]
	v_pk_mul_f32 v[194:195], v[214:215], v[208:209]
	v_pk_mul_f32 v[210:211], v[212:213], v[210:211]
	v_pk_mul_f32 v[64:65], v[194:195], v[64:65]
	v_pk_mul_f32 v[210:211], v[210:211], v[216:217]
	v_and_b32_sdwa v195, v65, v204 dst_sel:DWORD dst_unused:UNUSED_PAD src0_sel:WORD_1 src1_sel:DWORD
	v_and_b32_sdwa v196, v64, v204 dst_sel:DWORD dst_unused:UNUSED_PAD src0_sel:WORD_1 src1_sel:DWORD
	v_and_b32_sdwa v165, v211, v204 dst_sel:DWORD dst_unused:UNUSED_PAD src0_sel:WORD_1 src1_sel:DWORD
	v_and_b32_sdwa v194, v210, v204 dst_sel:DWORD dst_unused:UNUSED_PAD src0_sel:WORD_1 src1_sel:DWORD
	v_add3_u32 v65, v65, v195, s29
	v_add3_u32 v64, v64, v196, s29
	v_add3_u32 v194, v210, v194, s29
	v_add3_u32 v165, v211, v165, s29
	v_and_b32_e32 v65, 0xffff0000, v65
	v_and_b32_e32 v64, 0xffff0000, v64
	v_or_b32_sdwa v65, v65, v165 dst_sel:DWORD dst_unused:UNUSED_PAD src0_sel:DWORD src1_sel:WORD_1
	v_or_b32_sdwa v64, v64, v194 dst_sel:DWORD dst_unused:UNUSED_PAD src0_sel:DWORD src1_sel:WORD_1
	v_lshlrev_b32_e32 v194, 16, v188
	global_store_dwordx2 v[156:157], v[64:65], off offset:1056
	v_mul_f32_e32 v64, 0xbfb8aa3b, v194
	v_and_b32_e32 v188, 0xffff0000, v188
	v_exp_f32_e32 v64, v64
	v_mul_f32_e32 v65, 0xbfb8aa3b, v188
	v_lshlrev_b32_e32 v195, 16, v189
	v_exp_f32_e32 v65, v65
	v_mul_f32_e32 v165, 0xbfb8aa3b, v195
	v_exp_f32_e32 v165, v165
	v_add_f32_e32 v64, 1.0, v64
	v_rcp_f32_e32 v196, v64
	v_add_f32_e32 v64, 1.0, v65
	v_rcp_f32_e32 v208, v64
	v_mov_b32_e32 v64, v192
	v_mov_b32_e32 v65, v190
	v_and_b32_e32 v189, 0xffff0000, v189
	v_pk_mul_f32 v[210:211], v[64:65], v[164:165] op_sel_hi:[1,0]
	s_waitcnt vmcnt(7)
	v_mov_b32_e32 v64, v56
	v_add_f32_e32 v56, 1.0, v165
	v_rcp_f32_e32 v197, v56
	v_mul_f32_e32 v56, 0xbfb8aa3b, v189
	v_exp_f32_e32 v56, v56
	v_mov_b32_e32 v190, v193
	v_mov_b32_e32 v65, v58
	v_pk_mul_f32 v[190:191], v[190:191], v[164:165] op_sel_hi:[1,0]
	v_add_f32_e32 v56, 1.0, v56
	v_rcp_f32_e32 v209, v56
	v_mov_b32_e32 v58, v57
	v_pk_mul_f32 v[56:57], v[58:59], v[190:191]
	v_pk_mul_f32 v[210:211], v[64:65], v[210:211]
	v_pk_mul_f32 v[188:189], v[208:209], v[188:189]
	v_pk_mul_f32 v[194:195], v[196:197], v[194:195]
	v_pk_mul_f32 v[56:57], v[188:189], v[56:57]
	v_pk_mul_f32 v[194:195], v[194:195], v[210:211]
	v_and_b32_sdwa v189, v57, v204 dst_sel:DWORD dst_unused:UNUSED_PAD src0_sel:WORD_1 src1_sel:DWORD
	v_and_b32_sdwa v190, v56, v204 dst_sel:DWORD dst_unused:UNUSED_PAD src0_sel:WORD_1 src1_sel:DWORD
	v_and_b32_sdwa v165, v195, v204 dst_sel:DWORD dst_unused:UNUSED_PAD src0_sel:WORD_1 src1_sel:DWORD
	v_and_b32_sdwa v188, v194, v204 dst_sel:DWORD dst_unused:UNUSED_PAD src0_sel:WORD_1 src1_sel:DWORD
	v_add3_u32 v57, v57, v189, s29
	v_add3_u32 v56, v56, v190, s29
	v_add3_u32 v188, v194, v188, s29
	v_add3_u32 v165, v195, v165, s29
	v_and_b32_e32 v57, 0xffff0000, v57
	v_and_b32_e32 v56, 0xffff0000, v56
	v_or_b32_sdwa v57, v57, v165 dst_sel:DWORD dst_unused:UNUSED_PAD src0_sel:DWORD src1_sel:WORD_1
	v_or_b32_sdwa v56, v56, v188 dst_sel:DWORD dst_unused:UNUSED_PAD src0_sel:DWORD src1_sel:WORD_1
	v_lshlrev_b32_e32 v188, 16, v182
	global_store_dwordx2 v[156:157], v[56:57], off offset:1088
	v_mul_f32_e32 v56, 0xbfb8aa3b, v188
	v_and_b32_e32 v182, 0xffff0000, v182
	v_exp_f32_e32 v56, v56
	v_mul_f32_e32 v57, 0xbfb8aa3b, v182
	v_lshlrev_b32_e32 v189, 16, v183
	v_exp_f32_e32 v57, v57
	v_mul_f32_e32 v165, 0xbfb8aa3b, v189
	v_exp_f32_e32 v165, v165
	v_add_f32_e32 v56, 1.0, v56
	v_rcp_f32_e32 v190, v56
	v_add_f32_e32 v56, 1.0, v57
	v_rcp_f32_e32 v192, v56
	v_mov_b32_e32 v56, v186
	v_mov_b32_e32 v57, v184
	v_and_b32_e32 v183, 0xffff0000, v183
	v_pk_mul_f32 v[194:195], v[56:57], v[164:165] op_sel_hi:[1,0]
	s_waitcnt vmcnt(7)
	v_mov_b32_e32 v56, v48
	v_add_f32_e32 v48, 1.0, v165
	v_rcp_f32_e32 v191, v48
	v_mul_f32_e32 v48, 0xbfb8aa3b, v183
	v_exp_f32_e32 v48, v48
	v_mov_b32_e32 v184, v187
	v_mov_b32_e32 v57, v50
	v_pk_mul_f32 v[184:185], v[184:185], v[164:165] op_sel_hi:[1,0]
	v_add_f32_e32 v48, 1.0, v48
	v_rcp_f32_e32 v193, v48
	v_mov_b32_e32 v50, v49
	v_pk_mul_f32 v[48:49], v[50:51], v[184:185]
	v_pk_mul_f32 v[194:195], v[56:57], v[194:195]
	v_pk_mul_f32 v[182:183], v[192:193], v[182:183]
	v_pk_mul_f32 v[188:189], v[190:191], v[188:189]
	v_pk_mul_f32 v[48:49], v[182:183], v[48:49]
	v_pk_mul_f32 v[188:189], v[188:189], v[194:195]
	v_and_b32_sdwa v183, v49, v204 dst_sel:DWORD dst_unused:UNUSED_PAD src0_sel:WORD_1 src1_sel:DWORD
	v_and_b32_sdwa v184, v48, v204 dst_sel:DWORD dst_unused:UNUSED_PAD src0_sel:WORD_1 src1_sel:DWORD
	v_and_b32_sdwa v165, v189, v204 dst_sel:DWORD dst_unused:UNUSED_PAD src0_sel:WORD_1 src1_sel:DWORD
	v_and_b32_sdwa v182, v188, v204 dst_sel:DWORD dst_unused:UNUSED_PAD src0_sel:WORD_1 src1_sel:DWORD
	v_add3_u32 v49, v49, v183, s29
	v_add3_u32 v48, v48, v184, s29
	v_add3_u32 v182, v188, v182, s29
	v_add3_u32 v165, v189, v165, s29
	v_and_b32_e32 v49, 0xffff0000, v49
	v_and_b32_e32 v48, 0xffff0000, v48
	v_or_b32_sdwa v49, v49, v165 dst_sel:DWORD dst_unused:UNUSED_PAD src0_sel:DWORD src1_sel:WORD_1
	v_or_b32_sdwa v48, v48, v182 dst_sel:DWORD dst_unused:UNUSED_PAD src0_sel:DWORD src1_sel:WORD_1
	v_lshlrev_b32_e32 v182, 16, v176
	global_store_dwordx2 v[156:157], v[48:49], off offset:1120
	v_mul_f32_e32 v48, 0xbfb8aa3b, v182
	v_and_b32_e32 v176, 0xffff0000, v176
	v_exp_f32_e32 v48, v48
	v_mul_f32_e32 v49, 0xbfb8aa3b, v176
	v_lshlrev_b32_e32 v183, 16, v177
	v_exp_f32_e32 v49, v49
	v_mul_f32_e32 v165, 0xbfb8aa3b, v183
	v_exp_f32_e32 v165, v165
	v_add_f32_e32 v48, 1.0, v48
	v_rcp_f32_e32 v184, v48
	v_add_f32_e32 v48, 1.0, v49
	v_rcp_f32_e32 v186, v48
	v_mov_b32_e32 v48, v180
	v_mov_b32_e32 v49, v178
	v_and_b32_e32 v177, 0xffff0000, v177
	v_pk_mul_f32 v[188:189], v[48:49], v[164:165] op_sel_hi:[1,0]
	s_waitcnt vmcnt(7)
; __device__ __forceinline__ unsigned pk2(float lo, float hi) { return f2bf(lo) | (f2bf(hi) << 16); }
; __device__ __forceinline__ float silu_f(float g) { return g * __builtin_amdgcn_rcpf(1.0f + __expf(-g)); }
; __device__ __forceinline__ void gla_out_unit(const bf16* PROJ, const bf16* ST, const float* norm_o, bf16* Y, int unit, int lane) {
;     ...
; #pragma unroll
;         for (int mi = 0; mi < 8; ++mi) {
;             const int v = h * 128 + 16 * mi + 4 * fq;
;             const f32x4 no = nov[mi]; const u32x2 g2 = gg1[mi];
;             const f32x4 o = acc[mi][ni];
;             const float y0 = o[0] * rs * no[0] * silu_f(bf_lo(g2.x)), y1 = o[1] * rs * no[1] * silu_f(bf_hi(g2.x));
;             const float y2 = o[2] * rs * no[2] * silu_f(bf_lo(g2.y)), y3 = o[3] * rs * no[3] * silu_f(bf_hi(g2.y));
;             u32x2 w; w.x = pk2(y0, y1); w.y = pk2(y2, y3);
;             *(u32x2*)(Y + tok * D + 512 + v) = w;
;         }
	v_mov_b32_e32 v48, v44
	v_add_f32_e32 v44, 1.0, v165
	v_rcp_f32_e32 v185, v44
	v_mul_f32_e32 v44, 0xbfb8aa3b, v177
	v_exp_f32_e32 v44, v44
	v_mov_b32_e32 v178, v181
	v_mov_b32_e32 v49, v46
	v_pk_mul_f32 v[178:179], v[178:179], v[164:165] op_sel_hi:[1,0]
	v_add_f32_e32 v44, 1.0, v44
	v_rcp_f32_e32 v187, v44
	v_mov_b32_e32 v46, v45
	v_pk_mul_f32 v[44:45], v[46:47], v[178:179]
	v_pk_mul_f32 v[188:189], v[48:49], v[188:189]
	v_pk_mul_f32 v[176:177], v[186:187], v[176:177]
	v_pk_mul_f32 v[182:183], v[184:185], v[182:183]
	v_pk_mul_f32 v[44:45], v[176:177], v[44:45]
	v_pk_mul_f32 v[182:183], v[182:183], v[188:189]
	v_and_b32_sdwa v177, v45, v204 dst_sel:DWORD dst_unused:UNUSED_PAD src0_sel:WORD_1 src1_sel:DWORD
	v_and_b32_sdwa v178, v44, v204 dst_sel:DWORD dst_unused:UNUSED_PAD src0_sel:WORD_1 src1_sel:DWORD
	v_and_b32_sdwa v165, v183, v204 dst_sel:DWORD dst_unused:UNUSED_PAD src0_sel:WORD_1 src1_sel:DWORD
	v_and_b32_sdwa v176, v182, v204 dst_sel:DWORD dst_unused:UNUSED_PAD src0_sel:WORD_1 src1_sel:DWORD
	v_add3_u32 v45, v45, v177, s29
	v_add3_u32 v44, v44, v178, s29
	v_add3_u32 v176, v182, v176, s29
	v_add3_u32 v165, v183, v165, s29
	v_and_b32_e32 v45, 0xffff0000, v45
	v_and_b32_e32 v44, 0xffff0000, v44
	v_or_b32_sdwa v45, v45, v165 dst_sel:DWORD dst_unused:UNUSED_PAD src0_sel:DWORD src1_sel:WORD_1
	v_or_b32_sdwa v44, v44, v176 dst_sel:DWORD dst_unused:UNUSED_PAD src0_sel:DWORD src1_sel:WORD_1
	v_lshlrev_b32_e32 v176, 16, v170
	global_store_dwordx2 v[156:157], v[44:45], off offset:1152
	v_mul_f32_e32 v44, 0xbfb8aa3b, v176
	v_and_b32_e32 v170, 0xffff0000, v170
	v_exp_f32_e32 v44, v44
	v_mul_f32_e32 v45, 0xbfb8aa3b, v170
	v_lshlrev_b32_e32 v177, 16, v171
	v_exp_f32_e32 v45, v45
	v_mul_f32_e32 v165, 0xbfb8aa3b, v177
	v_exp_f32_e32 v165, v165
	v_add_f32_e32 v44, 1.0, v44
	v_rcp_f32_e32 v178, v44
	v_add_f32_e32 v44, 1.0, v45
	v_rcp_f32_e32 v180, v44
	v_mov_b32_e32 v44, v174
	v_mov_b32_e32 v45, v172
	v_and_b32_e32 v171, 0xffff0000, v171
	v_pk_mul_f32 v[182:183], v[44:45], v[164:165] op_sel_hi:[1,0]
	s_waitcnt vmcnt(7)
	v_mov_b32_e32 v44, v40
	v_add_f32_e32 v40, 1.0, v165
	v_rcp_f32_e32 v179, v40
	v_mul_f32_e32 v40, 0xbfb8aa3b, v171
	v_exp_f32_e32 v40, v40
	v_mov_b32_e32 v172, v175
	v_mov_b32_e32 v45, v42
	v_pk_mul_f32 v[172:173], v[172:173], v[164:165] op_sel_hi:[1,0]
	v_add_f32_e32 v40, 1.0, v40
	v_rcp_f32_e32 v181, v40
	v_mov_b32_e32 v42, v41
	v_pk_mul_f32 v[40:41], v[42:43], v[172:173]
	v_pk_mul_f32 v[182:183], v[44:45], v[182:183]
	v_pk_mul_f32 v[170:171], v[180:181], v[170:171]
	v_pk_mul_f32 v[176:177], v[178:179], v[176:177]
	v_pk_mul_f32 v[40:41], v[170:171], v[40:41]
	v_pk_mul_f32 v[176:177], v[176:177], v[182:183]
	v_and_b32_sdwa v171, v41, v204 dst_sel:DWORD dst_unused:UNUSED_PAD src0_sel:WORD_1 src1_sel:DWORD
	v_and_b32_sdwa v172, v40, v204 dst_sel:DWORD dst_unused:UNUSED_PAD src0_sel:WORD_1 src1_sel:DWORD
	v_and_b32_sdwa v165, v177, v204 dst_sel:DWORD dst_unused:UNUSED_PAD src0_sel:WORD_1 src1_sel:DWORD
	v_and_b32_sdwa v170, v176, v204 dst_sel:DWORD dst_unused:UNUSED_PAD src0_sel:WORD_1 src1_sel:DWORD
	v_add3_u32 v41, v41, v171, s29
	v_add3_u32 v40, v40, v172, s29
	v_add3_u32 v170, v176, v170, s29
	v_add3_u32 v165, v177, v165, s29
	v_and_b32_e32 v41, 0xffff0000, v41
	v_and_b32_e32 v40, 0xffff0000, v40
	v_or_b32_sdwa v41, v41, v165 dst_sel:DWORD dst_unused:UNUSED_PAD src0_sel:DWORD src1_sel:WORD_1
	v_or_b32_sdwa v40, v40, v170 dst_sel:DWORD dst_unused:UNUSED_PAD src0_sel:DWORD src1_sel:WORD_1
	v_lshlrev_b32_e32 v170, 16, v162
	global_store_dwordx2 v[156:157], v[40:41], off offset:1184
	v_mul_f32_e32 v40, 0xbfb8aa3b, v170
	v_and_b32_e32 v162, 0xffff0000, v162
	v_exp_f32_e32 v40, v40
	v_mul_f32_e32 v41, 0xbfb8aa3b, v162
	v_lshlrev_b32_e32 v171, 16, v163
	v_exp_f32_e32 v41, v41
	v_mul_f32_e32 v165, 0xbfb8aa3b, v171
	v_exp_f32_e32 v165, v165
	v_add_f32_e32 v40, 1.0, v40
	v_rcp_f32_e32 v172, v40
	v_add_f32_e32 v40, 1.0, v41
	v_rcp_f32_e32 v174, v40
	v_mov_b32_e32 v40, v168
	v_mov_b32_e32 v41, v166
	v_and_b32_e32 v163, 0xffff0000, v163
	v_pk_mul_f32 v[176:177], v[40:41], v[164:165] op_sel_hi:[1,0]
	s_waitcnt vmcnt(7)
	v_mov_b32_e32 v40, v36
	v_add_f32_e32 v36, 1.0, v165
	v_rcp_f32_e32 v173, v36
	v_mul_f32_e32 v36, 0xbfb8aa3b, v163
	v_exp_f32_e32 v36, v36
	v_mov_b32_e32 v166, v169
	v_mov_b32_e32 v41, v38
	v_pk_mul_f32 v[166:167], v[166:167], v[164:165] op_sel_hi:[1,0]
	v_add_f32_e32 v36, 1.0, v36
	v_rcp_f32_e32 v175, v36
	v_mov_b32_e32 v38, v37
	v_pk_mul_f32 v[36:37], v[38:39], v[166:167]
	v_pk_mul_f32 v[176:177], v[40:41], v[176:177]
	v_pk_mul_f32 v[162:163], v[174:175], v[162:163]
	v_pk_mul_f32 v[170:171], v[172:173], v[170:171]
	v_pk_mul_f32 v[36:37], v[162:163], v[36:37]
	v_pk_mul_f32 v[170:171], v[170:171], v[176:177]
	v_and_b32_sdwa v165, v37, v204 dst_sel:DWORD dst_unused:UNUSED_PAD src0_sel:WORD_1 src1_sel:DWORD
	v_and_b32_sdwa v166, v36, v204 dst_sel:DWORD dst_unused:UNUSED_PAD src0_sel:WORD_1 src1_sel:DWORD
	v_and_b32_sdwa v162, v171, v204 dst_sel:DWORD dst_unused:UNUSED_PAD src0_sel:WORD_1 src1_sel:DWORD
	v_and_b32_sdwa v163, v170, v204 dst_sel:DWORD dst_unused:UNUSED_PAD src0_sel:WORD_1 src1_sel:DWORD
	v_add3_u32 v37, v37, v165, s29
	v_add3_u32 v36, v36, v166, s29
	v_add3_u32 v163, v170, v163, s29
	v_add3_u32 v162, v171, v162, s29
	v_and_b32_e32 v37, 0xffff0000, v37
	v_and_b32_e32 v36, 0xffff0000, v36
	v_or_b32_sdwa v37, v37, v162 dst_sel:DWORD dst_unused:UNUSED_PAD src0_sel:DWORD src1_sel:WORD_1
	v_or_b32_sdwa v36, v36, v163 dst_sel:DWORD dst_unused:UNUSED_PAD src0_sel:DWORD src1_sel:WORD_1
	v_lshlrev_b32_e32 v162, 16, v158
	global_store_dwordx2 v[156:157], v[36:37], off offset:1216
	v_mul_f32_e32 v36, 0xbfb8aa3b, v162
	v_and_b32_e32 v158, 0xffff0000, v158
	v_exp_f32_e32 v36, v36
	v_mul_f32_e32 v37, 0xbfb8aa3b, v158
	v_exp_f32_e32 v37, v37
	v_lshlrev_b32_e32 v163, 16, v159
	v_add_f32_e32 v36, 1.0, v36
	v_rcp_f32_e32 v166, v36
	v_add_f32_e32 v36, 1.0, v37
	v_mov_b32_e32 v37, v130
	v_mul_f32_e32 v130, 0xbfb8aa3b, v163
	v_exp_f32_e32 v130, v130
	v_rcp_f32_e32 v168, v36
	v_mov_b32_e32 v36, v160
	v_and_b32_e32 v159, 0xffff0000, v159
	v_pk_mul_f32 v[170:171], v[36:37], v[164:165] op_sel_hi:[1,0]
	s_waitcnt vmcnt(7)
; __device__ __forceinline__ unsigned pk2(float lo, float hi) { return f2bf(lo) | (f2bf(hi) << 16); }
; __device__ __forceinline__ float silu_f(float g) { return g * __builtin_amdgcn_rcpf(1.0f + __expf(-g)); }
; __device__ __forceinline__ void gla_out_unit(const bf16* PROJ, const bf16* ST, const float* norm_o, bf16* Y, int unit, int lane) {
;     ...
;         for (int mi = 0; mi < 8; ++mi) gg1[mi] = *(const u32x2*)(PROJ + (size_t)(tok0 + 16 * ni + fr) * NPROJ + 2048 + h * 128 + 16 * mi + 4 * fq);
;         asm volatile("" : "+v"(gg1[0]), "+v"(gg1[1]), "+v"(gg1[2]), "+v"(gg1[3]), "+v"(gg1[4]), "+v"(gg1[5]), "+v"(gg1[6]), "+v"(gg1[7]));
;         float ss = 0.f;
; #pragma unroll
;         for (int mi = 0; mi < 8; ++mi) { acc[mi][ni] = acc[mi][ni] * 0.125f; const f32x4 o = acc[mi][ni]; ss += (o[0] * o[0] + o[1] * o[1]) + (o[2] * o[2] + o[3] * o[3]); }
;         ss += __shfl_xor(ss, 16); ss += __shfl_xor(ss, 32);
;         const float rs = __builtin_amdgcn_rsqf(ss * (1.f / 128.f) + EPS);
;         const size_t tok = (size_t)(tok0 + 16 * ni + fr);
; #pragma unroll
;         for (int mi = 0; mi < 8; ++mi) {
;             const int v = h * 128 + 16 * mi + 4 * fq;
;             const f32x4 no = nov[mi]; const u32x2 g2 = gg1[mi];
;             const f32x4 o = acc[mi][ni];
;             const float y0 = o[0] * rs * no[0] * silu_f(bf_lo(g2.x)), y1 = o[1] * rs * no[1] * silu_f(bf_hi(g2.x));
;             const float y2 = o[2] * rs * no[2] * silu_f(bf_lo(g2.y)), y3 = o[3] * rs * no[3] * silu_f(bf_hi(g2.y));
;             u32x2 w; w.x = pk2(y0, y1); w.y = pk2(y2, y3);
;             *(u32x2*)(Y + tok * D + 512 + v) = w;
;         }
	v_mov_b32_e32 v36, v32
	v_add_f32_e32 v32, 1.0, v130
	v_rcp_f32_e32 v167, v32
	v_mul_f32_e32 v32, 0xbfb8aa3b, v159
	v_exp_f32_e32 v32, v32
	v_mov_b32_e32 v130, v161
	v_mov_b32_e32 v37, v34
	v_pk_mul_f32 v[130:131], v[130:131], v[164:165] op_sel_hi:[1,0]
	v_add_f32_e32 v32, 1.0, v32
	v_rcp_f32_e32 v169, v32
	v_mov_b32_e32 v34, v33
	v_pk_mul_f32 v[32:33], v[34:35], v[130:131]
	v_pk_mul_f32 v[170:171], v[36:37], v[170:171]
	v_pk_mul_f32 v[130:131], v[168:169], v[158:159]
	v_pk_mul_f32 v[162:163], v[166:167], v[162:163]
	v_pk_mul_f32 v[32:33], v[130:131], v[32:33]
	v_pk_mul_f32 v[162:163], v[162:163], v[170:171]
	v_and_b32_sdwa v158, v33, v204 dst_sel:DWORD dst_unused:UNUSED_PAD src0_sel:WORD_1 src1_sel:DWORD
	v_and_b32_sdwa v159, v32, v204 dst_sel:DWORD dst_unused:UNUSED_PAD src0_sel:WORD_1 src1_sel:DWORD
	v_and_b32_sdwa v130, v163, v204 dst_sel:DWORD dst_unused:UNUSED_PAD src0_sel:WORD_1 src1_sel:DWORD
	v_and_b32_sdwa v131, v162, v204 dst_sel:DWORD dst_unused:UNUSED_PAD src0_sel:WORD_1 src1_sel:DWORD
	v_add3_u32 v33, v33, v158, s29
	v_add3_u32 v32, v32, v159, s29
	v_add3_u32 v131, v162, v131, s29
	v_add3_u32 v130, v163, v130, s29
	v_and_b32_e32 v33, 0xffff0000, v33
	v_and_b32_e32 v32, 0xffff0000, v32
	v_or_b32_sdwa v33, v33, v130 dst_sel:DWORD dst_unused:UNUSED_PAD src0_sel:DWORD src1_sel:WORD_1
	v_or_b32_sdwa v32, v32, v131 dst_sel:DWORD dst_unused:UNUSED_PAD src0_sel:DWORD src1_sel:WORD_1
	global_store_dwordx2 v[156:157], v[32:33], off offset:1248
	v_lshl_add_u64 v[32:33], v[154:155], 0, s[4:5]
	v_lshl_add_u64 v[32:33], v[32:33], 0, v[144:145]
	v_lshl_add_u64 v[162:163], v[32:33], 0, s[6:7]
	v_add_co_u32_e32 v32, vcc, s28, v32
	v_pk_mul_f32 v[172:173], v[124:125], s[12:13] op_sel_hi:[1,0]
	s_nop 0
	v_addc_co_u32_e32 v33, vcc, 0, v33, vcc
	global_load_dwordx2 v[166:167], v[162:163], off offset:32 nt
	global_load_dwordx2 v[160:161], v[162:163], off offset:64 nt
	global_load_dwordx2 v[158:159], v[162:163], off offset:96 nt
	global_load_dwordx2 v[156:157], v[162:163], off offset:128 nt
	global_load_dwordx2 v[168:169], v[32:33], off nt
	global_load_dwordx2 v[154:155], v[162:163], off offset:160 nt
	global_load_dwordx2 v[130:131], v[162:163], off offset:192 nt
	s_nop 0
	global_load_dwordx2 v[32:33], v[162:163], off offset:224 nt
	v_pk_mul_f32 v[176:177], v[120:121], s[12:13] op_sel_hi:[1,0]
	v_pk_mul_f32 v[170:171], v[126:127], s[12:13] op_sel_hi:[1,0]
	v_pk_mul_f32 v[174:175], v[122:123], s[12:13] op_sel_hi:[1,0]
	v_mov_b32_e32 v122, v173
	v_mov_b32_e32 v123, v177
	v_mov_b32_e32 v120, v172
	v_mov_b32_e32 v121, v176
	v_pk_mul_f32 v[122:123], v[122:123], v[122:123]
	v_mov_b32_e32 v124, v171
	v_mov_b32_e32 v125, v175
	v_pk_fma_f32 v[120:121], v[120:121], v[120:121], v[122:123]
	v_mov_b32_e32 v122, v170
	v_mov_b32_e32 v123, v174
	v_pk_mul_f32 v[124:125], v[124:125], v[124:125]
	v_pk_mul_f32 v[162:163], v[114:115], s[12:13] op_sel_hi:[1,0]
	v_pk_mul_f32 v[164:165], v[112:113], s[12:13] op_sel_hi:[1,0]
	v_pk_fma_f32 v[122:123], v[122:123], v[122:123], v[124:125]
	v_pk_mul_f32 v[112:113], v[162:163], v[162:163]
	v_pk_mul_f32 v[114:115], v[164:165], v[164:165]
	v_pk_add_f32 v[178:179], v[120:121], v[122:123]
	v_pk_mov_b32 v[120:121], v[114:115], v[112:113] op_sel:[1,0]
	v_mov_b32_e32 v115, v113
	v_pk_mul_f32 v[122:123], v[100:101], s[12:13] op_sel_hi:[1,0]
	v_pk_add_f32 v[112:113], v[120:121], v[114:115]
	v_pk_mul_f32 v[120:121], v[102:103], s[12:13] op_sel_hi:[1,0]
	v_mul_f32_e32 v102, v122, v122
	v_pk_add_f32 v[100:101], v[178:179], v[178:179] op_sel:[0,1] op_sel_hi:[1,0]
	v_pk_mul_f32 v[126:127], v[104:105], s[12:13] op_sel_hi:[1,0]
	v_mul_f32_e32 v104, v123, v123
	v_mov_b32_e32 v101, v102
	v_pk_add_f32 v[102:103], v[112:113], v[112:113] op_sel:[0,1] op_sel_hi:[1,0]
	v_pk_mul_f32 v[124:125], v[106:107], s[12:13] op_sel_hi:[1,0]
	v_mov_b32_e32 v103, v104
	v_pk_add_f32 v[100:101], v[100:101], v[102:103]
	v_mul_f32_e32 v102, v127, v127
	v_mul_f32_e32 v105, v120, v120
	v_pk_fma_f32 v[102:103], v[126:127], v[126:127], v[102:103] op_sel_hi:[1,1,0]
	v_mul_f32_e32 v104, v125, v125
	v_mul_f32_e32 v106, v121, v121
	v_mov_b32_e32 v103, v105
	v_pk_fma_f32 v[104:105], v[124:125], v[124:125], v[104:105] op_sel_hi:[1,1,0]
	v_pk_mul_f32 v[112:113], v[98:99], s[12:13] op_sel_hi:[1,0]
	v_mov_b32_e32 v105, v106
	v_pk_mul_f32 v[114:115], v[96:97], s[12:13] op_sel_hi:[1,0]
	v_pk_add_f32 v[102:103], v[102:103], v[104:105]
	v_pk_mul_f32 v[96:97], v[112:113], v[112:113]
	v_pk_mul_f32 v[98:99], v[114:115], v[114:115]
	v_pk_add_f32 v[100:101], v[100:101], v[102:103]
	v_pk_mov_b32 v[102:103], v[98:99], v[96:97] op_sel:[1,0]
	v_mov_b32_e32 v99, v97
	v_pk_add_f32 v[106:107], v[102:103], v[98:99]
	v_pk_mul_f32 v[98:99], v[116:117], s[12:13] op_sel_hi:[1,0]
	v_pk_mul_f32 v[104:105], v[108:109], s[12:13] op_sel_hi:[1,0]
	v_mul_f32_e32 v108, v98, v98
	v_mul_f32_e32 v109, v99, v99
	v_pk_add_f32 v[100:101], v[100:101], v[100:101] op_sel:[0,1] op_sel_hi:[1,0]
	v_pk_add_f32 v[106:107], v[106:107], v[106:107] op_sel:[0,1] op_sel_hi:[1,0]
	v_pk_mul_f32 v[102:103], v[110:111], s[12:13] op_sel_hi:[1,0]
	v_mov_b32_e32 v101, v108
	v_mov_b32_e32 v107, v109
	v_pk_mul_f32 v[96:97], v[118:119], s[12:13] op_sel_hi:[1,0]
	v_pk_add_f32 v[100:101], v[100:101], v[106:107]
	v_mul_f32_e32 v106, v105, v105
	v_mul_f32_e32 v108, v103, v103
	v_mul_f32_e32 v110, v96, v96
	v_mul_f32_e32 v111, v97, v97
	v_pk_fma_f32 v[106:107], v[104:105], v[104:105], v[106:107] op_sel_hi:[1,1,0]
	v_pk_fma_f32 v[108:109], v[102:103], v[102:103], v[108:109] op_sel_hi:[1,1,0]
	v_mov_b32_e32 v107, v110
	v_mov_b32_e32 v109, v111
	v_pk_add_f32 v[106:107], v[106:107], v[108:109]
	s_waitcnt vmcnt(0)
; __device__ __forceinline__ unsigned pk2(float lo, float hi) { return f2bf(lo) | (f2bf(hi) << 16); }
; __device__ __forceinline__ float silu_f(float g) { return g * __builtin_amdgcn_rcpf(1.0f + __expf(-g)); }
; __device__ __forceinline__ void gla_out_unit(const bf16* PROJ, const bf16* ST, const float* norm_o, bf16* Y, int unit, int lane) {
;     ...
;         ss += __shfl_xor(ss, 16); ss += __shfl_xor(ss, 32);
;         const float rs = __builtin_amdgcn_rsqf(ss * (1.f / 128.f) + EPS);
;         const size_t tok = (size_t)(tok0 + 16 * ni + fr);
; #pragma unroll
;         for (int mi = 0; mi < 8; ++mi) {
;             const int v = h * 128 + 16 * mi + 4 * fq;
;             const f32x4 no = nov[mi]; const u32x2 g2 = gg1[mi];
;             const f32x4 o = acc[mi][ni];
;             const float y0 = o[0] * rs * no[0] * silu_f(bf_lo(g2.x)), y1 = o[1] * rs * no[1] * silu_f(bf_hi(g2.x));
;             const float y2 = o[2] * rs * no[2] * silu_f(bf_lo(g2.y)), y3 = o[3] * rs * no[3] * silu_f(bf_hi(g2.y));
;             u32x2 w; w.x = pk2(y0, y1); w.y = pk2(y2, y3);
;             *(u32x2*)(Y + tok * D + 512 + v) = w;
;         }
	v_pk_add_f32 v[100:101], v[100:101], v[106:107]
	v_lshlrev_b32_e32 v108, 16, v168
	v_add_f32_e32 v100, v100, v101
	ds_bpermute_b32 v101, v205, v100
	v_and_b32_e32 v110, 0xffff0000, v168
	v_mul_f32_e32 v111, 0xbfb8aa3b, v110
	v_exp_f32_e32 v117, v111
	v_lshlrev_b32_e32 v109, 16, v169
	s_waitcnt lgkmcnt(0)
	v_add_f32_e32 v100, v100, v101
	ds_bpermute_b32 v101, v206, v100
	v_lshlrev_b64 v[106:107], 11, v[152:153]
	v_mov_b32_e32 v152, v172
	v_mov_b32_e32 v153, v170
	v_and_b32_e32 v111, 0xffff0000, v169
	s_waitcnt lgkmcnt(0)
	v_add_f32_e32 v100, v100, v101
	v_mul_f32_e32 v101, 0xbfb8aa3b, v108
	v_exp_f32_e32 v101, v101
	v_fmamk_f32 v100, v100, 0x3c000000, v199
	v_rsq_f32_e32 v100, v100
	v_mov_b32_e32 v170, v173
	v_add_f32_e32 v101, 1.0, v101
	v_rcp_f32_e32 v116, v101
	v_add_f32_e32 v101, 1.0, v117
	v_rcp_f32_e32 v118, v101
	v_mul_f32_e32 v101, 0xbfb8aa3b, v109
	v_exp_f32_e32 v101, v101
	v_lshl_add_u64 v[106:107], v[136:137], 0, v[106:107]
	v_pk_mul_f32 v[152:153], v[152:153], v[100:101] op_sel_hi:[1,0]
	v_add_f32_e32 v101, 1.0, v101
	v_rcp_f32_e32 v117, v101
	v_mul_f32_e32 v101, 0xbfb8aa3b, v111
	v_exp_f32_e32 v101, v101
	v_pk_mul_f32 v[152:153], v[128:129], v[152:153]
	v_pk_mul_f32 v[108:109], v[116:117], v[108:109]
	v_add_f32_e32 v101, 1.0, v101
	v_rcp_f32_e32 v119, v101
	v_pk_mul_f32 v[116:117], v[170:171], v[100:101] op_sel_hi:[1,0]
	v_pk_mul_f32 v[108:109], v[152:153], v[108:109]
	v_pk_mul_f32 v[116:117], v[54:55], v[116:117]
	v_pk_mul_f32 v[110:111], v[118:119], v[110:111]
	v_and_b32_sdwa v101, v109, v204 dst_sel:DWORD dst_unused:UNUSED_PAD src0_sel:WORD_1 src1_sel:DWORD
	v_pk_mul_f32 v[110:111], v[116:117], v[110:111]
	v_and_b32_sdwa v116, v108, v204 dst_sel:DWORD dst_unused:UNUSED_PAD src0_sel:WORD_1 src1_sel:DWORD
	v_add3_u32 v108, v108, v116, s29
	v_add3_u32 v101, v109, v101, s29
	v_and_b32_sdwa v109, v111, v204 dst_sel:DWORD dst_unused:UNUSED_PAD src0_sel:WORD_1 src1_sel:DWORD
	v_and_b32_sdwa v116, v110, v204 dst_sel:DWORD dst_unused:UNUSED_PAD src0_sel:WORD_1 src1_sel:DWORD
	v_add3_u32 v109, v111, v109, s29
	v_add3_u32 v110, v110, v116, s29
	v_and_b32_e32 v109, 0xffff0000, v109
	v_and_b32_e32 v110, 0xffff0000, v110
	v_or_b32_sdwa v109, v109, v101 dst_sel:DWORD dst_unused:UNUSED_PAD src0_sel:DWORD src1_sel:WORD_1
	v_or_b32_sdwa v108, v110, v108 dst_sel:DWORD dst_unused:UNUSED_PAD src0_sel:DWORD src1_sel:WORD_1
	global_store_dwordx2 v[106:107], v[108:109], off offset:1024
	v_lshlrev_b32_e32 v108, 16, v166
	v_mul_f32_e32 v101, 0xbfb8aa3b, v108
	v_and_b32_e32 v110, 0xffff0000, v166
	v_exp_f32_e32 v101, v101
	v_mul_f32_e32 v111, 0xbfb8aa3b, v110
	v_exp_f32_e32 v117, v111
	v_lshlrev_b32_e32 v109, 16, v167
	v_add_f32_e32 v101, 1.0, v101
	v_rcp_f32_e32 v116, v101
	v_add_f32_e32 v101, 1.0, v117
	v_rcp_f32_e32 v118, v101
	v_mul_f32_e32 v101, 0xbfb8aa3b, v109
	v_exp_f32_e32 v101, v101
	v_mov_b32_e32 v152, v176
	v_mov_b32_e32 v153, v174
	v_and_b32_e32 v111, 0xffff0000, v167
	v_pk_mul_f32 v[152:153], v[152:153], v[100:101] op_sel_hi:[1,0]
	v_add_f32_e32 v101, 1.0, v101
	v_rcp_f32_e32 v117, v101
	v_mul_f32_e32 v101, 0xbfb8aa3b, v111
	v_exp_f32_e32 v101, v101
	v_mov_b32_e32 v174, v177
	v_pk_mul_f32 v[152:153], v[52:53], v[152:153]
	v_pk_mul_f32 v[108:109], v[116:117], v[108:109]
	v_add_f32_e32 v101, 1.0, v101
	v_rcp_f32_e32 v119, v101
	v_pk_mul_f32 v[116:117], v[174:175], v[100:101] op_sel_hi:[1,0]
	v_pk_mul_f32 v[108:109], v[152:153], v[108:109]
	v_pk_mul_f32 v[116:117], v[66:67], v[116:117]
	v_pk_mul_f32 v[110:111], v[118:119], v[110:111]
	v_and_b32_sdwa v101, v109, v204 dst_sel:DWORD dst_unused:UNUSED_PAD src0_sel:WORD_1 src1_sel:DWORD
	v_pk_mul_f32 v[110:111], v[116:117], v[110:111]
	v_and_b32_sdwa v116, v108, v204 dst_sel:DWORD dst_unused:UNUSED_PAD src0_sel:WORD_1 src1_sel:DWORD
	v_add3_u32 v108, v108, v116, s29
	v_add3_u32 v101, v109, v101, s29
	v_and_b32_sdwa v109, v111, v204 dst_sel:DWORD dst_unused:UNUSED_PAD src0_sel:WORD_1 src1_sel:DWORD
	v_and_b32_sdwa v116, v110, v204 dst_sel:DWORD dst_unused:UNUSED_PAD src0_sel:WORD_1 src1_sel:DWORD
	v_add3_u32 v109, v111, v109, s29
	v_add3_u32 v110, v110, v116, s29
	v_and_b32_e32 v109, 0xffff0000, v109
	v_and_b32_e32 v110, 0xffff0000, v110
	v_or_b32_sdwa v109, v109, v101 dst_sel:DWORD dst_unused:UNUSED_PAD src0_sel:DWORD src1_sel:WORD_1
	v_or_b32_sdwa v108, v110, v108 dst_sel:DWORD dst_unused:UNUSED_PAD src0_sel:DWORD src1_sel:WORD_1
	global_store_dwordx2 v[106:107], v[108:109], off offset:1056
	v_lshlrev_b32_e32 v108, 16, v160
	v_mul_f32_e32 v101, 0xbfb8aa3b, v108
	v_and_b32_e32 v110, 0xffff0000, v160
	v_exp_f32_e32 v101, v101
	v_mul_f32_e32 v111, 0xbfb8aa3b, v110
	v_exp_f32_e32 v117, v111
	v_lshlrev_b32_e32 v109, 16, v161
	v_add_f32_e32 v101, 1.0, v101
	v_rcp_f32_e32 v116, v101
	v_add_f32_e32 v101, 1.0, v117
	v_rcp_f32_e32 v118, v101
	v_mul_f32_e32 v101, 0xbfb8aa3b, v109
	v_exp_f32_e32 v101, v101
	v_mov_b32_e32 v152, v164
	v_mov_b32_e32 v153, v162
	v_and_b32_e32 v111, 0xffff0000, v161
	v_pk_mul_f32 v[152:153], v[152:153], v[100:101] op_sel_hi:[1,0]
	v_add_f32_e32 v101, 1.0, v101
	v_rcp_f32_e32 v117, v101
	v_mul_f32_e32 v101, 0xbfb8aa3b, v111
	v_exp_f32_e32 v101, v101
	v_mov_b32_e32 v162, v165
	v_pk_mul_f32 v[152:153], v[64:65], v[152:153]
	v_pk_mul_f32 v[108:109], v[116:117], v[108:109]
	v_add_f32_e32 v101, 1.0, v101
	v_rcp_f32_e32 v119, v101
	v_pk_mul_f32 v[116:117], v[162:163], v[100:101] op_sel_hi:[1,0]
	v_pk_mul_f32 v[108:109], v[152:153], v[108:109]
	v_pk_mul_f32 v[116:117], v[58:59], v[116:117]
	v_pk_mul_f32 v[110:111], v[118:119], v[110:111]
	v_and_b32_sdwa v101, v109, v204 dst_sel:DWORD dst_unused:UNUSED_PAD src0_sel:WORD_1 src1_sel:DWORD
	v_pk_mul_f32 v[110:111], v[116:117], v[110:111]
; __device__ __forceinline__ unsigned pk2(float lo, float hi) { return f2bf(lo) | (f2bf(hi) << 16); }
; __device__ __forceinline__ float silu_f(float g) { return g * __builtin_amdgcn_rcpf(1.0f + __expf(-g)); }
; __device__ __forceinline__ void gla_out_unit(const bf16* PROJ, const bf16* ST, const float* norm_o, bf16* Y, int unit, int lane) {
;     ...
; #pragma unroll
;         for (int mi = 0; mi < 8; ++mi) {
;             const int v = h * 128 + 16 * mi + 4 * fq;
;             const f32x4 no = nov[mi]; const u32x2 g2 = gg1[mi];
;             const f32x4 o = acc[mi][ni];
;             const float y0 = o[0] * rs * no[0] * silu_f(bf_lo(g2.x)), y1 = o[1] * rs * no[1] * silu_f(bf_hi(g2.x));
;             const float y2 = o[2] * rs * no[2] * silu_f(bf_lo(g2.y)), y3 = o[3] * rs * no[3] * silu_f(bf_hi(g2.y));
;             u32x2 w; w.x = pk2(y0, y1); w.y = pk2(y2, y3);
;             *(u32x2*)(Y + tok * D + 512 + v) = w;
;         }
	v_and_b32_sdwa v116, v108, v204 dst_sel:DWORD dst_unused:UNUSED_PAD src0_sel:WORD_1 src1_sel:DWORD
	v_add3_u32 v108, v108, v116, s29
	v_add3_u32 v101, v109, v101, s29
	v_and_b32_sdwa v109, v111, v204 dst_sel:DWORD dst_unused:UNUSED_PAD src0_sel:WORD_1 src1_sel:DWORD
	v_and_b32_sdwa v116, v110, v204 dst_sel:DWORD dst_unused:UNUSED_PAD src0_sel:WORD_1 src1_sel:DWORD
	v_add3_u32 v109, v111, v109, s29
	v_add3_u32 v110, v110, v116, s29
	v_and_b32_e32 v109, 0xffff0000, v109
	v_and_b32_e32 v110, 0xffff0000, v110
	v_or_b32_sdwa v109, v109, v101 dst_sel:DWORD dst_unused:UNUSED_PAD src0_sel:DWORD src1_sel:WORD_1
	v_or_b32_sdwa v108, v110, v108 dst_sel:DWORD dst_unused:UNUSED_PAD src0_sel:DWORD src1_sel:WORD_1
	global_store_dwordx2 v[106:107], v[108:109], off offset:1088
	v_lshlrev_b32_e32 v108, 16, v158
	v_mul_f32_e32 v101, 0xbfb8aa3b, v108
	v_and_b32_e32 v110, 0xffff0000, v158
	v_exp_f32_e32 v101, v101
	v_mul_f32_e32 v111, 0xbfb8aa3b, v110
	v_exp_f32_e32 v117, v111
	v_lshlrev_b32_e32 v109, 16, v159
	v_add_f32_e32 v101, 1.0, v101
	v_rcp_f32_e32 v116, v101
	v_add_f32_e32 v101, 1.0, v117
	v_rcp_f32_e32 v118, v101
	v_mul_f32_e32 v101, 0xbfb8aa3b, v109
	v_exp_f32_e32 v101, v101
	v_mov_b32_e32 v152, v126
	v_mov_b32_e32 v153, v124
	v_and_b32_e32 v111, 0xffff0000, v159
	v_pk_mul_f32 v[152:153], v[152:153], v[100:101] op_sel_hi:[1,0]
	v_add_f32_e32 v101, 1.0, v101
	v_rcp_f32_e32 v117, v101
	v_mul_f32_e32 v101, 0xbfb8aa3b, v111
	v_exp_f32_e32 v101, v101
	v_mov_b32_e32 v124, v127
	v_pk_mul_f32 v[152:153], v[56:57], v[152:153]
	v_pk_mul_f32 v[108:109], v[116:117], v[108:109]
	v_add_f32_e32 v101, 1.0, v101
	v_rcp_f32_e32 v119, v101
	v_pk_mul_f32 v[116:117], v[124:125], v[100:101] op_sel_hi:[1,0]
	v_pk_mul_f32 v[108:109], v[152:153], v[108:109]
	v_pk_mul_f32 v[116:117], v[50:51], v[116:117]
	v_pk_mul_f32 v[110:111], v[118:119], v[110:111]
	v_and_b32_sdwa v101, v109, v204 dst_sel:DWORD dst_unused:UNUSED_PAD src0_sel:WORD_1 src1_sel:DWORD
	v_pk_mul_f32 v[110:111], v[116:117], v[110:111]
	v_and_b32_sdwa v116, v108, v204 dst_sel:DWORD dst_unused:UNUSED_PAD src0_sel:WORD_1 src1_sel:DWORD
	v_add3_u32 v108, v108, v116, s29
	v_add3_u32 v101, v109, v101, s29
	v_and_b32_sdwa v109, v111, v204 dst_sel:DWORD dst_unused:UNUSED_PAD src0_sel:WORD_1 src1_sel:DWORD
	v_and_b32_sdwa v116, v110, v204 dst_sel:DWORD dst_unused:UNUSED_PAD src0_sel:WORD_1 src1_sel:DWORD
	v_add3_u32 v109, v111, v109, s29
	v_add3_u32 v110, v110, v116, s29
	v_and_b32_e32 v109, 0xffff0000, v109
	v_and_b32_e32 v110, 0xffff0000, v110
	v_or_b32_sdwa v109, v109, v101 dst_sel:DWORD dst_unused:UNUSED_PAD src0_sel:DWORD src1_sel:WORD_1
	v_or_b32_sdwa v108, v110, v108 dst_sel:DWORD dst_unused:UNUSED_PAD src0_sel:DWORD src1_sel:WORD_1
	global_store_dwordx2 v[106:107], v[108:109], off offset:1120
	v_lshlrev_b32_e32 v108, 16, v156
	v_mul_f32_e32 v101, 0xbfb8aa3b, v108
	v_and_b32_e32 v110, 0xffff0000, v156
	v_exp_f32_e32 v101, v101
	v_mul_f32_e32 v111, 0xbfb8aa3b, v110
	v_exp_f32_e32 v117, v111
	v_lshlrev_b32_e32 v109, 16, v157
	v_add_f32_e32 v101, 1.0, v101
	v_rcp_f32_e32 v116, v101
	v_add_f32_e32 v101, 1.0, v117
	v_rcp_f32_e32 v118, v101
	v_mul_f32_e32 v101, 0xbfb8aa3b, v109
	v_exp_f32_e32 v101, v101
	v_mov_b32_e32 v124, v122
	v_mov_b32_e32 v125, v120
	v_and_b32_e32 v111, 0xffff0000, v157
	v_pk_mul_f32 v[124:125], v[124:125], v[100:101] op_sel_hi:[1,0]
	v_add_f32_e32 v101, 1.0, v101
	v_rcp_f32_e32 v117, v101
	v_mul_f32_e32 v101, 0xbfb8aa3b, v111
	v_exp_f32_e32 v101, v101
	v_mov_b32_e32 v120, v123
	v_pk_mul_f32 v[124:125], v[48:49], v[124:125]
	v_pk_mul_f32 v[108:109], v[116:117], v[108:109]
	v_add_f32_e32 v101, 1.0, v101
	v_rcp_f32_e32 v119, v101
	v_pk_mul_f32 v[116:117], v[120:121], v[100:101] op_sel_hi:[1,0]
	v_pk_mul_f32 v[108:109], v[124:125], v[108:109]
	v_pk_mul_f32 v[116:117], v[46:47], v[116:117]
	v_pk_mul_f32 v[110:111], v[118:119], v[110:111]
	v_and_b32_sdwa v101, v109, v204 dst_sel:DWORD dst_unused:UNUSED_PAD src0_sel:WORD_1 src1_sel:DWORD
	v_pk_mul_f32 v[110:111], v[116:117], v[110:111]
	v_and_b32_sdwa v116, v108, v204 dst_sel:DWORD dst_unused:UNUSED_PAD src0_sel:WORD_1 src1_sel:DWORD
	v_add3_u32 v108, v108, v116, s29
	v_add3_u32 v101, v109, v101, s29
	v_and_b32_sdwa v109, v111, v204 dst_sel:DWORD dst_unused:UNUSED_PAD src0_sel:WORD_1 src1_sel:DWORD
	v_and_b32_sdwa v116, v110, v204 dst_sel:DWORD dst_unused:UNUSED_PAD src0_sel:WORD_1 src1_sel:DWORD
	v_add3_u32 v109, v111, v109, s29
	v_add3_u32 v110, v110, v116, s29
	v_and_b32_e32 v109, 0xffff0000, v109
	v_and_b32_e32 v110, 0xffff0000, v110
	v_or_b32_sdwa v109, v109, v101 dst_sel:DWORD dst_unused:UNUSED_PAD src0_sel:DWORD src1_sel:WORD_1
	v_or_b32_sdwa v108, v110, v108 dst_sel:DWORD dst_unused:UNUSED_PAD src0_sel:DWORD src1_sel:WORD_1
	global_store_dwordx2 v[106:107], v[108:109], off offset:1152
	v_lshlrev_b32_e32 v108, 16, v154
	v_mul_f32_e32 v101, 0xbfb8aa3b, v108
	v_and_b32_e32 v110, 0xffff0000, v154
	v_exp_f32_e32 v101, v101
	v_mul_f32_e32 v111, 0xbfb8aa3b, v110
	v_exp_f32_e32 v117, v111
	v_lshlrev_b32_e32 v109, 16, v155
	v_add_f32_e32 v101, 1.0, v101
	v_rcp_f32_e32 v116, v101
	v_add_f32_e32 v101, 1.0, v117
	v_rcp_f32_e32 v118, v101
	v_mul_f32_e32 v101, 0xbfb8aa3b, v109
	v_exp_f32_e32 v101, v101
	v_mov_b32_e32 v120, v114
	v_mov_b32_e32 v121, v112
	v_and_b32_e32 v111, 0xffff0000, v155
	v_pk_mul_f32 v[120:121], v[120:121], v[100:101] op_sel_hi:[1,0]
	v_add_f32_e32 v101, 1.0, v101
	v_rcp_f32_e32 v117, v101
	v_mul_f32_e32 v101, 0xbfb8aa3b, v111
	v_exp_f32_e32 v101, v101
	v_mov_b32_e32 v112, v115
	v_pk_mul_f32 v[120:121], v[44:45], v[120:121]
	v_pk_mul_f32 v[108:109], v[116:117], v[108:109]
	v_add_f32_e32 v101, 1.0, v101
	v_rcp_f32_e32 v119, v101
; __device__ __forceinline__ unsigned pk2(float lo, float hi) { return f2bf(lo) | (f2bf(hi) << 16); }
; __device__ __forceinline__ float silu_f(float g) { return g * __builtin_amdgcn_rcpf(1.0f + __expf(-g)); }
; __device__ __forceinline__ void gla_out_unit(const bf16* PROJ, const bf16* ST, const float* norm_o, bf16* Y, int unit, int lane) {
;     ...
;         for (int mi = 0; mi < 8; ++mi) gg1[mi] = *(const u32x2*)(PROJ + (size_t)(tok0 + 16 * ni + fr) * NPROJ + 2048 + h * 128 + 16 * mi + 4 * fq);
;         asm volatile("" : "+v"(gg1[0]), "+v"(gg1[1]), "+v"(gg1[2]), "+v"(gg1[3]), "+v"(gg1[4]), "+v"(gg1[5]), "+v"(gg1[6]), "+v"(gg1[7]));
;         float ss = 0.f;
; #pragma unroll
;         for (int mi = 0; mi < 8; ++mi) { acc[mi][ni] = acc[mi][ni] * 0.125f; const f32x4 o = acc[mi][ni]; ss += (o[0] * o[0] + o[1] * o[1]) + (o[2] * o[2] + o[3] * o[3]); }
;         ss += __shfl_xor(ss, 16); ss += __shfl_xor(ss, 32);
;         const float rs = __builtin_amdgcn_rsqf(ss * (1.f / 128.f) + EPS);
;         const size_t tok = (size_t)(tok0 + 16 * ni + fr);
; #pragma unroll
;         for (int mi = 0; mi < 8; ++mi) {
;             const int v = h * 128 + 16 * mi + 4 * fq;
;             const f32x4 no = nov[mi]; const u32x2 g2 = gg1[mi];
;             const f32x4 o = acc[mi][ni];
;             const float y0 = o[0] * rs * no[0] * silu_f(bf_lo(g2.x)), y1 = o[1] * rs * no[1] * silu_f(bf_hi(g2.x));
;             const float y2 = o[2] * rs * no[2] * silu_f(bf_lo(g2.y)), y3 = o[3] * rs * no[3] * silu_f(bf_hi(g2.y));
;             u32x2 w; w.x = pk2(y0, y1); w.y = pk2(y2, y3);
;             *(u32x2*)(Y + tok * D + 512 + v) = w;
;         }
	v_pk_mul_f32 v[112:113], v[112:113], v[100:101] op_sel_hi:[1,0]
	v_pk_mul_f32 v[108:109], v[120:121], v[108:109]
	v_pk_mul_f32 v[112:113], v[42:43], v[112:113]
	v_pk_mul_f32 v[110:111], v[118:119], v[110:111]
	v_and_b32_sdwa v101, v109, v204 dst_sel:DWORD dst_unused:UNUSED_PAD src0_sel:WORD_1 src1_sel:DWORD
	v_pk_mul_f32 v[110:111], v[112:113], v[110:111]
	v_and_b32_sdwa v112, v108, v204 dst_sel:DWORD dst_unused:UNUSED_PAD src0_sel:WORD_1 src1_sel:DWORD
	v_add3_u32 v108, v108, v112, s29
	v_add3_u32 v101, v109, v101, s29
	v_and_b32_sdwa v109, v111, v204 dst_sel:DWORD dst_unused:UNUSED_PAD src0_sel:WORD_1 src1_sel:DWORD
	v_and_b32_sdwa v112, v110, v204 dst_sel:DWORD dst_unused:UNUSED_PAD src0_sel:WORD_1 src1_sel:DWORD
	v_add3_u32 v109, v111, v109, s29
	v_add3_u32 v110, v110, v112, s29
	v_and_b32_e32 v109, 0xffff0000, v109
	v_and_b32_e32 v110, 0xffff0000, v110
	v_or_b32_sdwa v109, v109, v101 dst_sel:DWORD dst_unused:UNUSED_PAD src0_sel:DWORD src1_sel:WORD_1
	v_or_b32_sdwa v108, v110, v108 dst_sel:DWORD dst_unused:UNUSED_PAD src0_sel:DWORD src1_sel:WORD_1
	global_store_dwordx2 v[106:107], v[108:109], off offset:1184
	v_lshlrev_b32_e32 v108, 16, v130
	v_mul_f32_e32 v101, 0xbfb8aa3b, v108
	v_and_b32_e32 v110, 0xffff0000, v130
	v_exp_f32_e32 v101, v101
	v_mul_f32_e32 v111, 0xbfb8aa3b, v110
	v_exp_f32_e32 v113, v111
	v_lshlrev_b32_e32 v109, 16, v131
	v_add_f32_e32 v101, 1.0, v101
	v_rcp_f32_e32 v112, v101
	v_add_f32_e32 v101, 1.0, v113
	v_rcp_f32_e32 v114, v101
	v_mul_f32_e32 v101, 0xbfb8aa3b, v109
	v_exp_f32_e32 v101, v101
	v_mov_b32_e32 v116, v104
	v_mov_b32_e32 v117, v102
	v_and_b32_e32 v111, 0xffff0000, v131
	v_pk_mul_f32 v[116:117], v[116:117], v[100:101] op_sel_hi:[1,0]
	v_add_f32_e32 v101, 1.0, v101
	v_rcp_f32_e32 v113, v101
	v_mul_f32_e32 v101, 0xbfb8aa3b, v111
	v_exp_f32_e32 v101, v101
	v_mov_b32_e32 v102, v105
	v_pk_mul_f32 v[116:117], v[40:41], v[116:117]
	v_pk_mul_f32 v[108:109], v[112:113], v[108:109]
	v_add_f32_e32 v101, 1.0, v101
	v_rcp_f32_e32 v115, v101
	v_pk_mul_f32 v[102:103], v[102:103], v[100:101] op_sel_hi:[1,0]
	v_pk_mul_f32 v[108:109], v[116:117], v[108:109]
	v_pk_mul_f32 v[102:103], v[38:39], v[102:103]
	v_pk_mul_f32 v[104:105], v[114:115], v[110:111]
	v_and_b32_sdwa v101, v109, v204 dst_sel:DWORD dst_unused:UNUSED_PAD src0_sel:WORD_1 src1_sel:DWORD
	v_pk_mul_f32 v[102:103], v[102:103], v[104:105]
	v_and_b32_sdwa v104, v108, v204 dst_sel:DWORD dst_unused:UNUSED_PAD src0_sel:WORD_1 src1_sel:DWORD
	v_add3_u32 v104, v108, v104, s29
	v_and_b32_sdwa v105, v103, v204 dst_sel:DWORD dst_unused:UNUSED_PAD src0_sel:WORD_1 src1_sel:DWORD
	v_and_b32_sdwa v108, v102, v204 dst_sel:DWORD dst_unused:UNUSED_PAD src0_sel:WORD_1 src1_sel:DWORD
	v_add3_u32 v103, v103, v105, s29
	v_add3_u32 v102, v102, v108, s29
	v_add3_u32 v101, v109, v101, s29
	v_and_b32_e32 v103, 0xffff0000, v103
	v_and_b32_e32 v102, 0xffff0000, v102
	v_or_b32_sdwa v103, v103, v101 dst_sel:DWORD dst_unused:UNUSED_PAD src0_sel:DWORD src1_sel:WORD_1
	v_or_b32_sdwa v102, v102, v104 dst_sel:DWORD dst_unused:UNUSED_PAD src0_sel:DWORD src1_sel:WORD_1
	global_store_dwordx2 v[106:107], v[102:103], off offset:1216
	v_lshlrev_b32_e32 v102, 16, v32
	v_mul_f32_e32 v101, 0xbfb8aa3b, v102
	v_and_b32_e32 v32, 0xffff0000, v32
	v_exp_f32_e32 v101, v101
	v_mul_f32_e32 v104, 0xbfb8aa3b, v32
	v_exp_f32_e32 v105, v104
	v_lshlrev_b32_e32 v103, 16, v33
	v_add_f32_e32 v101, 1.0, v101
	v_rcp_f32_e32 v104, v101
	v_add_f32_e32 v101, 1.0, v105
	v_rcp_f32_e32 v108, v101
	v_mul_f32_e32 v101, 0xbfb8aa3b, v103
	v_exp_f32_e32 v101, v101
	v_and_b32_e32 v33, 0xffff0000, v33
	v_mov_b32_e32 v111, v96
	v_mov_b32_e32 v110, v98
	v_add_f32_e32 v96, 1.0, v101
	v_rcp_f32_e32 v105, v96
	v_mul_f32_e32 v96, 0xbfb8aa3b, v33
	v_exp_f32_e32 v96, v96
	v_pk_mul_f32 v[110:111], v[110:111], v[100:101] op_sel_hi:[1,0]
	v_pk_mul_f32 v[102:103], v[104:105], v[102:103]
	v_pk_mul_f32 v[110:111], v[36:37], v[110:111]
	v_add_f32_e32 v96, 1.0, v96
	v_rcp_f32_e32 v109, v96
	v_mov_b32_e32 v96, v99
	v_pk_mul_f32 v[96:97], v[96:97], v[100:101] op_sel_hi:[1,0]
	v_pk_mul_f32 v[102:103], v[110:111], v[102:103]
	v_pk_mul_f32 v[96:97], v[34:35], v[96:97]
	v_pk_mul_f32 v[32:33], v[108:109], v[32:33]
	v_pk_mul_f32 v[116:117], v[92:93], s[12:13] op_sel_hi:[1,0]
	v_pk_mul_f32 v[32:33], v[96:97], v[32:33]
	v_and_b32_sdwa v96, v103, v204 dst_sel:DWORD dst_unused:UNUSED_PAD src0_sel:WORD_1 src1_sel:DWORD
	v_and_b32_sdwa v98, v33, v204 dst_sel:DWORD dst_unused:UNUSED_PAD src0_sel:WORD_1 src1_sel:DWORD
	v_and_b32_sdwa v99, v32, v204 dst_sel:DWORD dst_unused:UNUSED_PAD src0_sel:WORD_1 src1_sel:DWORD
	v_and_b32_sdwa v97, v102, v204 dst_sel:DWORD dst_unused:UNUSED_PAD src0_sel:WORD_1 src1_sel:DWORD
	v_add3_u32 v33, v33, v98, s29
	v_add3_u32 v32, v32, v99, s29
	v_add3_u32 v97, v102, v97, s29
	v_add3_u32 v96, v103, v96, s29
	v_and_b32_e32 v33, 0xffff0000, v33
	v_and_b32_e32 v32, 0xffff0000, v32
	v_or_b32_sdwa v33, v33, v96 dst_sel:DWORD dst_unused:UNUSED_PAD src0_sel:DWORD src1_sel:WORD_1
	v_or_b32_sdwa v32, v32, v97 dst_sel:DWORD dst_unused:UNUSED_PAD src0_sel:DWORD src1_sel:WORD_1
	global_store_dwordx2 v[106:107], v[32:33], off offset:1248
	v_lshl_add_u64 v[32:33], v[150:151], 0, s[4:5]
	v_lshl_add_u64 v[32:33], v[32:33], 0, v[144:145]
	v_lshl_add_u64 v[106:107], v[32:33], 0, s[6:7]
	v_add_co_u32_e32 v32, vcc, s28, v32
	v_pk_mul_f32 v[120:121], v[88:89], s[12:13] op_sel_hi:[1,0]
	s_nop 0
	v_addc_co_u32_e32 v33, vcc, 0, v33, vcc
	global_load_dwordx2 v[110:111], v[106:107], off offset:32 nt
	global_load_dwordx2 v[104:105], v[106:107], off offset:64 nt
	global_load_dwordx2 v[102:103], v[106:107], off offset:96 nt
	global_load_dwordx2 v[100:101], v[106:107], off offset:128 nt
; __device__ __forceinline__ unsigned pk2(float lo, float hi) { return f2bf(lo) | (f2bf(hi) << 16); }
; __device__ __forceinline__ float silu_f(float g) { return g * __builtin_amdgcn_rcpf(1.0f + __expf(-g)); }
; __device__ __forceinline__ void gla_out_unit(const bf16* PROJ, const bf16* ST, const float* norm_o, bf16* Y, int unit, int lane) {
;     ...
;         for (int mi = 0; mi < 8; ++mi) gg1[mi] = *(const u32x2*)(PROJ + (size_t)(tok0 + 16 * ni + fr) * NPROJ + 2048 + h * 128 + 16 * mi + 4 * fq);
;         asm volatile("" : "+v"(gg1[0]), "+v"(gg1[1]), "+v"(gg1[2]), "+v"(gg1[3]), "+v"(gg1[4]), "+v"(gg1[5]), "+v"(gg1[6]), "+v"(gg1[7]));
;         float ss = 0.f;
; #pragma unroll
;         for (int mi = 0; mi < 8; ++mi) { acc[mi][ni] = acc[mi][ni] * 0.125f; const f32x4 o = acc[mi][ni]; ss += (o[0] * o[0] + o[1] * o[1]) + (o[2] * o[2] + o[3] * o[3]); }
;         ss += __shfl_xor(ss, 16); ss += __shfl_xor(ss, 32);
;         const float rs = __builtin_amdgcn_rsqf(ss * (1.f / 128.f) + EPS);
;         const size_t tok = (size_t)(tok0 + 16 * ni + fr);
; #pragma unroll
;         for (int mi = 0; mi < 8; ++mi) {
;             const int v = h * 128 + 16 * mi + 4 * fq;
;             const f32x4 no = nov[mi]; const u32x2 g2 = gg1[mi];
;             const f32x4 o = acc[mi][ni];
;             const float y0 = o[0] * rs * no[0] * silu_f(bf_lo(g2.x)), y1 = o[1] * rs * no[1] * silu_f(bf_hi(g2.x));
;             const float y2 = o[2] * rs * no[2] * silu_f(bf_lo(g2.y)), y3 = o[3] * rs * no[3] * silu_f(bf_hi(g2.y));
;             u32x2 w; w.x = pk2(y0, y1); w.y = pk2(y2, y3);
;             *(u32x2*)(Y + tok * D + 512 + v) = w;
;         }
	global_load_dwordx2 v[112:113], v[32:33], off nt
	global_load_dwordx2 v[98:99], v[106:107], off offset:160 nt
	global_load_dwordx2 v[96:97], v[106:107], off offset:192 nt
	s_nop 0
	global_load_dwordx2 v[32:33], v[106:107], off offset:224 nt
	v_pk_mul_f32 v[114:115], v[94:95], s[12:13] op_sel_hi:[1,0]
	v_pk_mul_f32 v[118:119], v[90:91], s[12:13] op_sel_hi:[1,0]
	v_mov_b32_e32 v90, v117
	v_mov_b32_e32 v91, v121
	v_mov_b32_e32 v88, v116
	v_mov_b32_e32 v89, v120
	v_pk_mul_f32 v[90:91], v[90:91], v[90:91]
	v_mov_b32_e32 v92, v115
	v_mov_b32_e32 v93, v119
	v_pk_fma_f32 v[88:89], v[88:89], v[88:89], v[90:91]
	v_mov_b32_e32 v90, v114
	v_mov_b32_e32 v91, v118
	v_pk_mul_f32 v[92:93], v[92:93], v[92:93]
	v_pk_mul_f32 v[106:107], v[82:83], s[12:13] op_sel_hi:[1,0]
	v_pk_mul_f32 v[108:109], v[80:81], s[12:13] op_sel_hi:[1,0]
	v_pk_fma_f32 v[90:91], v[90:91], v[90:91], v[92:93]
	v_pk_mul_f32 v[80:81], v[106:107], v[106:107]
	v_pk_mul_f32 v[82:83], v[108:109], v[108:109]
	v_pk_add_f32 v[122:123], v[88:89], v[90:91]
	v_pk_mov_b32 v[88:89], v[82:83], v[80:81] op_sel:[1,0]
	v_mov_b32_e32 v83, v81
	v_pk_mul_f32 v[90:91], v[68:69], s[12:13] op_sel_hi:[1,0]
	v_pk_add_f32 v[80:81], v[88:89], v[82:83]
	v_pk_mul_f32 v[88:89], v[70:71], s[12:13] op_sel_hi:[1,0]
	v_mul_f32_e32 v70, v90, v90
	v_pk_add_f32 v[68:69], v[122:123], v[122:123] op_sel:[0,1] op_sel_hi:[1,0]
	v_pk_mul_f32 v[94:95], v[72:73], s[12:13] op_sel_hi:[1,0]
	v_mul_f32_e32 v72, v91, v91
	v_mov_b32_e32 v69, v70
	v_pk_add_f32 v[70:71], v[80:81], v[80:81] op_sel:[0,1] op_sel_hi:[1,0]
	v_pk_mul_f32 v[92:93], v[74:75], s[12:13] op_sel_hi:[1,0]
	v_mov_b32_e32 v71, v72
	v_pk_add_f32 v[68:69], v[68:69], v[70:71]
	v_mul_f32_e32 v70, v95, v95
	v_mul_f32_e32 v73, v88, v88
	v_pk_fma_f32 v[70:71], v[94:95], v[94:95], v[70:71] op_sel_hi:[1,1,0]
	v_mul_f32_e32 v72, v93, v93
	v_mul_f32_e32 v74, v89, v89
	v_mov_b32_e32 v71, v73
	v_pk_fma_f32 v[72:73], v[92:93], v[92:93], v[72:73] op_sel_hi:[1,1,0]
	v_pk_mul_f32 v[80:81], v[62:63], s[12:13] op_sel_hi:[1,0]
	v_mov_b32_e32 v73, v74
	v_pk_mul_f32 v[82:83], v[60:61], s[12:13] op_sel_hi:[1,0]
	v_pk_add_f32 v[70:71], v[70:71], v[72:73]
	v_pk_mul_f32 v[60:61], v[80:81], v[80:81]
	v_pk_mul_f32 v[62:63], v[82:83], v[82:83]
	v_pk_add_f32 v[68:69], v[68:69], v[70:71]
	v_pk_mov_b32 v[70:71], v[62:63], v[60:61] op_sel:[1,0]
	v_mov_b32_e32 v63, v61
	v_pk_add_f32 v[74:75], v[70:71], v[62:63]
	v_pk_mul_f32 v[62:63], v[84:85], s[12:13] op_sel_hi:[1,0]
	v_pk_mul_f32 v[72:73], v[76:77], s[12:13] op_sel_hi:[1,0]
	v_mul_f32_e32 v76, v62, v62
	v_mul_f32_e32 v77, v63, v63
	v_pk_add_f32 v[68:69], v[68:69], v[68:69] op_sel:[0,1] op_sel_hi:[1,0]
	v_pk_add_f32 v[74:75], v[74:75], v[74:75] op_sel:[0,1] op_sel_hi:[1,0]
	v_pk_mul_f32 v[70:71], v[78:79], s[12:13] op_sel_hi:[1,0]
	v_mov_b32_e32 v69, v76
	v_mov_b32_e32 v75, v77
	v_pk_mul_f32 v[60:61], v[86:87], s[12:13] op_sel_hi:[1,0]
	v_pk_add_f32 v[68:69], v[68:69], v[74:75]
	v_mul_f32_e32 v74, v73, v73
	v_mul_f32_e32 v76, v71, v71
	v_mul_f32_e32 v78, v60, v60
	v_mul_f32_e32 v79, v61, v61
	v_pk_fma_f32 v[74:75], v[72:73], v[72:73], v[74:75] op_sel_hi:[1,1,0]
	v_pk_fma_f32 v[76:77], v[70:71], v[70:71], v[76:77] op_sel_hi:[1,1,0]
	v_mov_b32_e32 v75, v78
	v_mov_b32_e32 v77, v79
	v_pk_add_f32 v[74:75], v[74:75], v[76:77]
	s_waitcnt vmcnt(0)
	v_pk_add_f32 v[68:69], v[68:69], v[74:75]
	v_lshlrev_b32_e32 v76, 16, v112
	v_add_f32_e32 v68, v68, v69
	ds_bpermute_b32 v69, v205, v68
	v_and_b32_e32 v78, 0xffff0000, v112
	v_mul_f32_e32 v79, 0xbfb8aa3b, v78
	v_exp_f32_e32 v85, v79
	v_lshlrev_b32_e32 v77, 16, v113
	s_waitcnt lgkmcnt(0)
	v_add_f32_e32 v68, v68, v69
	ds_bpermute_b32 v69, v206, v68
	v_and_b32_e32 v79, 0xffff0000, v113
	v_mov_b32_e32 v112, v116
	v_mov_b32_e32 v113, v114
	v_mov_b32_e32 v114, v117
	s_waitcnt lgkmcnt(0)
	v_add_f32_e32 v68, v68, v69
	v_mul_f32_e32 v69, 0xbfb8aa3b, v76
	v_exp_f32_e32 v69, v69
	v_fmamk_f32 v68, v68, 0x3c000000, v199
	v_rsq_f32_e32 v68, v68
	v_lshlrev_b64 v[74:75], 11, v[148:149]
	v_add_f32_e32 v69, 1.0, v69
	v_rcp_f32_e32 v84, v69
	v_add_f32_e32 v69, 1.0, v85
	v_rcp_f32_e32 v86, v69
	v_mul_f32_e32 v69, 0xbfb8aa3b, v77
	v_exp_f32_e32 v69, v69
	v_lshl_add_u64 v[74:75], v[136:137], 0, v[74:75]
	v_pk_mul_f32 v[112:113], v[112:113], v[68:69] op_sel_hi:[1,0]
	v_add_f32_e32 v69, 1.0, v69
	v_rcp_f32_e32 v85, v69
	v_mul_f32_e32 v69, 0xbfb8aa3b, v79
	v_exp_f32_e32 v69, v69
	v_pk_mul_f32 v[112:113], v[128:129], v[112:113]
	v_pk_mul_f32 v[76:77], v[84:85], v[76:77]
	v_add_f32_e32 v69, 1.0, v69
	v_rcp_f32_e32 v87, v69
	v_pk_mul_f32 v[84:85], v[114:115], v[68:69] op_sel_hi:[1,0]
	v_pk_mul_f32 v[76:77], v[112:113], v[76:77]
	v_pk_mul_f32 v[84:85], v[54:55], v[84:85]
	v_pk_mul_f32 v[78:79], v[86:87], v[78:79]
	v_and_b32_sdwa v69, v77, v204 dst_sel:DWORD dst_unused:UNUSED_PAD src0_sel:WORD_1 src1_sel:DWORD
	v_pk_mul_f32 v[78:79], v[84:85], v[78:79]
	v_and_b32_sdwa v84, v76, v204 dst_sel:DWORD dst_unused:UNUSED_PAD src0_sel:WORD_1 src1_sel:DWORD
	v_add3_u32 v76, v76, v84, s29
	v_add3_u32 v69, v77, v69, s29
	v_and_b32_sdwa v77, v79, v204 dst_sel:DWORD dst_unused:UNUSED_PAD src0_sel:WORD_1 src1_sel:DWORD
	v_and_b32_sdwa v84, v78, v204 dst_sel:DWORD dst_unused:UNUSED_PAD src0_sel:WORD_1 src1_sel:DWORD
	v_add3_u32 v77, v79, v77, s29
	v_add3_u32 v78, v78, v84, s29
	v_and_b32_e32 v77, 0xffff0000, v77
	v_and_b32_e32 v78, 0xffff0000, v78
	v_or_b32_sdwa v77, v77, v69 dst_sel:DWORD dst_unused:UNUSED_PAD src0_sel:DWORD src1_sel:WORD_1
	v_or_b32_sdwa v76, v78, v76 dst_sel:DWORD dst_unused:UNUSED_PAD src0_sel:DWORD src1_sel:WORD_1
	global_store_dwordx2 v[74:75], v[76:77], off offset:1024
	v_lshlrev_b32_e32 v76, 16, v110
	v_mul_f32_e32 v69, 0xbfb8aa3b, v76
; __device__ __forceinline__ unsigned pk2(float lo, float hi) { return f2bf(lo) | (f2bf(hi) << 16); }
; __device__ __forceinline__ float silu_f(float g) { return g * __builtin_amdgcn_rcpf(1.0f + __expf(-g)); }
; __device__ __forceinline__ void gla_out_unit(const bf16* PROJ, const bf16* ST, const float* norm_o, bf16* Y, int unit, int lane) {
;     ...
; #pragma unroll
;         for (int mi = 0; mi < 8; ++mi) {
;             const int v = h * 128 + 16 * mi + 4 * fq;
;             const f32x4 no = nov[mi]; const u32x2 g2 = gg1[mi];
;             const f32x4 o = acc[mi][ni];
;             const float y0 = o[0] * rs * no[0] * silu_f(bf_lo(g2.x)), y1 = o[1] * rs * no[1] * silu_f(bf_hi(g2.x));
;             const float y2 = o[2] * rs * no[2] * silu_f(bf_lo(g2.y)), y3 = o[3] * rs * no[3] * silu_f(bf_hi(g2.y));
;             u32x2 w; w.x = pk2(y0, y1); w.y = pk2(y2, y3);
;             *(u32x2*)(Y + tok * D + 512 + v) = w;
;         }
	v_and_b32_e32 v78, 0xffff0000, v110
	v_exp_f32_e32 v69, v69
	v_mul_f32_e32 v79, 0xbfb8aa3b, v78
	v_exp_f32_e32 v85, v79
	v_lshlrev_b32_e32 v77, 16, v111
	v_add_f32_e32 v69, 1.0, v69
	v_rcp_f32_e32 v84, v69
	v_add_f32_e32 v69, 1.0, v85
	v_rcp_f32_e32 v86, v69
	v_mul_f32_e32 v69, 0xbfb8aa3b, v77
	v_exp_f32_e32 v69, v69
	v_and_b32_e32 v79, 0xffff0000, v111
	v_mov_b32_e32 v110, v120
	v_mov_b32_e32 v111, v118
	v_pk_mul_f32 v[110:111], v[110:111], v[68:69] op_sel_hi:[1,0]
	v_add_f32_e32 v69, 1.0, v69
	v_rcp_f32_e32 v85, v69
	v_mul_f32_e32 v69, 0xbfb8aa3b, v79
	v_exp_f32_e32 v69, v69
	v_mov_b32_e32 v118, v121
	v_pk_mul_f32 v[110:111], v[52:53], v[110:111]
	v_pk_mul_f32 v[76:77], v[84:85], v[76:77]
	v_add_f32_e32 v69, 1.0, v69
	v_rcp_f32_e32 v87, v69
	v_pk_mul_f32 v[84:85], v[118:119], v[68:69] op_sel_hi:[1,0]
	v_pk_mul_f32 v[76:77], v[110:111], v[76:77]
	v_pk_mul_f32 v[84:85], v[66:67], v[84:85]
	v_pk_mul_f32 v[78:79], v[86:87], v[78:79]
	v_and_b32_sdwa v69, v77, v204 dst_sel:DWORD dst_unused:UNUSED_PAD src0_sel:WORD_1 src1_sel:DWORD
	v_pk_mul_f32 v[78:79], v[84:85], v[78:79]
	v_and_b32_sdwa v84, v76, v204 dst_sel:DWORD dst_unused:UNUSED_PAD src0_sel:WORD_1 src1_sel:DWORD
	v_add3_u32 v76, v76, v84, s29
	v_add3_u32 v69, v77, v69, s29
	v_and_b32_sdwa v77, v79, v204 dst_sel:DWORD dst_unused:UNUSED_PAD src0_sel:WORD_1 src1_sel:DWORD
	v_and_b32_sdwa v84, v78, v204 dst_sel:DWORD dst_unused:UNUSED_PAD src0_sel:WORD_1 src1_sel:DWORD
	v_add3_u32 v77, v79, v77, s29
	v_add3_u32 v78, v78, v84, s29
	v_and_b32_e32 v77, 0xffff0000, v77
	v_and_b32_e32 v78, 0xffff0000, v78
	v_or_b32_sdwa v77, v77, v69 dst_sel:DWORD dst_unused:UNUSED_PAD src0_sel:DWORD src1_sel:WORD_1
	v_or_b32_sdwa v76, v78, v76 dst_sel:DWORD dst_unused:UNUSED_PAD src0_sel:DWORD src1_sel:WORD_1
	global_store_dwordx2 v[74:75], v[76:77], off offset:1056
	v_lshlrev_b32_e32 v76, 16, v104
	v_mul_f32_e32 v69, 0xbfb8aa3b, v76
	v_and_b32_e32 v78, 0xffff0000, v104
	v_exp_f32_e32 v69, v69
	v_mul_f32_e32 v79, 0xbfb8aa3b, v78
	v_exp_f32_e32 v85, v79
	v_lshlrev_b32_e32 v77, 16, v105
	v_add_f32_e32 v69, 1.0, v69
	v_rcp_f32_e32 v84, v69
	v_add_f32_e32 v69, 1.0, v85
	v_rcp_f32_e32 v86, v69
	v_mul_f32_e32 v69, 0xbfb8aa3b, v77
	v_exp_f32_e32 v69, v69
	v_and_b32_e32 v79, 0xffff0000, v105
	v_mov_b32_e32 v104, v108
	v_mov_b32_e32 v105, v106
	v_pk_mul_f32 v[104:105], v[104:105], v[68:69] op_sel_hi:[1,0]
	v_add_f32_e32 v69, 1.0, v69
	v_rcp_f32_e32 v85, v69
	v_mul_f32_e32 v69, 0xbfb8aa3b, v79
	v_exp_f32_e32 v69, v69
	v_mov_b32_e32 v106, v109
	v_pk_mul_f32 v[104:105], v[64:65], v[104:105]
	v_pk_mul_f32 v[76:77], v[84:85], v[76:77]
	v_add_f32_e32 v69, 1.0, v69
	v_rcp_f32_e32 v87, v69
	v_pk_mul_f32 v[84:85], v[106:107], v[68:69] op_sel_hi:[1,0]
	v_pk_mul_f32 v[76:77], v[104:105], v[76:77]
	v_pk_mul_f32 v[84:85], v[58:59], v[84:85]
	v_pk_mul_f32 v[78:79], v[86:87], v[78:79]
	v_and_b32_sdwa v69, v77, v204 dst_sel:DWORD dst_unused:UNUSED_PAD src0_sel:WORD_1 src1_sel:DWORD
	v_pk_mul_f32 v[78:79], v[84:85], v[78:79]
	v_and_b32_sdwa v84, v76, v204 dst_sel:DWORD dst_unused:UNUSED_PAD src0_sel:WORD_1 src1_sel:DWORD
	v_add3_u32 v76, v76, v84, s29
	v_add3_u32 v69, v77, v69, s29
	v_and_b32_sdwa v77, v79, v204 dst_sel:DWORD dst_unused:UNUSED_PAD src0_sel:WORD_1 src1_sel:DWORD
	v_and_b32_sdwa v84, v78, v204 dst_sel:DWORD dst_unused:UNUSED_PAD src0_sel:WORD_1 src1_sel:DWORD
	v_add3_u32 v77, v79, v77, s29
	v_add3_u32 v78, v78, v84, s29
	v_and_b32_e32 v77, 0xffff0000, v77
	v_and_b32_e32 v78, 0xffff0000, v78
	v_or_b32_sdwa v77, v77, v69 dst_sel:DWORD dst_unused:UNUSED_PAD src0_sel:DWORD src1_sel:WORD_1
	v_or_b32_sdwa v76, v78, v76 dst_sel:DWORD dst_unused:UNUSED_PAD src0_sel:DWORD src1_sel:WORD_1
	global_store_dwordx2 v[74:75], v[76:77], off offset:1088
	v_lshlrev_b32_e32 v76, 16, v102
	v_mul_f32_e32 v69, 0xbfb8aa3b, v76
	v_and_b32_e32 v78, 0xffff0000, v102
	v_exp_f32_e32 v69, v69
	v_mul_f32_e32 v79, 0xbfb8aa3b, v78
	v_exp_f32_e32 v85, v79
	v_lshlrev_b32_e32 v77, 16, v103
	v_add_f32_e32 v69, 1.0, v69
	v_rcp_f32_e32 v84, v69
	v_add_f32_e32 v69, 1.0, v85
	v_rcp_f32_e32 v86, v69
	v_mul_f32_e32 v69, 0xbfb8aa3b, v77
	v_exp_f32_e32 v69, v69
	v_and_b32_e32 v79, 0xffff0000, v103
	v_mov_b32_e32 v102, v94
	v_mov_b32_e32 v103, v92
	v_pk_mul_f32 v[102:103], v[102:103], v[68:69] op_sel_hi:[1,0]
	v_add_f32_e32 v69, 1.0, v69
	v_rcp_f32_e32 v85, v69
	v_mul_f32_e32 v69, 0xbfb8aa3b, v79
	v_exp_f32_e32 v69, v69
	v_mov_b32_e32 v92, v95
	v_pk_mul_f32 v[102:103], v[56:57], v[102:103]
	v_pk_mul_f32 v[76:77], v[84:85], v[76:77]
	v_add_f32_e32 v69, 1.0, v69
	v_rcp_f32_e32 v87, v69
	v_pk_mul_f32 v[84:85], v[92:93], v[68:69] op_sel_hi:[1,0]
	v_pk_mul_f32 v[76:77], v[102:103], v[76:77]
	v_pk_mul_f32 v[84:85], v[50:51], v[84:85]
	v_pk_mul_f32 v[78:79], v[86:87], v[78:79]
	v_and_b32_sdwa v69, v77, v204 dst_sel:DWORD dst_unused:UNUSED_PAD src0_sel:WORD_1 src1_sel:DWORD
	v_pk_mul_f32 v[78:79], v[84:85], v[78:79]
	v_and_b32_sdwa v84, v76, v204 dst_sel:DWORD dst_unused:UNUSED_PAD src0_sel:WORD_1 src1_sel:DWORD
	v_add3_u32 v76, v76, v84, s29
	v_add3_u32 v69, v77, v69, s29
	v_and_b32_sdwa v77, v79, v204 dst_sel:DWORD dst_unused:UNUSED_PAD src0_sel:WORD_1 src1_sel:DWORD
	v_and_b32_sdwa v84, v78, v204 dst_sel:DWORD dst_unused:UNUSED_PAD src0_sel:WORD_1 src1_sel:DWORD
	v_add3_u32 v77, v79, v77, s29
	v_add3_u32 v78, v78, v84, s29
	v_and_b32_e32 v77, 0xffff0000, v77
	v_and_b32_e32 v78, 0xffff0000, v78
	v_or_b32_sdwa v77, v77, v69 dst_sel:DWORD dst_unused:UNUSED_PAD src0_sel:DWORD src1_sel:WORD_1
	v_or_b32_sdwa v76, v78, v76 dst_sel:DWORD dst_unused:UNUSED_PAD src0_sel:DWORD src1_sel:WORD_1
	global_store_dwordx2 v[74:75], v[76:77], off offset:1120
	v_lshlrev_b32_e32 v76, 16, v100
; __device__ __forceinline__ unsigned pk2(float lo, float hi) { return f2bf(lo) | (f2bf(hi) << 16); }
; __device__ __forceinline__ float silu_f(float g) { return g * __builtin_amdgcn_rcpf(1.0f + __expf(-g)); }
; __device__ __forceinline__ void gla_out_unit(const bf16* PROJ, const bf16* ST, const float* norm_o, bf16* Y, int unit, int lane) {
;     ...
; #pragma unroll
;         for (int mi = 0; mi < 8; ++mi) {
;             const int v = h * 128 + 16 * mi + 4 * fq;
;             const f32x4 no = nov[mi]; const u32x2 g2 = gg1[mi];
;             const f32x4 o = acc[mi][ni];
;             const float y0 = o[0] * rs * no[0] * silu_f(bf_lo(g2.x)), y1 = o[1] * rs * no[1] * silu_f(bf_hi(g2.x));
;             const float y2 = o[2] * rs * no[2] * silu_f(bf_lo(g2.y)), y3 = o[3] * rs * no[3] * silu_f(bf_hi(g2.y));
;             u32x2 w; w.x = pk2(y0, y1); w.y = pk2(y2, y3);
;             *(u32x2*)(Y + tok * D + 512 + v) = w;
;         }
	v_mul_f32_e32 v69, 0xbfb8aa3b, v76
	v_and_b32_e32 v78, 0xffff0000, v100
	v_exp_f32_e32 v69, v69
	v_mul_f32_e32 v79, 0xbfb8aa3b, v78
	v_exp_f32_e32 v85, v79
	v_lshlrev_b32_e32 v77, 16, v101
	v_add_f32_e32 v69, 1.0, v69
	v_rcp_f32_e32 v84, v69
	v_add_f32_e32 v69, 1.0, v85
	v_rcp_f32_e32 v86, v69
	v_mul_f32_e32 v69, 0xbfb8aa3b, v77
	v_exp_f32_e32 v69, v69
	v_mov_b32_e32 v92, v90
	v_mov_b32_e32 v93, v88
	v_and_b32_e32 v79, 0xffff0000, v101
	v_pk_mul_f32 v[92:93], v[92:93], v[68:69] op_sel_hi:[1,0]
	v_add_f32_e32 v69, 1.0, v69
	v_rcp_f32_e32 v85, v69
	v_mul_f32_e32 v69, 0xbfb8aa3b, v79
	v_exp_f32_e32 v69, v69
	v_mov_b32_e32 v88, v91
	v_pk_mul_f32 v[92:93], v[48:49], v[92:93]
	v_pk_mul_f32 v[76:77], v[84:85], v[76:77]
	v_add_f32_e32 v69, 1.0, v69
	v_rcp_f32_e32 v87, v69
	v_pk_mul_f32 v[84:85], v[88:89], v[68:69] op_sel_hi:[1,0]
	v_pk_mul_f32 v[76:77], v[92:93], v[76:77]
	v_pk_mul_f32 v[84:85], v[46:47], v[84:85]
	v_pk_mul_f32 v[78:79], v[86:87], v[78:79]
	v_and_b32_sdwa v69, v77, v204 dst_sel:DWORD dst_unused:UNUSED_PAD src0_sel:WORD_1 src1_sel:DWORD
	v_pk_mul_f32 v[78:79], v[84:85], v[78:79]
	v_and_b32_sdwa v84, v76, v204 dst_sel:DWORD dst_unused:UNUSED_PAD src0_sel:WORD_1 src1_sel:DWORD
	v_add3_u32 v76, v76, v84, s29
	v_add3_u32 v69, v77, v69, s29
	v_and_b32_sdwa v77, v79, v204 dst_sel:DWORD dst_unused:UNUSED_PAD src0_sel:WORD_1 src1_sel:DWORD
	v_and_b32_sdwa v84, v78, v204 dst_sel:DWORD dst_unused:UNUSED_PAD src0_sel:WORD_1 src1_sel:DWORD
	v_add3_u32 v77, v79, v77, s29
	v_add3_u32 v78, v78, v84, s29
	v_and_b32_e32 v77, 0xffff0000, v77
	v_and_b32_e32 v78, 0xffff0000, v78
	v_or_b32_sdwa v77, v77, v69 dst_sel:DWORD dst_unused:UNUSED_PAD src0_sel:DWORD src1_sel:WORD_1
	v_or_b32_sdwa v76, v78, v76 dst_sel:DWORD dst_unused:UNUSED_PAD src0_sel:DWORD src1_sel:WORD_1
	global_store_dwordx2 v[74:75], v[76:77], off offset:1152
	v_lshlrev_b32_e32 v76, 16, v98
	v_mul_f32_e32 v69, 0xbfb8aa3b, v76
	v_and_b32_e32 v78, 0xffff0000, v98
	v_exp_f32_e32 v69, v69
	v_mul_f32_e32 v79, 0xbfb8aa3b, v78
	v_exp_f32_e32 v85, v79
	v_lshlrev_b32_e32 v77, 16, v99
	v_add_f32_e32 v69, 1.0, v69
	v_rcp_f32_e32 v84, v69
	v_add_f32_e32 v69, 1.0, v85
	v_rcp_f32_e32 v86, v69
	v_mul_f32_e32 v69, 0xbfb8aa3b, v77
	v_exp_f32_e32 v69, v69
	v_mov_b32_e32 v88, v82
	v_mov_b32_e32 v89, v80
	v_and_b32_e32 v79, 0xffff0000, v99
	v_pk_mul_f32 v[88:89], v[88:89], v[68:69] op_sel_hi:[1,0]
	v_add_f32_e32 v69, 1.0, v69
	v_rcp_f32_e32 v85, v69
	v_mul_f32_e32 v69, 0xbfb8aa3b, v79
	v_exp_f32_e32 v69, v69
	v_mov_b32_e32 v80, v83
	v_pk_mul_f32 v[88:89], v[44:45], v[88:89]
	v_pk_mul_f32 v[76:77], v[84:85], v[76:77]
	v_add_f32_e32 v69, 1.0, v69
	v_rcp_f32_e32 v87, v69
	v_pk_mul_f32 v[80:81], v[80:81], v[68:69] op_sel_hi:[1,0]
	v_pk_mul_f32 v[76:77], v[88:89], v[76:77]
	v_pk_mul_f32 v[80:81], v[42:43], v[80:81]
	v_pk_mul_f32 v[78:79], v[86:87], v[78:79]
	v_and_b32_sdwa v69, v77, v204 dst_sel:DWORD dst_unused:UNUSED_PAD src0_sel:WORD_1 src1_sel:DWORD
	v_pk_mul_f32 v[78:79], v[80:81], v[78:79]
	v_and_b32_sdwa v80, v76, v204 dst_sel:DWORD dst_unused:UNUSED_PAD src0_sel:WORD_1 src1_sel:DWORD
	v_add3_u32 v76, v76, v80, s29
	v_add3_u32 v69, v77, v69, s29
	v_and_b32_sdwa v77, v79, v204 dst_sel:DWORD dst_unused:UNUSED_PAD src0_sel:WORD_1 src1_sel:DWORD
	v_and_b32_sdwa v80, v78, v204 dst_sel:DWORD dst_unused:UNUSED_PAD src0_sel:WORD_1 src1_sel:DWORD
	v_add3_u32 v77, v79, v77, s29
	v_add3_u32 v78, v78, v80, s29
	v_and_b32_e32 v77, 0xffff0000, v77
	v_and_b32_e32 v78, 0xffff0000, v78
	v_or_b32_sdwa v77, v77, v69 dst_sel:DWORD dst_unused:UNUSED_PAD src0_sel:DWORD src1_sel:WORD_1
	v_or_b32_sdwa v76, v78, v76 dst_sel:DWORD dst_unused:UNUSED_PAD src0_sel:DWORD src1_sel:WORD_1
	global_store_dwordx2 v[74:75], v[76:77], off offset:1184
	v_lshlrev_b32_e32 v76, 16, v96
	v_mul_f32_e32 v69, 0xbfb8aa3b, v76
	v_and_b32_e32 v78, 0xffff0000, v96
	v_exp_f32_e32 v69, v69
	v_mul_f32_e32 v79, 0xbfb8aa3b, v78
	v_exp_f32_e32 v81, v79
	v_lshlrev_b32_e32 v77, 16, v97
	v_add_f32_e32 v69, 1.0, v69
	v_rcp_f32_e32 v80, v69
	v_add_f32_e32 v69, 1.0, v81
	v_rcp_f32_e32 v82, v69
	v_mul_f32_e32 v69, 0xbfb8aa3b, v77
	v_exp_f32_e32 v69, v69
	v_mov_b32_e32 v84, v72
	v_mov_b32_e32 v85, v70
	v_and_b32_e32 v79, 0xffff0000, v97
	v_pk_mul_f32 v[84:85], v[84:85], v[68:69] op_sel_hi:[1,0]
	v_add_f32_e32 v69, 1.0, v69
	v_rcp_f32_e32 v81, v69
	v_mul_f32_e32 v69, 0xbfb8aa3b, v79
	v_exp_f32_e32 v69, v69
	v_mov_b32_e32 v70, v73
	v_pk_mul_f32 v[84:85], v[40:41], v[84:85]
	v_pk_mul_f32 v[76:77], v[80:81], v[76:77]
	v_add_f32_e32 v69, 1.0, v69
	v_rcp_f32_e32 v83, v69
	v_pk_mul_f32 v[70:71], v[70:71], v[68:69] op_sel_hi:[1,0]
	v_pk_mul_f32 v[76:77], v[84:85], v[76:77]
	v_pk_mul_f32 v[70:71], v[38:39], v[70:71]
	v_pk_mul_f32 v[72:73], v[82:83], v[78:79]
	v_and_b32_sdwa v69, v77, v204 dst_sel:DWORD dst_unused:UNUSED_PAD src0_sel:WORD_1 src1_sel:DWORD
	v_pk_mul_f32 v[70:71], v[70:71], v[72:73]
	v_and_b32_sdwa v72, v76, v204 dst_sel:DWORD dst_unused:UNUSED_PAD src0_sel:WORD_1 src1_sel:DWORD
	v_add3_u32 v72, v76, v72, s29
	v_and_b32_sdwa v73, v71, v204 dst_sel:DWORD dst_unused:UNUSED_PAD src0_sel:WORD_1 src1_sel:DWORD
	v_and_b32_sdwa v76, v70, v204 dst_sel:DWORD dst_unused:UNUSED_PAD src0_sel:WORD_1 src1_sel:DWORD
	v_add3_u32 v71, v71, v73, s29
	v_add3_u32 v70, v70, v76, s29
	v_add3_u32 v69, v77, v69, s29
	v_and_b32_e32 v71, 0xffff0000, v71
	v_and_b32_e32 v70, 0xffff0000, v70
	v_or_b32_sdwa v71, v71, v69 dst_sel:DWORD dst_unused:UNUSED_PAD src0_sel:DWORD src1_sel:WORD_1
	v_or_b32_sdwa v70, v70, v72 dst_sel:DWORD dst_unused:UNUSED_PAD src0_sel:DWORD src1_sel:WORD_1
	global_store_dwordx2 v[74:75], v[70:71], off offset:1216
	v_lshlrev_b32_e32 v70, 16, v32
; __device__ __forceinline__ unsigned pk2(float lo, float hi) { return f2bf(lo) | (f2bf(hi) << 16); }
; __device__ __forceinline__ float silu_f(float g) { return g * __builtin_amdgcn_rcpf(1.0f + __expf(-g)); }
; __device__ __forceinline__ void gla_out_unit(const bf16* PROJ, const bf16* ST, const float* norm_o, bf16* Y, int unit, int lane) {
;     ...
;         for (int mi = 0; mi < 8; ++mi) gg1[mi] = *(const u32x2*)(PROJ + (size_t)(tok0 + 16 * ni + fr) * NPROJ + 2048 + h * 128 + 16 * mi + 4 * fq);
;         asm volatile("" : "+v"(gg1[0]), "+v"(gg1[1]), "+v"(gg1[2]), "+v"(gg1[3]), "+v"(gg1[4]), "+v"(gg1[5]), "+v"(gg1[6]), "+v"(gg1[7]));
;         float ss = 0.f;
; #pragma unroll
;         for (int mi = 0; mi < 8; ++mi) { acc[mi][ni] = acc[mi][ni] * 0.125f; const f32x4 o = acc[mi][ni]; ss += (o[0] * o[0] + o[1] * o[1]) + (o[2] * o[2] + o[3] * o[3]); }
;         ss += __shfl_xor(ss, 16); ss += __shfl_xor(ss, 32);
;         const float rs = __builtin_amdgcn_rsqf(ss * (1.f / 128.f) + EPS);
;         const size_t tok = (size_t)(tok0 + 16 * ni + fr);
; #pragma unroll
;         for (int mi = 0; mi < 8; ++mi) {
;             const int v = h * 128 + 16 * mi + 4 * fq;
;             const f32x4 no = nov[mi]; const u32x2 g2 = gg1[mi];
;             const f32x4 o = acc[mi][ni];
;             const float y0 = o[0] * rs * no[0] * silu_f(bf_lo(g2.x)), y1 = o[1] * rs * no[1] * silu_f(bf_hi(g2.x));
;             const float y2 = o[2] * rs * no[2] * silu_f(bf_lo(g2.y)), y3 = o[3] * rs * no[3] * silu_f(bf_hi(g2.y));
;             u32x2 w; w.x = pk2(y0, y1); w.y = pk2(y2, y3);
;             *(u32x2*)(Y + tok * D + 512 + v) = w;
;         }
	v_mul_f32_e32 v69, 0xbfb8aa3b, v70
	v_and_b32_e32 v32, 0xffff0000, v32
	v_exp_f32_e32 v69, v69
	v_mul_f32_e32 v72, 0xbfb8aa3b, v32
	v_exp_f32_e32 v73, v72
	v_lshlrev_b32_e32 v71, 16, v33
	v_add_f32_e32 v69, 1.0, v69
	v_rcp_f32_e32 v72, v69
	v_add_f32_e32 v69, 1.0, v73
	v_rcp_f32_e32 v76, v69
	v_mul_f32_e32 v69, 0xbfb8aa3b, v71
	v_exp_f32_e32 v69, v69
	v_and_b32_e32 v33, 0xffff0000, v33
	v_mov_b32_e32 v79, v60
	v_mov_b32_e32 v78, v62
	v_add_f32_e32 v60, 1.0, v69
	v_rcp_f32_e32 v73, v60
	v_mul_f32_e32 v60, 0xbfb8aa3b, v33
	v_exp_f32_e32 v60, v60
	v_pk_mul_f32 v[78:79], v[78:79], v[68:69] op_sel_hi:[1,0]
	v_pk_mul_f32 v[70:71], v[72:73], v[70:71]
	v_pk_mul_f32 v[78:79], v[36:37], v[78:79]
	v_add_f32_e32 v60, 1.0, v60
	v_rcp_f32_e32 v77, v60
	v_mov_b32_e32 v60, v63
	v_pk_mul_f32 v[60:61], v[60:61], v[68:69] op_sel_hi:[1,0]
	v_pk_mul_f32 v[70:71], v[78:79], v[70:71]
	v_pk_mul_f32 v[60:61], v[34:35], v[60:61]
	v_pk_mul_f32 v[32:33], v[76:77], v[32:33]
	v_pk_mul_f32 v[84:85], v[28:29], s[12:13] op_sel_hi:[1,0]
	v_pk_mul_f32 v[32:33], v[60:61], v[32:33]
	v_and_b32_sdwa v60, v71, v204 dst_sel:DWORD dst_unused:UNUSED_PAD src0_sel:WORD_1 src1_sel:DWORD
	v_and_b32_sdwa v62, v33, v204 dst_sel:DWORD dst_unused:UNUSED_PAD src0_sel:WORD_1 src1_sel:DWORD
	v_and_b32_sdwa v63, v32, v204 dst_sel:DWORD dst_unused:UNUSED_PAD src0_sel:WORD_1 src1_sel:DWORD
	v_and_b32_sdwa v61, v70, v204 dst_sel:DWORD dst_unused:UNUSED_PAD src0_sel:WORD_1 src1_sel:DWORD
	v_add3_u32 v33, v33, v62, s29
	v_add3_u32 v32, v32, v63, s29
	v_add3_u32 v61, v70, v61, s29
	v_add3_u32 v60, v71, v60, s29
	v_and_b32_e32 v33, 0xffff0000, v33
	v_and_b32_e32 v32, 0xffff0000, v32
	v_or_b32_sdwa v33, v33, v60 dst_sel:DWORD dst_unused:UNUSED_PAD src0_sel:DWORD src1_sel:WORD_1
	v_or_b32_sdwa v32, v32, v61 dst_sel:DWORD dst_unused:UNUSED_PAD src0_sel:DWORD src1_sel:WORD_1
	global_store_dwordx2 v[74:75], v[32:33], off offset:1248
	v_lshl_add_u64 v[32:33], v[146:147], 0, s[4:5]
	v_lshl_add_u64 v[32:33], v[32:33], 0, v[144:145]
	v_lshl_add_u64 v[74:75], v[32:33], 0, s[6:7]
	v_add_co_u32_e32 v76, vcc, s28, v32
	v_pk_mul_f32 v[88:89], v[24:25], s[12:13] op_sel_hi:[1,0]
	s_nop 0
	v_addc_co_u32_e32 v77, vcc, 0, v33, vcc
	global_load_dwordx2 v[78:79], v[74:75], off offset:32 nt
	global_load_dwordx2 v[72:73], v[74:75], off offset:64 nt
	global_load_dwordx2 v[70:71], v[74:75], off offset:96 nt
	global_load_dwordx2 v[68:69], v[74:75], off offset:128 nt
	global_load_dwordx2 v[80:81], v[76:77], off nt
	global_load_dwordx2 v[62:63], v[74:75], off offset:160 nt
	global_load_dwordx2 v[60:61], v[74:75], off offset:192 nt
	global_load_dwordx2 v[32:33], v[74:75], off offset:224 nt
	v_pk_mul_f32 v[82:83], v[30:31], s[12:13] op_sel_hi:[1,0]
	v_pk_mul_f32 v[86:87], v[26:27], s[12:13] op_sel_hi:[1,0]
	v_mov_b32_e32 v26, v85
	v_mov_b32_e32 v27, v89
	v_mov_b32_e32 v24, v84
	v_mov_b32_e32 v25, v88
	v_pk_mul_f32 v[26:27], v[26:27], v[26:27]
	v_mov_b32_e32 v28, v83
	v_mov_b32_e32 v29, v87
	v_pk_fma_f32 v[24:25], v[24:25], v[24:25], v[26:27]
	v_mov_b32_e32 v26, v82
	v_mov_b32_e32 v27, v86
	v_pk_mul_f32 v[28:29], v[28:29], v[28:29]
	v_pk_mul_f32 v[74:75], v[14:15], s[12:13] op_sel_hi:[1,0]
	v_pk_mul_f32 v[76:77], v[12:13], s[12:13] op_sel_hi:[1,0]
	v_pk_fma_f32 v[26:27], v[26:27], v[26:27], v[28:29]
	v_pk_mul_f32 v[12:13], v[74:75], v[74:75]
	v_pk_mul_f32 v[14:15], v[76:77], v[76:77]
	v_pk_add_f32 v[90:91], v[24:25], v[26:27]
	v_pk_mov_b32 v[24:25], v[14:15], v[12:13] op_sel:[1,0]
	v_mov_b32_e32 v15, v13
	v_pk_mul_f32 v[26:27], v[4:5], s[12:13] op_sel_hi:[1,0]
	v_pk_add_f32 v[12:13], v[24:25], v[14:15]
	v_pk_mul_f32 v[24:25], v[6:7], s[12:13] op_sel_hi:[1,0]
	v_mul_f32_e32 v6, v26, v26
	v_pk_add_f32 v[4:5], v[90:91], v[90:91] op_sel:[0,1] op_sel_hi:[1,0]
	v_pk_mul_f32 v[30:31], v[8:9], s[12:13] op_sel_hi:[1,0]
	v_mul_f32_e32 v8, v27, v27
	v_mov_b32_e32 v5, v6
	v_pk_add_f32 v[6:7], v[12:13], v[12:13] op_sel:[0,1] op_sel_hi:[1,0]
	v_pk_mul_f32 v[28:29], v[10:11], s[12:13] op_sel_hi:[1,0]
	v_mov_b32_e32 v7, v8
	v_pk_add_f32 v[4:5], v[4:5], v[6:7]
	v_mul_f32_e32 v6, v31, v31
	v_mul_f32_e32 v9, v24, v24
	v_pk_fma_f32 v[6:7], v[30:31], v[30:31], v[6:7] op_sel_hi:[1,1,0]
	v_mul_f32_e32 v8, v29, v29
	v_mul_f32_e32 v10, v25, v25
	v_mov_b32_e32 v7, v9
	v_pk_fma_f32 v[8:9], v[28:29], v[28:29], v[8:9] op_sel_hi:[1,1,0]
	v_pk_mul_f32 v[12:13], v[2:3], s[12:13] op_sel_hi:[1,0]
	v_mov_b32_e32 v9, v10
	v_pk_mul_f32 v[14:15], v[0:1], s[12:13] op_sel_hi:[1,0]
	v_pk_add_f32 v[6:7], v[6:7], v[8:9]
	v_pk_mul_f32 v[0:1], v[12:13], v[12:13]
	v_pk_mul_f32 v[2:3], v[14:15], v[14:15]
	v_pk_add_f32 v[4:5], v[4:5], v[6:7]
	v_pk_mov_b32 v[6:7], v[2:3], v[0:1] op_sel:[1,0]
	v_mov_b32_e32 v3, v1
	v_pk_add_f32 v[10:11], v[6:7], v[2:3]
	v_pk_mul_f32 v[2:3], v[20:21], s[12:13] op_sel_hi:[1,0]
	v_pk_mul_f32 v[8:9], v[16:17], s[12:13] op_sel_hi:[1,0]
	v_mul_f32_e32 v16, v2, v2
	v_mul_f32_e32 v17, v3, v3
	v_pk_add_f32 v[4:5], v[4:5], v[4:5] op_sel:[0,1] op_sel_hi:[1,0]
	v_pk_add_f32 v[10:11], v[10:11], v[10:11] op_sel:[0,1] op_sel_hi:[1,0]
	v_pk_mul_f32 v[6:7], v[18:19], s[12:13] op_sel_hi:[1,0]
	v_mov_b32_e32 v5, v16
	v_mov_b32_e32 v11, v17
	v_pk_mul_f32 v[0:1], v[22:23], s[12:13] op_sel_hi:[1,0]
	v_pk_add_f32 v[4:5], v[4:5], v[10:11]
	v_mul_f32_e32 v10, v9, v9
	v_mul_f32_e32 v16, v7, v7
	v_mul_f32_e32 v18, v0, v0
	v_mul_f32_e32 v19, v1, v1
	v_pk_fma_f32 v[10:11], v[8:9], v[8:9], v[10:11] op_sel_hi:[1,1,0]
	v_pk_fma_f32 v[16:17], v[6:7], v[6:7], v[16:17] op_sel_hi:[1,1,0]
	v_mov_b32_e32 v11, v18
	v_mov_b32_e32 v17, v19
	v_pk_add_f32 v[10:11], v[10:11], v[16:17]
	s_waitcnt vmcnt(0)
; __device__ __forceinline__ unsigned pk2(float lo, float hi) { return f2bf(lo) | (f2bf(hi) << 16); }
; __device__ __forceinline__ float silu_f(float g) { return g * __builtin_amdgcn_rcpf(1.0f + __expf(-g)); }
; __device__ __forceinline__ void gla_out_unit(const bf16* PROJ, const bf16* ST, const float* norm_o, bf16* Y, int unit, int lane) {
;     ...
;         ss += __shfl_xor(ss, 16); ss += __shfl_xor(ss, 32);
;         const float rs = __builtin_amdgcn_rsqf(ss * (1.f / 128.f) + EPS);
;         const size_t tok = (size_t)(tok0 + 16 * ni + fr);
; #pragma unroll
;         for (int mi = 0; mi < 8; ++mi) {
;             const int v = h * 128 + 16 * mi + 4 * fq;
;             const f32x4 no = nov[mi]; const u32x2 g2 = gg1[mi];
;             const f32x4 o = acc[mi][ni];
;             const float y0 = o[0] * rs * no[0] * silu_f(bf_lo(g2.x)), y1 = o[1] * rs * no[1] * silu_f(bf_hi(g2.x));
;             const float y2 = o[2] * rs * no[2] * silu_f(bf_lo(g2.y)), y3 = o[3] * rs * no[3] * silu_f(bf_hi(g2.y));
;             u32x2 w; w.x = pk2(y0, y1); w.y = pk2(y2, y3);
;             *(u32x2*)(Y + tok * D + 512 + v) = w;
;         }
	v_pk_add_f32 v[4:5], v[4:5], v[10:11]
	v_lshlrev_b32_e32 v16, 16, v80
	v_add_f32_e32 v4, v4, v5
	ds_bpermute_b32 v5, v205, v4
	v_and_b32_e32 v18, 0xffff0000, v80
	v_mul_f32_e32 v19, 0xbfb8aa3b, v18
	v_exp_f32_e32 v21, v19
	v_lshlrev_b32_e32 v17, 16, v81
	s_waitcnt lgkmcnt(0)
	v_add_f32_e32 v4, v4, v5
	ds_bpermute_b32 v5, v206, v4
	v_and_b32_e32 v19, 0xffff0000, v81
	v_mov_b32_e32 v80, v84
	v_mov_b32_e32 v81, v82
	v_mov_b32_e32 v82, v85
	s_waitcnt lgkmcnt(0)
	v_add_f32_e32 v4, v4, v5
	v_mul_f32_e32 v5, 0xbfb8aa3b, v16
	v_exp_f32_e32 v5, v5
	v_fmamk_f32 v4, v4, 0x3c000000, v199
	v_rsq_f32_e32 v4, v4
	v_lshlrev_b64 v[10:11], 11, v[142:143]
	v_add_f32_e32 v5, 1.0, v5
	v_rcp_f32_e32 v20, v5
	v_add_f32_e32 v5, 1.0, v21
	v_rcp_f32_e32 v22, v5
	v_mul_f32_e32 v5, 0xbfb8aa3b, v17
	v_exp_f32_e32 v5, v5
	v_lshl_add_u64 v[10:11], v[136:137], 0, v[10:11]
	v_pk_mul_f32 v[80:81], v[80:81], v[4:5] op_sel_hi:[1,0]
	v_add_f32_e32 v5, 1.0, v5
	v_rcp_f32_e32 v21, v5
	v_mul_f32_e32 v5, 0xbfb8aa3b, v19
	v_exp_f32_e32 v5, v5
	v_pk_mul_f32 v[80:81], v[128:129], v[80:81]
	v_pk_mul_f32 v[16:17], v[20:21], v[16:17]
	v_add_f32_e32 v5, 1.0, v5
	v_rcp_f32_e32 v23, v5
	v_pk_mul_f32 v[20:21], v[82:83], v[4:5] op_sel_hi:[1,0]
	v_pk_mul_f32 v[16:17], v[80:81], v[16:17]
	v_pk_mul_f32 v[20:21], v[54:55], v[20:21]
	v_pk_mul_f32 v[18:19], v[22:23], v[18:19]
	v_and_b32_sdwa v5, v17, v204 dst_sel:DWORD dst_unused:UNUSED_PAD src0_sel:WORD_1 src1_sel:DWORD
	v_pk_mul_f32 v[18:19], v[20:21], v[18:19]
	v_and_b32_sdwa v20, v16, v204 dst_sel:DWORD dst_unused:UNUSED_PAD src0_sel:WORD_1 src1_sel:DWORD
	v_add3_u32 v16, v16, v20, s29
	v_add3_u32 v5, v17, v5, s29
	v_and_b32_sdwa v17, v19, v204 dst_sel:DWORD dst_unused:UNUSED_PAD src0_sel:WORD_1 src1_sel:DWORD
	v_and_b32_sdwa v20, v18, v204 dst_sel:DWORD dst_unused:UNUSED_PAD src0_sel:WORD_1 src1_sel:DWORD
	v_add3_u32 v17, v19, v17, s29
	v_add3_u32 v18, v18, v20, s29
	v_and_b32_e32 v17, 0xffff0000, v17
	v_and_b32_e32 v18, 0xffff0000, v18
	v_or_b32_sdwa v17, v17, v5 dst_sel:DWORD dst_unused:UNUSED_PAD src0_sel:DWORD src1_sel:WORD_1
	v_or_b32_sdwa v16, v18, v16 dst_sel:DWORD dst_unused:UNUSED_PAD src0_sel:DWORD src1_sel:WORD_1
	global_store_dwordx2 v[10:11], v[16:17], off offset:1024
	v_lshlrev_b32_e32 v16, 16, v78
	v_mul_f32_e32 v5, 0xbfb8aa3b, v16
	v_and_b32_e32 v18, 0xffff0000, v78
	v_exp_f32_e32 v5, v5
	v_mul_f32_e32 v19, 0xbfb8aa3b, v18
	v_exp_f32_e32 v21, v19
	v_lshlrev_b32_e32 v17, 16, v79
	v_add_f32_e32 v5, 1.0, v5
	v_rcp_f32_e32 v20, v5
	v_add_f32_e32 v5, 1.0, v21
	v_rcp_f32_e32 v22, v5
	v_mul_f32_e32 v5, 0xbfb8aa3b, v17
	v_exp_f32_e32 v5, v5
	v_mov_b32_e32 v54, v88
	v_mov_b32_e32 v55, v86
	v_and_b32_e32 v19, 0xffff0000, v79
	v_pk_mul_f32 v[54:55], v[54:55], v[4:5] op_sel_hi:[1,0]
	v_add_f32_e32 v5, 1.0, v5
	v_rcp_f32_e32 v21, v5
	v_mul_f32_e32 v5, 0xbfb8aa3b, v19
	v_exp_f32_e32 v5, v5
	v_mov_b32_e32 v86, v89
	v_pk_mul_f32 v[52:53], v[52:53], v[54:55]
	v_pk_mul_f32 v[16:17], v[20:21], v[16:17]
	v_add_f32_e32 v5, 1.0, v5
	v_rcp_f32_e32 v23, v5
	v_pk_mul_f32 v[20:21], v[86:87], v[4:5] op_sel_hi:[1,0]
	v_pk_mul_f32 v[16:17], v[52:53], v[16:17]
	v_pk_mul_f32 v[20:21], v[66:67], v[20:21]
	v_pk_mul_f32 v[18:19], v[22:23], v[18:19]
	v_and_b32_sdwa v5, v17, v204 dst_sel:DWORD dst_unused:UNUSED_PAD src0_sel:WORD_1 src1_sel:DWORD
	v_pk_mul_f32 v[18:19], v[20:21], v[18:19]
	v_and_b32_sdwa v20, v16, v204 dst_sel:DWORD dst_unused:UNUSED_PAD src0_sel:WORD_1 src1_sel:DWORD
	v_add3_u32 v16, v16, v20, s29
	v_add3_u32 v5, v17, v5, s29
	v_and_b32_sdwa v17, v19, v204 dst_sel:DWORD dst_unused:UNUSED_PAD src0_sel:WORD_1 src1_sel:DWORD
	v_and_b32_sdwa v20, v18, v204 dst_sel:DWORD dst_unused:UNUSED_PAD src0_sel:WORD_1 src1_sel:DWORD
	v_add3_u32 v17, v19, v17, s29
	v_add3_u32 v18, v18, v20, s29
	v_and_b32_e32 v17, 0xffff0000, v17
	v_and_b32_e32 v18, 0xffff0000, v18
	v_or_b32_sdwa v17, v17, v5 dst_sel:DWORD dst_unused:UNUSED_PAD src0_sel:DWORD src1_sel:WORD_1
	v_or_b32_sdwa v16, v18, v16 dst_sel:DWORD dst_unused:UNUSED_PAD src0_sel:DWORD src1_sel:WORD_1
	global_store_dwordx2 v[10:11], v[16:17], off offset:1056
	v_lshlrev_b32_e32 v16, 16, v72
	v_mul_f32_e32 v5, 0xbfb8aa3b, v16
	v_and_b32_e32 v18, 0xffff0000, v72
	v_exp_f32_e32 v5, v5
	v_mul_f32_e32 v19, 0xbfb8aa3b, v18
	v_exp_f32_e32 v21, v19
	v_lshlrev_b32_e32 v17, 16, v73
	v_add_f32_e32 v5, 1.0, v5
	v_rcp_f32_e32 v20, v5
	v_add_f32_e32 v5, 1.0, v21
	v_rcp_f32_e32 v22, v5
	v_mul_f32_e32 v5, 0xbfb8aa3b, v17
	v_exp_f32_e32 v5, v5
	v_mov_b32_e32 v52, v76
	v_mov_b32_e32 v53, v74
	v_and_b32_e32 v19, 0xffff0000, v73
	v_pk_mul_f32 v[52:53], v[52:53], v[4:5] op_sel_hi:[1,0]
	v_add_f32_e32 v5, 1.0, v5
	v_rcp_f32_e32 v21, v5
	v_mul_f32_e32 v5, 0xbfb8aa3b, v19
	v_exp_f32_e32 v5, v5
	v_mov_b32_e32 v74, v77
	v_pk_mul_f32 v[52:53], v[64:65], v[52:53]
	v_pk_mul_f32 v[16:17], v[20:21], v[16:17]
	v_add_f32_e32 v5, 1.0, v5
	v_rcp_f32_e32 v23, v5
	v_pk_mul_f32 v[20:21], v[74:75], v[4:5] op_sel_hi:[1,0]
	v_pk_mul_f32 v[16:17], v[52:53], v[16:17]
	v_pk_mul_f32 v[20:21], v[58:59], v[20:21]
	v_pk_mul_f32 v[18:19], v[22:23], v[18:19]
	v_and_b32_sdwa v5, v17, v204 dst_sel:DWORD dst_unused:UNUSED_PAD src0_sel:WORD_1 src1_sel:DWORD
	v_pk_mul_f32 v[18:19], v[20:21], v[18:19]
	v_and_b32_sdwa v20, v16, v204 dst_sel:DWORD dst_unused:UNUSED_PAD src0_sel:WORD_1 src1_sel:DWORD
	v_add3_u32 v16, v16, v20, s29
	v_add3_u32 v5, v17, v5, s29
	v_and_b32_sdwa v17, v19, v204 dst_sel:DWORD dst_unused:UNUSED_PAD src0_sel:WORD_1 src1_sel:DWORD
	v_and_b32_sdwa v20, v18, v204 dst_sel:DWORD dst_unused:UNUSED_PAD src0_sel:WORD_1 src1_sel:DWORD
	v_add3_u32 v17, v19, v17, s29
	v_add3_u32 v18, v18, v20, s29
	v_and_b32_e32 v17, 0xffff0000, v17
; __device__ __forceinline__ unsigned pk2(float lo, float hi) { return f2bf(lo) | (f2bf(hi) << 16); }
; __device__ __forceinline__ float silu_f(float g) { return g * __builtin_amdgcn_rcpf(1.0f + __expf(-g)); }
; __device__ __forceinline__ void gla_out_unit(const bf16* PROJ, const bf16* ST, const float* norm_o, bf16* Y, int unit, int lane) {
;     ...
; #pragma unroll
;         for (int mi = 0; mi < 8; ++mi) {
;             const int v = h * 128 + 16 * mi + 4 * fq;
;             const f32x4 no = nov[mi]; const u32x2 g2 = gg1[mi];
;             const f32x4 o = acc[mi][ni];
;             const float y0 = o[0] * rs * no[0] * silu_f(bf_lo(g2.x)), y1 = o[1] * rs * no[1] * silu_f(bf_hi(g2.x));
;             const float y2 = o[2] * rs * no[2] * silu_f(bf_lo(g2.y)), y3 = o[3] * rs * no[3] * silu_f(bf_hi(g2.y));
;             u32x2 w; w.x = pk2(y0, y1); w.y = pk2(y2, y3);
;             *(u32x2*)(Y + tok * D + 512 + v) = w;
;         }
	v_and_b32_e32 v18, 0xffff0000, v18
	v_or_b32_sdwa v17, v17, v5 dst_sel:DWORD dst_unused:UNUSED_PAD src0_sel:DWORD src1_sel:WORD_1
	v_or_b32_sdwa v16, v18, v16 dst_sel:DWORD dst_unused:UNUSED_PAD src0_sel:DWORD src1_sel:WORD_1
	global_store_dwordx2 v[10:11], v[16:17], off offset:1088
	v_lshlrev_b32_e32 v16, 16, v70
	v_mul_f32_e32 v5, 0xbfb8aa3b, v16
	v_and_b32_e32 v18, 0xffff0000, v70
	v_exp_f32_e32 v5, v5
	v_mul_f32_e32 v19, 0xbfb8aa3b, v18
	v_exp_f32_e32 v21, v19
	v_lshlrev_b32_e32 v17, 16, v71
	v_add_f32_e32 v5, 1.0, v5
	v_rcp_f32_e32 v20, v5
	v_add_f32_e32 v5, 1.0, v21
	v_rcp_f32_e32 v22, v5
	v_mul_f32_e32 v5, 0xbfb8aa3b, v17
	v_exp_f32_e32 v5, v5
	v_mov_b32_e32 v52, v30
	v_mov_b32_e32 v53, v28
	v_and_b32_e32 v19, 0xffff0000, v71
	v_pk_mul_f32 v[52:53], v[52:53], v[4:5] op_sel_hi:[1,0]
	v_add_f32_e32 v5, 1.0, v5
	v_rcp_f32_e32 v21, v5
	v_mul_f32_e32 v5, 0xbfb8aa3b, v19
	v_exp_f32_e32 v5, v5
	v_mov_b32_e32 v28, v31
	v_pk_mul_f32 v[52:53], v[56:57], v[52:53]
	v_pk_mul_f32 v[16:17], v[20:21], v[16:17]
	v_add_f32_e32 v5, 1.0, v5
	v_rcp_f32_e32 v23, v5
	v_pk_mul_f32 v[20:21], v[28:29], v[4:5] op_sel_hi:[1,0]
	v_pk_mul_f32 v[16:17], v[52:53], v[16:17]
	v_pk_mul_f32 v[20:21], v[50:51], v[20:21]
	v_pk_mul_f32 v[18:19], v[22:23], v[18:19]
	v_and_b32_sdwa v5, v17, v204 dst_sel:DWORD dst_unused:UNUSED_PAD src0_sel:WORD_1 src1_sel:DWORD
	v_pk_mul_f32 v[18:19], v[20:21], v[18:19]
	v_and_b32_sdwa v20, v16, v204 dst_sel:DWORD dst_unused:UNUSED_PAD src0_sel:WORD_1 src1_sel:DWORD
	v_add3_u32 v16, v16, v20, s29
	v_add3_u32 v5, v17, v5, s29
	v_and_b32_sdwa v17, v19, v204 dst_sel:DWORD dst_unused:UNUSED_PAD src0_sel:WORD_1 src1_sel:DWORD
	v_and_b32_sdwa v20, v18, v204 dst_sel:DWORD dst_unused:UNUSED_PAD src0_sel:WORD_1 src1_sel:DWORD
	v_add3_u32 v17, v19, v17, s29
	v_add3_u32 v18, v18, v20, s29
	v_and_b32_e32 v17, 0xffff0000, v17
	v_and_b32_e32 v18, 0xffff0000, v18
	v_or_b32_sdwa v17, v17, v5 dst_sel:DWORD dst_unused:UNUSED_PAD src0_sel:DWORD src1_sel:WORD_1
	v_or_b32_sdwa v16, v18, v16 dst_sel:DWORD dst_unused:UNUSED_PAD src0_sel:DWORD src1_sel:WORD_1
	global_store_dwordx2 v[10:11], v[16:17], off offset:1120
	v_lshlrev_b32_e32 v16, 16, v68
	v_mul_f32_e32 v5, 0xbfb8aa3b, v16
	v_and_b32_e32 v18, 0xffff0000, v68
	v_exp_f32_e32 v5, v5
	v_mul_f32_e32 v19, 0xbfb8aa3b, v18
	v_exp_f32_e32 v21, v19
	v_lshlrev_b32_e32 v17, 16, v69
	v_add_f32_e32 v5, 1.0, v5
	v_rcp_f32_e32 v20, v5
	v_add_f32_e32 v5, 1.0, v21
	v_rcp_f32_e32 v22, v5
	v_mul_f32_e32 v5, 0xbfb8aa3b, v17
	v_exp_f32_e32 v5, v5
	v_mov_b32_e32 v28, v26
	v_mov_b32_e32 v29, v24
	v_and_b32_e32 v19, 0xffff0000, v69
	v_pk_mul_f32 v[28:29], v[28:29], v[4:5] op_sel_hi:[1,0]
	v_add_f32_e32 v5, 1.0, v5
	v_rcp_f32_e32 v21, v5
	v_mul_f32_e32 v5, 0xbfb8aa3b, v19
	v_exp_f32_e32 v5, v5
	v_mov_b32_e32 v24, v27
	v_pk_mul_f32 v[28:29], v[48:49], v[28:29]
	v_pk_mul_f32 v[16:17], v[20:21], v[16:17]
	v_add_f32_e32 v5, 1.0, v5
	v_rcp_f32_e32 v23, v5
	v_pk_mul_f32 v[20:21], v[24:25], v[4:5] op_sel_hi:[1,0]
	v_pk_mul_f32 v[16:17], v[28:29], v[16:17]
	v_pk_mul_f32 v[20:21], v[46:47], v[20:21]
	v_pk_mul_f32 v[18:19], v[22:23], v[18:19]
	v_and_b32_sdwa v5, v17, v204 dst_sel:DWORD dst_unused:UNUSED_PAD src0_sel:WORD_1 src1_sel:DWORD
	v_pk_mul_f32 v[18:19], v[20:21], v[18:19]
	v_and_b32_sdwa v20, v16, v204 dst_sel:DWORD dst_unused:UNUSED_PAD src0_sel:WORD_1 src1_sel:DWORD
	v_add3_u32 v16, v16, v20, s29
	v_add3_u32 v5, v17, v5, s29
	v_and_b32_sdwa v17, v19, v204 dst_sel:DWORD dst_unused:UNUSED_PAD src0_sel:WORD_1 src1_sel:DWORD
	v_and_b32_sdwa v20, v18, v204 dst_sel:DWORD dst_unused:UNUSED_PAD src0_sel:WORD_1 src1_sel:DWORD
	v_add3_u32 v17, v19, v17, s29
	v_add3_u32 v18, v18, v20, s29
	v_and_b32_e32 v17, 0xffff0000, v17
	v_and_b32_e32 v18, 0xffff0000, v18
	v_or_b32_sdwa v17, v17, v5 dst_sel:DWORD dst_unused:UNUSED_PAD src0_sel:DWORD src1_sel:WORD_1
	v_or_b32_sdwa v16, v18, v16 dst_sel:DWORD dst_unused:UNUSED_PAD src0_sel:DWORD src1_sel:WORD_1
	global_store_dwordx2 v[10:11], v[16:17], off offset:1152
	v_lshlrev_b32_e32 v16, 16, v62
	v_mul_f32_e32 v5, 0xbfb8aa3b, v16
	v_and_b32_e32 v18, 0xffff0000, v62
	v_exp_f32_e32 v5, v5
	v_mul_f32_e32 v19, 0xbfb8aa3b, v18
	v_exp_f32_e32 v21, v19
	v_lshlrev_b32_e32 v17, 16, v63
	v_add_f32_e32 v5, 1.0, v5
	v_rcp_f32_e32 v20, v5
	v_add_f32_e32 v5, 1.0, v21
	v_rcp_f32_e32 v22, v5
	v_mul_f32_e32 v5, 0xbfb8aa3b, v17
	v_exp_f32_e32 v5, v5
	v_mov_b32_e32 v24, v14
	v_mov_b32_e32 v25, v12
	v_and_b32_e32 v19, 0xffff0000, v63
	v_pk_mul_f32 v[24:25], v[24:25], v[4:5] op_sel_hi:[1,0]
	v_add_f32_e32 v5, 1.0, v5
	v_rcp_f32_e32 v21, v5
	v_mul_f32_e32 v5, 0xbfb8aa3b, v19
	v_exp_f32_e32 v5, v5
	v_mov_b32_e32 v12, v15
	v_pk_mul_f32 v[24:25], v[44:45], v[24:25]
	v_pk_mul_f32 v[16:17], v[20:21], v[16:17]
; __device__ __forceinline__ unsigned pk2(float lo, float hi) { return f2bf(lo) | (f2bf(hi) << 16); }
; __device__ __forceinline__ float silu_f(float g) { return g * __builtin_amdgcn_rcpf(1.0f + __expf(-g)); }
; __device__ __forceinline__ void gla_out_unit(const bf16* PROJ, const bf16* ST, const float* norm_o, bf16* Y, int unit, int lane) {
;     ...
;         for (int mi = 0; mi < 8; ++mi) {
;             const int v = h * 128 + 16 * mi + 4 * fq;
;             const f32x4 no = nov[mi]; const u32x2 g2 = gg1[mi];
;             const f32x4 o = acc[mi][ni];
;             const float y0 = o[0] * rs * no[0] * silu_f(bf_lo(g2.x)), y1 = o[1] * rs * no[1] * silu_f(bf_hi(g2.x));
;             const float y2 = o[2] * rs * no[2] * silu_f(bf_lo(g2.y)), y3 = o[3] * rs * no[3] * silu_f(bf_hi(g2.y));
;             u32x2 w; w.x = pk2(y0, y1); w.y = pk2(y2, y3);
;             *(u32x2*)(Y + tok * D + 512 + v) = w;
;         }
	v_add_f32_e32 v5, 1.0, v5
	v_rcp_f32_e32 v23, v5
	v_pk_mul_f32 v[12:13], v[12:13], v[4:5] op_sel_hi:[1,0]
	v_pk_mul_f32 v[16:17], v[24:25], v[16:17]
	v_pk_mul_f32 v[12:13], v[42:43], v[12:13]
	v_pk_mul_f32 v[14:15], v[22:23], v[18:19]
	v_and_b32_sdwa v5, v17, v204 dst_sel:DWORD dst_unused:UNUSED_PAD src0_sel:WORD_1 src1_sel:DWORD
	v_pk_mul_f32 v[12:13], v[12:13], v[14:15]
	v_and_b32_sdwa v14, v16, v204 dst_sel:DWORD dst_unused:UNUSED_PAD src0_sel:WORD_1 src1_sel:DWORD
	v_add3_u32 v14, v16, v14, s29
	v_and_b32_sdwa v15, v13, v204 dst_sel:DWORD dst_unused:UNUSED_PAD src0_sel:WORD_1 src1_sel:DWORD
	v_and_b32_sdwa v16, v12, v204 dst_sel:DWORD dst_unused:UNUSED_PAD src0_sel:WORD_1 src1_sel:DWORD
	v_add3_u32 v13, v13, v15, s29
	v_add3_u32 v12, v12, v16, s29
	v_add3_u32 v5, v17, v5, s29
	v_and_b32_e32 v13, 0xffff0000, v13
	v_and_b32_e32 v12, 0xffff0000, v12
	v_or_b32_sdwa v13, v13, v5 dst_sel:DWORD dst_unused:UNUSED_PAD src0_sel:DWORD src1_sel:WORD_1
	v_or_b32_sdwa v12, v12, v14 dst_sel:DWORD dst_unused:UNUSED_PAD src0_sel:DWORD src1_sel:WORD_1
	global_store_dwordx2 v[10:11], v[12:13], off offset:1184
	v_lshlrev_b32_e32 v12, 16, v60
	v_mul_f32_e32 v5, 0xbfb8aa3b, v12
	v_and_b32_e32 v14, 0xffff0000, v60
	v_exp_f32_e32 v5, v5
	v_mul_f32_e32 v15, 0xbfb8aa3b, v14
	v_exp_f32_e32 v17, v15
	v_lshlrev_b32_e32 v13, 16, v61
	v_add_f32_e32 v5, 1.0, v5
	v_rcp_f32_e32 v16, v5
	v_add_f32_e32 v5, 1.0, v17
	v_rcp_f32_e32 v18, v5
	v_mul_f32_e32 v5, 0xbfb8aa3b, v13
	v_exp_f32_e32 v5, v5
	v_mov_b32_e32 v20, v8
	v_mov_b32_e32 v21, v6
	v_and_b32_e32 v15, 0xffff0000, v61
	v_pk_mul_f32 v[20:21], v[20:21], v[4:5] op_sel_hi:[1,0]
	v_add_f32_e32 v5, 1.0, v5
	v_rcp_f32_e32 v17, v5
	v_mul_f32_e32 v5, 0xbfb8aa3b, v15
	v_exp_f32_e32 v5, v5
	v_mov_b32_e32 v6, v9
	v_pk_mul_f32 v[20:21], v[40:41], v[20:21]
	v_pk_mul_f32 v[12:13], v[16:17], v[12:13]
	v_add_f32_e32 v5, 1.0, v5
	v_rcp_f32_e32 v19, v5
	v_pk_mul_f32 v[6:7], v[6:7], v[4:5] op_sel_hi:[1,0]
	v_pk_mul_f32 v[12:13], v[20:21], v[12:13]
	v_pk_mul_f32 v[6:7], v[38:39], v[6:7]
	v_pk_mul_f32 v[8:9], v[18:19], v[14:15]
	v_and_b32_sdwa v5, v13, v204 dst_sel:DWORD dst_unused:UNUSED_PAD src0_sel:WORD_1 src1_sel:DWORD
	v_pk_mul_f32 v[6:7], v[6:7], v[8:9]
	v_and_b32_sdwa v8, v12, v204 dst_sel:DWORD dst_unused:UNUSED_PAD src0_sel:WORD_1 src1_sel:DWORD
	v_add3_u32 v8, v12, v8, s29
	v_and_b32_sdwa v9, v7, v204 dst_sel:DWORD dst_unused:UNUSED_PAD src0_sel:WORD_1 src1_sel:DWORD
	v_and_b32_sdwa v12, v6, v204 dst_sel:DWORD dst_unused:UNUSED_PAD src0_sel:WORD_1 src1_sel:DWORD
	v_add3_u32 v7, v7, v9, s29
	v_add3_u32 v6, v6, v12, s29
	v_add3_u32 v5, v13, v5, s29
	v_and_b32_e32 v7, 0xffff0000, v7
	v_and_b32_e32 v6, 0xffff0000, v6
	v_or_b32_sdwa v7, v7, v5 dst_sel:DWORD dst_unused:UNUSED_PAD src0_sel:DWORD src1_sel:WORD_1
	v_or_b32_sdwa v6, v6, v8 dst_sel:DWORD dst_unused:UNUSED_PAD src0_sel:DWORD src1_sel:WORD_1
	global_store_dwordx2 v[10:11], v[6:7], off offset:1216
	v_lshlrev_b32_e32 v6, 16, v32
	v_mul_f32_e32 v5, 0xbfb8aa3b, v6
	v_and_b32_e32 v8, 0xffff0000, v32
	v_exp_f32_e32 v5, v5
	v_mul_f32_e32 v9, 0xbfb8aa3b, v8
	v_exp_f32_e32 v13, v9
	v_lshlrev_b32_e32 v7, 16, v33
	v_add_f32_e32 v5, 1.0, v5
	v_rcp_f32_e32 v12, v5
	v_add_f32_e32 v5, 1.0, v13
	v_rcp_f32_e32 v14, v5
	v_mul_f32_e32 v5, 0xbfb8aa3b, v7
	v_exp_f32_e32 v5, v5
	v_and_b32_e32 v9, 0xffff0000, v33
	v_mov_b32_e32 v17, v0
	v_mov_b32_e32 v16, v2
	v_add_f32_e32 v0, 1.0, v5
	v_rcp_f32_e32 v13, v0
	v_mul_f32_e32 v0, 0xbfb8aa3b, v9
	v_exp_f32_e32 v0, v0
	v_pk_mul_f32 v[16:17], v[16:17], v[4:5] op_sel_hi:[1,0]
	v_pk_mul_f32 v[6:7], v[12:13], v[6:7]
	v_pk_mul_f32 v[16:17], v[36:37], v[16:17]
	v_add_f32_e32 v0, 1.0, v0
	v_rcp_f32_e32 v15, v0
	v_mov_b32_e32 v0, v3
	v_pk_mul_f32 v[0:1], v[0:1], v[4:5] op_sel_hi:[1,0]
	v_pk_mul_f32 v[6:7], v[16:17], v[6:7]
	v_pk_mul_f32 v[0:1], v[34:35], v[0:1]
	v_pk_mul_f32 v[2:3], v[14:15], v[8:9]
	s_nop 0
	v_pk_mul_f32 v[0:1], v[0:1], v[2:3]
	v_and_b32_sdwa v2, v7, v204 dst_sel:DWORD dst_unused:UNUSED_PAD src0_sel:WORD_1 src1_sel:DWORD
	v_and_b32_sdwa v4, v1, v204 dst_sel:DWORD dst_unused:UNUSED_PAD src0_sel:WORD_1 src1_sel:DWORD
	v_and_b32_sdwa v5, v0, v204 dst_sel:DWORD dst_unused:UNUSED_PAD src0_sel:WORD_1 src1_sel:DWORD
	v_and_b32_sdwa v3, v6, v204 dst_sel:DWORD dst_unused:UNUSED_PAD src0_sel:WORD_1 src1_sel:DWORD
	v_add3_u32 v1, v1, v4, s29
	v_add3_u32 v0, v0, v5, s29
	v_add3_u32 v3, v6, v3, s29
	v_add3_u32 v2, v7, v2, s29
	v_and_b32_e32 v1, 0xffff0000, v1
	v_and_b32_e32 v0, 0xffff0000, v0
	v_or_b32_sdwa v1, v1, v2 dst_sel:DWORD dst_unused:UNUSED_PAD src0_sel:DWORD src1_sel:WORD_1
	v_or_b32_sdwa v0, v0, v3 dst_sel:DWORD dst_unused:UNUSED_PAD src0_sel:DWORD src1_sel:WORD_1
	global_store_dwordx2 v[10:11], v[0:1], off offset:1248
	s_cbranch_scc1 .LBB0_1155
